# merged 32-MFMA blocks with accumulator pairs in original k order (bit-identical accumulation) + static s_setprio 1 for waves 0-3
# speedup vs baseline: 1.0075x; 1.0075x over previous
.LBB0_142:
	ds_read_b128 v[168:171], v165
	ds_read_b128 v[172:175], v165 offset:1024
	ds_read_b128 v[176:179], v165 offset:2048
	ds_read_b128 v[180:183], v165 offset:3072
	ds_read_b128 v[184:187], v166
	ds_read_b128 v[188:191], v166 offset:1024
	ds_read_b128 v[192:195], v166 offset:2048
	ds_read_b128 v[196:199], v166 offset:3072
	s_add_i32 s54, s22, 2
	s_add_u32 s55, s20, 0x80
	s_addc_u32 s23, s21, 0
	s_cmp_eq_u32 s42, s22
	s_cselect_b32 s22, s4, s55
	s_cselect_b32 s23, s5, s23
	s_cselect_b32 s61, s19, s53
	s_cselect_b32 s60, s18, s52
	v_lshl_add_u64 v[234:235], s[20:21], 0, v[154:155]
	s_add_i32 m0, s31, 0xc000
	ds_read_b128 v[200:203], v167
	ds_read_b128 v[204:207], v167 offset:1024
	ds_read_b128 v[208:211], v167 offset:2048
	ds_read_b128 v[212:215], v167 offset:3072
	ds_read_b128 v[216:219], v167 offset:4096
	ds_read_b128 v[222:225], v167 offset:5120
	ds_read_b128 v[226:229], v167 offset:6144
	ds_read_b128 v[230:233], v167 offset:7168
	global_load_lds_dwordx4 v[234:235], off
	v_lshl_add_u64 v[234:235], s[20:21], 0, v[156:157]
	s_add_i32 m0, s31, 0xe000
	s_nop 0
	global_load_lds_dwordx4 v[234:235], off
	s_waitcnt vmcnt(8)
	s_waitcnt lgkmcnt(0)
	s_barrier
	s_waitcnt lgkmcnt(0)
	v_mfma_f32_16x16x32_bf16 v[120:123], v[168:171], v[200:203], v[120:123]
	v_mfma_f32_16x16x32_bf16 v[120:123], v[172:175], v[204:207], v[120:123]
	v_mfma_f32_16x16x32_bf16 v[116:119], v[176:179], v[200:203], v[116:119]
	v_mfma_f32_16x16x32_bf16 v[116:119], v[180:183], v[204:207], v[116:119]
	v_mfma_f32_16x16x32_bf16 v[124:127], v[184:187], v[200:203], v[124:127]
	v_mfma_f32_16x16x32_bf16 v[124:127], v[188:191], v[204:207], v[124:127]
	v_mfma_f32_16x16x32_bf16 v[112:115], v[192:195], v[200:203], v[112:115]
	v_mfma_f32_16x16x32_bf16 v[112:115], v[196:199], v[204:207], v[112:115]
	v_mfma_f32_16x16x32_bf16 v[96:99], v[192:195], v[208:211], v[96:99]
	v_mfma_f32_16x16x32_bf16 v[96:99], v[196:199], v[212:215], v[96:99]
	v_mfma_f32_16x16x32_bf16 v[104:107], v[184:187], v[208:211], v[104:107]
	v_mfma_f32_16x16x32_bf16 v[104:107], v[188:191], v[212:215], v[104:107]
	v_mfma_f32_16x16x32_bf16 v[100:103], v[176:179], v[208:211], v[100:103]
	v_mfma_f32_16x16x32_bf16 v[100:103], v[180:183], v[212:215], v[100:103]
	v_mfma_f32_16x16x32_bf16 v[108:111], v[168:171], v[208:211], v[108:111]
	v_mfma_f32_16x16x32_bf16 v[108:111], v[172:175], v[212:215], v[108:111]
	v_mfma_f32_16x16x32_bf16 v[92:95], v[168:171], v[216:219], v[92:95]
	v_mfma_f32_16x16x32_bf16 v[92:95], v[172:175], v[222:225], v[92:95]
	v_mfma_f32_16x16x32_bf16 v[84:87], v[176:179], v[216:219], v[84:87]
	v_mfma_f32_16x16x32_bf16 v[84:87], v[180:183], v[222:225], v[84:87]
	v_mfma_f32_16x16x32_bf16 v[88:91], v[184:187], v[216:219], v[88:91]
	v_mfma_f32_16x16x32_bf16 v[88:91], v[188:191], v[222:225], v[88:91]
	v_mfma_f32_16x16x32_bf16 v[80:83], v[192:195], v[216:219], v[80:83]
	v_mfma_f32_16x16x32_bf16 v[80:83], v[196:199], v[222:225], v[80:83]
	v_mfma_f32_16x16x32_bf16 v[64:67], v[192:195], v[226:229], v[64:67]
	v_mfma_f32_16x16x32_bf16 v[64:67], v[196:199], v[230:233], v[64:67]
	v_mfma_f32_16x16x32_bf16 v[72:75], v[184:187], v[226:229], v[72:75]
	v_mfma_f32_16x16x32_bf16 v[72:75], v[188:191], v[230:233], v[72:75]
	v_mfma_f32_16x16x32_bf16 v[68:71], v[176:179], v[226:229], v[68:71]
	v_mfma_f32_16x16x32_bf16 v[68:71], v[180:183], v[230:233], v[68:71]
	v_mfma_f32_16x16x32_bf16 v[76:79], v[168:171], v[226:229], v[76:79]
	v_mfma_f32_16x16x32_bf16 v[76:79], v[172:175], v[230:233], v[76:79]
	s_barrier
	s_add_i32 s55, s46, s28
	v_lshl_add_u64 v[234:235], s[60:61], 0, v[132:133]
	s_mov_b32 m0, s55
	ds_read_b128 v[200:203], v167 offset:16384
	ds_read_b128 v[204:207], v167 offset:17408
	ds_read_b128 v[208:211], v167 offset:18432
	ds_read_b128 v[212:215], v167 offset:19456
	ds_read_b128 v[216:219], v167 offset:20480
	ds_read_b128 v[222:225], v167 offset:21504
	ds_read_b128 v[226:229], v167 offset:22528
	ds_read_b128 v[230:233], v167 offset:23552
	global_load_lds_dwordx4 v[234:235], off
	s_add_i32 m0, s55, 0x2000
	v_lshl_add_u64 v[236:237], s[60:61], 0, v[128:129]
	s_add_u32 s60, s60, s10
	s_addc_u32 s61, s61, s11
	s_add_i32 s55, s47, s28
	global_load_lds_dwordx4 v[236:237], off
	v_lshl_add_u64 v[238:239], s[60:61], 0, v[132:133]
	s_mov_b32 m0, s55
	v_lshl_add_u64 v[240:241], s[60:61], 0, v[128:129]
	global_load_lds_dwordx4 v[238:239], off
	s_add_i32 m0, s55, 0x2000
	v_lshl_add_u64 v[242:243], s[22:23], 0, v[134:135]
	global_load_lds_dwordx4 v[240:241], off
	s_mov_b32 m0, s31
	v_lshl_add_u64 v[244:245], s[22:23], 0, v[130:131]
	global_load_lds_dwordx4 v[242:243], off
	s_mov_b32 m0, s33
	s_nop 0
	global_load_lds_dwordx4 v[244:245], off
	s_waitcnt vmcnt(8)
	s_waitcnt lgkmcnt(0)
	s_barrier
	s_waitcnt lgkmcnt(0)
	v_mfma_f32_16x16x32_bf16 v[60:63], v[168:171], v[200:203], v[60:63]
	v_mfma_f32_16x16x32_bf16 v[60:63], v[172:175], v[204:207], v[60:63]
	v_mfma_f32_16x16x32_bf16 v[52:55], v[176:179], v[200:203], v[52:55]
	v_mfma_f32_16x16x32_bf16 v[52:55], v[180:183], v[204:207], v[52:55]
	v_mfma_f32_16x16x32_bf16 v[56:59], v[184:187], v[200:203], v[56:59]
	v_mfma_f32_16x16x32_bf16 v[56:59], v[188:191], v[204:207], v[56:59]
	v_mfma_f32_16x16x32_bf16 v[48:51], v[192:195], v[200:203], v[48:51]
	v_mfma_f32_16x16x32_bf16 v[48:51], v[196:199], v[204:207], v[48:51]
	v_mfma_f32_16x16x32_bf16 v[32:35], v[192:195], v[208:211], v[32:35]
	v_mfma_f32_16x16x32_bf16 v[32:35], v[196:199], v[212:215], v[32:35]
	v_mfma_f32_16x16x32_bf16 v[40:43], v[184:187], v[208:211], v[40:43]
	v_mfma_f32_16x16x32_bf16 v[40:43], v[188:191], v[212:215], v[40:43]
	v_mfma_f32_16x16x32_bf16 v[36:39], v[176:179], v[208:211], v[36:39]
	v_mfma_f32_16x16x32_bf16 v[36:39], v[180:183], v[212:215], v[36:39]
	v_mfma_f32_16x16x32_bf16 v[44:47], v[168:171], v[208:211], v[44:47]
	v_mfma_f32_16x16x32_bf16 v[44:47], v[172:175], v[212:215], v[44:47]
	v_mfma_f32_16x16x32_bf16 v[28:31], v[168:171], v[216:219], v[28:31]
	v_mfma_f32_16x16x32_bf16 v[28:31], v[172:175], v[222:225], v[28:31]
	v_mfma_f32_16x16x32_bf16 v[20:23], v[176:179], v[216:219], v[20:23]
	v_mfma_f32_16x16x32_bf16 v[20:23], v[180:183], v[222:225], v[20:23]
	v_mfma_f32_16x16x32_bf16 v[24:27], v[184:187], v[216:219], v[24:27]
	v_mfma_f32_16x16x32_bf16 v[24:27], v[188:191], v[222:225], v[24:27]
	v_mfma_f32_16x16x32_bf16 v[16:19], v[192:195], v[216:219], v[16:19]
	v_mfma_f32_16x16x32_bf16 v[16:19], v[196:199], v[222:225], v[16:19]
	v_mfma_f32_16x16x32_bf16 v[0:3], v[192:195], v[226:229], v[0:3]
	v_mfma_f32_16x16x32_bf16 v[0:3], v[196:199], v[230:233], v[0:3]
	v_mfma_f32_16x16x32_bf16 v[8:11], v[184:187], v[226:229], v[8:11]
	v_mfma_f32_16x16x32_bf16 v[8:11], v[188:191], v[230:233], v[8:11]
	v_mfma_f32_16x16x32_bf16 v[4:7], v[176:179], v[226:229], v[4:7]
	v_mfma_f32_16x16x32_bf16 v[4:7], v[180:183], v[230:233], v[4:7]
	v_mfma_f32_16x16x32_bf16 v[12:15], v[168:171], v[226:229], v[12:15]
	v_mfma_f32_16x16x32_bf16 v[12:15], v[172:175], v[230:233], v[12:15]
	s_barrier
	s_add_i32 s55, 0, 0x18000
	s_add_i32 s60, 0, 0x1c000
	v_add_u32_e32 v180, s55, v164
	v_add_u32_e32 v196, s60, v164
	ds_read_b128 v[168:171], v180
	ds_read_b128 v[172:175], v180 offset:1024
	ds_read_b128 v[176:179], v180 offset:2048
	ds_read_b128 v[180:183], v180 offset:3072
	ds_read_b128 v[184:187], v196
	ds_read_b128 v[188:191], v196 offset:1024
	ds_read_b128 v[192:195], v196 offset:2048
	ds_read_b128 v[196:199], v196 offset:3072
	s_add_u32 s22, s22, s10
	s_addc_u32 s23, s23, s11
	s_mov_b32 m0, s34
	v_lshl_add_u64 v[246:247], s[22:23], 0, v[134:135]
	ds_read_b128 v[200:203], v167 offset:32768
	ds_read_b128 v[204:207], v167 offset:33792
	ds_read_b128 v[208:211], v167 offset:34816
	ds_read_b128 v[212:215], v167 offset:35840
	ds_read_b128 v[216:219], v167 offset:36864
	ds_read_b128 v[222:225], v167 offset:37888
	ds_read_b128 v[226:229], v167 offset:38912
	ds_read_b128 v[230:233], v167 offset:39936
	global_load_lds_dwordx4 v[246:247], off
	v_lshl_add_u64 v[246:247], s[22:23], 0, v[130:131]
	s_mov_b32 m0, s35
	s_nop 0
	global_load_lds_dwordx4 v[246:247], off
	s_waitcnt vmcnt(8)
	s_waitcnt lgkmcnt(0)
	s_barrier
	s_waitcnt lgkmcnt(0)
	v_mfma_f32_16x16x32_bf16 v[120:123], v[168:171], v[200:203], v[120:123]
	v_mfma_f32_16x16x32_bf16 v[120:123], v[172:175], v[204:207], v[120:123]
	v_mfma_f32_16x16x32_bf16 v[116:119], v[176:179], v[200:203], v[116:119]
	v_mfma_f32_16x16x32_bf16 v[116:119], v[180:183], v[204:207], v[116:119]
	v_mfma_f32_16x16x32_bf16 v[124:127], v[184:187], v[200:203], v[124:127]
	v_mfma_f32_16x16x32_bf16 v[124:127], v[188:191], v[204:207], v[124:127]
	v_mfma_f32_16x16x32_bf16 v[112:115], v[192:195], v[200:203], v[112:115]
	v_mfma_f32_16x16x32_bf16 v[112:115], v[196:199], v[204:207], v[112:115]
	v_mfma_f32_16x16x32_bf16 v[96:99], v[192:195], v[208:211], v[96:99]
	v_mfma_f32_16x16x32_bf16 v[96:99], v[196:199], v[212:215], v[96:99]
	v_mfma_f32_16x16x32_bf16 v[104:107], v[184:187], v[208:211], v[104:107]
	v_mfma_f32_16x16x32_bf16 v[104:107], v[188:191], v[212:215], v[104:107]
	v_mfma_f32_16x16x32_bf16 v[100:103], v[176:179], v[208:211], v[100:103]
	v_mfma_f32_16x16x32_bf16 v[100:103], v[180:183], v[212:215], v[100:103]
	v_mfma_f32_16x16x32_bf16 v[108:111], v[168:171], v[208:211], v[108:111]
	v_mfma_f32_16x16x32_bf16 v[108:111], v[172:175], v[212:215], v[108:111]
	v_mfma_f32_16x16x32_bf16 v[92:95], v[168:171], v[216:219], v[92:95]
	v_mfma_f32_16x16x32_bf16 v[92:95], v[172:175], v[222:225], v[92:95]
	v_mfma_f32_16x16x32_bf16 v[84:87], v[176:179], v[216:219], v[84:87]
	v_mfma_f32_16x16x32_bf16 v[84:87], v[180:183], v[222:225], v[84:87]
	v_mfma_f32_16x16x32_bf16 v[88:91], v[184:187], v[216:219], v[88:91]
	v_mfma_f32_16x16x32_bf16 v[88:91], v[188:191], v[222:225], v[88:91]
	v_mfma_f32_16x16x32_bf16 v[80:83], v[192:195], v[216:219], v[80:83]
	v_mfma_f32_16x16x32_bf16 v[80:83], v[196:199], v[222:225], v[80:83]
	v_mfma_f32_16x16x32_bf16 v[64:67], v[192:195], v[226:229], v[64:67]
	v_mfma_f32_16x16x32_bf16 v[64:67], v[196:199], v[230:233], v[64:67]
	v_mfma_f32_16x16x32_bf16 v[72:75], v[184:187], v[226:229], v[72:75]
	v_mfma_f32_16x16x32_bf16 v[72:75], v[188:191], v[230:233], v[72:75]
	v_mfma_f32_16x16x32_bf16 v[68:71], v[176:179], v[226:229], v[68:71]
	v_mfma_f32_16x16x32_bf16 v[68:71], v[180:183], v[230:233], v[68:71]
	v_mfma_f32_16x16x32_bf16 v[76:79], v[168:171], v[226:229], v[76:79]
	v_mfma_f32_16x16x32_bf16 v[76:79], v[172:175], v[230:233], v[76:79]
	s_barrier
	s_add_i32 s22, s55, s28
	v_lshl_add_u64 v[234:235], v[234:235], 0, s[14:15]
	s_mov_b32 m0, s22
	ds_read_b128 v[200:203], v167 offset:49152
	ds_read_b128 v[204:207], v167 offset:50176
	ds_read_b128 v[208:211], v167 offset:51200
	ds_read_b128 v[212:215], v167 offset:52224
	ds_read_b128 v[216:219], v167 offset:53248
	ds_read_b128 v[222:225], v167 offset:54272
	ds_read_b128 v[226:229], v167 offset:55296
	ds_read_b128 v[230:233], v167 offset:56320
	global_load_lds_dwordx4 v[234:235], off
	v_lshl_add_u64 v[234:235], v[236:237], 0, s[14:15]
	s_add_i32 m0, s22, 0x2000
	s_add_i32 s22, s60, s28
	global_load_lds_dwordx4 v[234:235], off
	v_lshl_add_u64 v[234:235], v[238:239], 0, s[14:15]
	s_mov_b32 m0, s22
	s_nop 0
	global_load_lds_dwordx4 v[234:235], off
	v_lshl_add_u64 v[234:235], v[240:241], 0, s[14:15]
	s_add_i32 m0, s22, 0x2000
	s_nop 0
	global_load_lds_dwordx4 v[234:235], off
	v_lshl_add_u64 v[234:235], v[242:243], 0, s[14:15]
	s_mov_b32 m0, s39
	s_nop 0
	global_load_lds_dwordx4 v[234:235], off
	v_lshl_add_u64 v[234:235], v[244:245], 0, s[14:15]
	s_mov_b32 m0, s40
	s_nop 0
	global_load_lds_dwordx4 v[234:235], off
	s_waitcnt vmcnt(8)
	s_waitcnt lgkmcnt(0)
	s_barrier
	s_waitcnt lgkmcnt(0)
	v_mfma_f32_16x16x32_bf16 v[60:63], v[168:171], v[200:203], v[60:63]
	v_mfma_f32_16x16x32_bf16 v[60:63], v[172:175], v[204:207], v[60:63]
	v_mfma_f32_16x16x32_bf16 v[52:55], v[176:179], v[200:203], v[52:55]
	v_mfma_f32_16x16x32_bf16 v[52:55], v[180:183], v[204:207], v[52:55]
	v_mfma_f32_16x16x32_bf16 v[56:59], v[184:187], v[200:203], v[56:59]
	v_mfma_f32_16x16x32_bf16 v[56:59], v[188:191], v[204:207], v[56:59]
	v_mfma_f32_16x16x32_bf16 v[48:51], v[192:195], v[200:203], v[48:51]
	v_mfma_f32_16x16x32_bf16 v[48:51], v[196:199], v[204:207], v[48:51]
	v_mfma_f32_16x16x32_bf16 v[32:35], v[192:195], v[208:211], v[32:35]
	v_mfma_f32_16x16x32_bf16 v[32:35], v[196:199], v[212:215], v[32:35]
	v_mfma_f32_16x16x32_bf16 v[40:43], v[184:187], v[208:211], v[40:43]
	v_mfma_f32_16x16x32_bf16 v[40:43], v[188:191], v[212:215], v[40:43]
	v_mfma_f32_16x16x32_bf16 v[36:39], v[176:179], v[208:211], v[36:39]
	v_mfma_f32_16x16x32_bf16 v[36:39], v[180:183], v[212:215], v[36:39]
	v_mfma_f32_16x16x32_bf16 v[44:47], v[168:171], v[208:211], v[44:47]
	v_mfma_f32_16x16x32_bf16 v[44:47], v[172:175], v[212:215], v[44:47]
	v_mfma_f32_16x16x32_bf16 v[28:31], v[168:171], v[216:219], v[28:31]
	v_mfma_f32_16x16x32_bf16 v[28:31], v[172:175], v[222:225], v[28:31]
	v_mfma_f32_16x16x32_bf16 v[20:23], v[176:179], v[216:219], v[20:23]
	v_mfma_f32_16x16x32_bf16 v[20:23], v[180:183], v[222:225], v[20:23]
	v_mfma_f32_16x16x32_bf16 v[24:27], v[184:187], v[216:219], v[24:27]
	v_mfma_f32_16x16x32_bf16 v[24:27], v[188:191], v[222:225], v[24:27]
	v_mfma_f32_16x16x32_bf16 v[16:19], v[192:195], v[216:219], v[16:19]
	v_mfma_f32_16x16x32_bf16 v[16:19], v[196:199], v[222:225], v[16:19]
	v_mfma_f32_16x16x32_bf16 v[0:3], v[192:195], v[226:229], v[0:3]
	v_mfma_f32_16x16x32_bf16 v[0:3], v[196:199], v[230:233], v[0:3]
	v_mfma_f32_16x16x32_bf16 v[8:11], v[184:187], v[226:229], v[8:11]
	v_mfma_f32_16x16x32_bf16 v[8:11], v[188:191], v[230:233], v[8:11]
	v_mfma_f32_16x16x32_bf16 v[4:7], v[176:179], v[226:229], v[4:7]
	v_mfma_f32_16x16x32_bf16 v[4:7], v[180:183], v[230:233], v[4:7]
	v_mfma_f32_16x16x32_bf16 v[12:15], v[168:171], v[226:229], v[12:15]
	v_mfma_f32_16x16x32_bf16 v[12:15], v[172:175], v[230:233], v[12:15]
	s_barrier
	s_add_u32 s20, s20, 0x100
	s_addc_u32 s21, s21, 0
	s_add_u32 s52, s52, 0x100
	s_addc_u32 s53, s53, 0
	s_cmp_ge_i32 s54, s41
	s_mov_b32 s22, s54
	s_cbranch_scc0 .LBB0_142

.LBB0_228:
	ds_read_b128 v[140:143], v219
	ds_read_b128 v[144:147], v219 offset:1024
	ds_read_b128 v[148:151], v219 offset:2048
	ds_read_b128 v[152:155], v219 offset:3072
	ds_read_b128 v[156:159], v221
	ds_read_b128 v[164:167], v221 offset:1024
	ds_read_b128 v[168:171], v221 offset:2048
	ds_read_b128 v[172:175], v221 offset:3072
	s_add_i32 s62, s26, 2
	s_add_u32 s27, s24, 0x4000
	s_addc_u32 s28, s25, 0
	s_cmp_eq_u32 s46, s26
	s_cselect_b32 s30, s0, s27
	s_cselect_b32 s31, s1, s28
	s_cselect_b32 s28, s22, s60
	s_cselect_b32 s29, s23, s61
	s_add_u32 s26, s30, 0x8000
	s_addc_u32 s27, s31, 0
	v_lshl_add_u64 v[160:161], s[24:25], 0, v[132:133]
	s_add_i32 m0, s38, 0xc000
	ds_read_b128 v[176:179], v222
	ds_read_b128 v[180:183], v222 offset:1024
	ds_read_b128 v[184:187], v222 offset:2048
	ds_read_b128 v[188:191], v222 offset:3072
	ds_read_b128 v[192:195], v222 offset:4096
	ds_read_b128 v[196:199], v222 offset:5120
	ds_read_b128 v[200:203], v222 offset:6144
	ds_read_b128 v[204:207], v222 offset:7168
	global_load_lds_dwordx4 v[160:161], off
	v_lshl_add_u64 v[160:161], s[24:25], 0, v[134:135]
	s_add_i32 m0, s38, 0xe000
	s_nop 0
	global_load_lds_dwordx4 v[160:161], off
	s_waitcnt vmcnt(8)
	s_waitcnt lgkmcnt(0)
	s_barrier
	s_waitcnt lgkmcnt(0)
	v_mfma_f32_16x16x32_bf16 v[124:127], v[140:143], v[176:179], v[124:127]
	v_mfma_f32_16x16x32_bf16 v[124:127], v[144:147], v[180:183], v[124:127]
	v_mfma_f32_16x16x32_bf16 v[120:123], v[148:151], v[176:179], v[120:123]
	v_mfma_f32_16x16x32_bf16 v[120:123], v[152:155], v[180:183], v[120:123]
	v_mfma_f32_16x16x32_bf16 v[108:111], v[156:159], v[176:179], v[108:111]
	v_mfma_f32_16x16x32_bf16 v[108:111], v[164:167], v[180:183], v[108:111]
	v_mfma_f32_16x16x32_bf16 v[100:103], v[168:171], v[176:179], v[100:103]
	v_mfma_f32_16x16x32_bf16 v[100:103], v[172:175], v[180:183], v[100:103]
	v_mfma_f32_16x16x32_bf16 v[84:87], v[168:171], v[184:187], v[84:87]
	v_mfma_f32_16x16x32_bf16 v[84:87], v[172:175], v[188:191], v[84:87]
	v_mfma_f32_16x16x32_bf16 v[92:95], v[156:159], v[184:187], v[92:95]
	v_mfma_f32_16x16x32_bf16 v[92:95], v[164:167], v[188:191], v[92:95]
	v_mfma_f32_16x16x32_bf16 v[112:115], v[148:151], v[184:187], v[112:115]
	v_mfma_f32_16x16x32_bf16 v[112:115], v[152:155], v[188:191], v[112:115]
	v_mfma_f32_16x16x32_bf16 v[116:119], v[140:143], v[184:187], v[116:119]
	v_mfma_f32_16x16x32_bf16 v[116:119], v[144:147], v[188:191], v[116:119]
	v_mfma_f32_16x16x32_bf16 v[104:107], v[140:143], v[192:195], v[104:107]
	v_mfma_f32_16x16x32_bf16 v[104:107], v[144:147], v[196:199], v[104:107]
	v_mfma_f32_16x16x32_bf16 v[96:99], v[148:151], v[192:195], v[96:99]
	v_mfma_f32_16x16x32_bf16 v[96:99], v[152:155], v[196:199], v[96:99]
	v_mfma_f32_16x16x32_bf16 v[76:79], v[156:159], v[192:195], v[76:79]
	v_mfma_f32_16x16x32_bf16 v[76:79], v[164:167], v[196:199], v[76:79]
	v_mfma_f32_16x16x32_bf16 v[72:75], v[168:171], v[192:195], v[72:75]
	v_mfma_f32_16x16x32_bf16 v[72:75], v[172:175], v[196:199], v[72:75]
	v_mfma_f32_16x16x32_bf16 v[64:67], v[168:171], v[200:203], v[64:67]
	v_mfma_f32_16x16x32_bf16 v[64:67], v[172:175], v[204:207], v[64:67]
	v_mfma_f32_16x16x32_bf16 v[68:71], v[156:159], v[200:203], v[68:71]
	v_mfma_f32_16x16x32_bf16 v[68:71], v[164:167], v[204:207], v[68:71]
	v_mfma_f32_16x16x32_bf16 v[80:83], v[148:151], v[200:203], v[80:83]
	v_mfma_f32_16x16x32_bf16 v[80:83], v[152:155], v[204:207], v[80:83]
	v_mfma_f32_16x16x32_bf16 v[88:91], v[140:143], v[200:203], v[88:91]
	v_mfma_f32_16x16x32_bf16 v[88:91], v[144:147], v[204:207], v[88:91]
	s_barrier
	s_add_i32 s63, s50, s37
	v_lshl_add_u64 v[160:161], s[28:29], 0, v[128:129]
	s_mov_b32 m0, s63
	ds_read_b128 v[176:179], v222 offset:16384
	ds_read_b128 v[180:183], v222 offset:17408
	ds_read_b128 v[184:187], v222 offset:18432
	ds_read_b128 v[188:191], v222 offset:19456
	ds_read_b128 v[192:195], v222 offset:20480
	ds_read_b128 v[196:199], v222 offset:21504
	ds_read_b128 v[200:203], v222 offset:22528
	ds_read_b128 v[204:207], v222 offset:23552
	global_load_lds_dwordx4 v[160:161], off
	s_add_i32 m0, s63, 0x2000
	s_add_u32 s64, s28, 0x4000
	v_lshl_add_u64 v[160:161], s[28:29], 0, v[130:131]
	s_addc_u32 s65, s29, 0
	s_add_i32 s63, s51, s37
	global_load_lds_dwordx4 v[160:161], off
	v_lshl_add_u64 v[160:161], s[64:65], 0, v[128:129]
	s_mov_b32 m0, s63
	s_nop 0
	global_load_lds_dwordx4 v[160:161], off
	v_lshl_add_u64 v[160:161], s[64:65], 0, v[130:131]
	s_add_i32 m0, s63, 0x2000
	s_nop 0
	global_load_lds_dwordx4 v[160:161], off
	v_lshl_add_u64 v[160:161], s[30:31], 0, v[128:129]
	s_mov_b32 m0, s38
	s_nop 0
	global_load_lds_dwordx4 v[160:161], off
	v_lshl_add_u64 v[160:161], s[30:31], 0, v[130:131]
	s_mov_b32 m0, s39
	s_nop 0
	global_load_lds_dwordx4 v[160:161], off
	s_waitcnt vmcnt(8)
	s_waitcnt lgkmcnt(0)
	s_barrier
	s_waitcnt lgkmcnt(0)
	v_mfma_f32_16x16x32_bf16 v[60:63], v[140:143], v[176:179], v[60:63]
	v_mfma_f32_16x16x32_bf16 v[60:63], v[144:147], v[180:183], v[60:63]
	v_mfma_f32_16x16x32_bf16 v[56:59], v[148:151], v[176:179], v[56:59]
	v_mfma_f32_16x16x32_bf16 v[56:59], v[152:155], v[180:183], v[56:59]
	v_mfma_f32_16x16x32_bf16 v[44:47], v[156:159], v[176:179], v[44:47]
	v_mfma_f32_16x16x32_bf16 v[44:47], v[164:167], v[180:183], v[44:47]
	v_mfma_f32_16x16x32_bf16 v[36:39], v[168:171], v[176:179], v[36:39]
	v_mfma_f32_16x16x32_bf16 v[36:39], v[172:175], v[180:183], v[36:39]
	v_mfma_f32_16x16x32_bf16 v[20:23], v[168:171], v[184:187], v[20:23]
	v_mfma_f32_16x16x32_bf16 v[20:23], v[172:175], v[188:191], v[20:23]
	v_mfma_f32_16x16x32_bf16 v[28:31], v[156:159], v[184:187], v[28:31]
	v_mfma_f32_16x16x32_bf16 v[28:31], v[164:167], v[188:191], v[28:31]
	v_mfma_f32_16x16x32_bf16 v[48:51], v[148:151], v[184:187], v[48:51]
	v_mfma_f32_16x16x32_bf16 v[48:51], v[152:155], v[188:191], v[48:51]
	v_mfma_f32_16x16x32_bf16 v[52:55], v[140:143], v[184:187], v[52:55]
	v_mfma_f32_16x16x32_bf16 v[52:55], v[144:147], v[188:191], v[52:55]
	v_mfma_f32_16x16x32_bf16 v[40:43], v[140:143], v[192:195], v[40:43]
	v_mfma_f32_16x16x32_bf16 v[40:43], v[144:147], v[196:199], v[40:43]
	v_mfma_f32_16x16x32_bf16 v[32:35], v[148:151], v[192:195], v[32:35]
	v_mfma_f32_16x16x32_bf16 v[32:35], v[152:155], v[196:199], v[32:35]
	v_mfma_f32_16x16x32_bf16 v[12:15], v[156:159], v[192:195], v[12:15]
	v_mfma_f32_16x16x32_bf16 v[12:15], v[164:167], v[196:199], v[12:15]
	v_mfma_f32_16x16x32_bf16 v[8:11], v[168:171], v[192:195], v[8:11]
	v_mfma_f32_16x16x32_bf16 v[8:11], v[172:175], v[196:199], v[8:11]
	v_mfma_f32_16x16x32_bf16 v[0:3], v[168:171], v[200:203], v[0:3]
	v_mfma_f32_16x16x32_bf16 v[0:3], v[172:175], v[204:207], v[0:3]
	v_mfma_f32_16x16x32_bf16 v[4:7], v[156:159], v[200:203], v[4:7]
	v_mfma_f32_16x16x32_bf16 v[4:7], v[164:167], v[204:207], v[4:7]
	v_mfma_f32_16x16x32_bf16 v[16:19], v[148:151], v[200:203], v[16:19]
	v_mfma_f32_16x16x32_bf16 v[16:19], v[152:155], v[204:207], v[16:19]
	v_mfma_f32_16x16x32_bf16 v[24:27], v[140:143], v[200:203], v[24:27]
	v_mfma_f32_16x16x32_bf16 v[24:27], v[144:147], v[204:207], v[24:27]
	s_barrier
	s_add_i32 s63, 0, 0x18000
	s_add_i32 s64, 0, 0x1c000
	v_add_u32_e32 v152, s63, v217
	v_add_u32_e32 v160, s64, v217
	ds_read_b128 v[140:143], v152
	ds_read_b128 v[144:147], v152 offset:1024
	ds_read_b128 v[148:151], v152 offset:2048
	ds_read_b128 v[152:155], v152 offset:3072
	ds_read_b128 v[156:159], v160
	ds_read_b128 v[164:167], v160 offset:1024
	ds_read_b128 v[168:171], v160 offset:2048
	ds_read_b128 v[172:175], v160 offset:3072
	s_add_u32 s30, s30, 0x4000
	s_addc_u32 s31, s31, 0
	s_mov_b32 m0, s40
	v_lshl_add_u64 v[160:161], s[30:31], 0, v[128:129]
	ds_read_b128 v[176:179], v222 offset:32768
	ds_read_b128 v[180:183], v222 offset:33792
	ds_read_b128 v[184:187], v222 offset:34816
	ds_read_b128 v[188:191], v222 offset:35840
	ds_read_b128 v[192:195], v222 offset:36864
	ds_read_b128 v[196:199], v222 offset:37888
	ds_read_b128 v[200:203], v222 offset:38912
	ds_read_b128 v[204:207], v222 offset:39936
	global_load_lds_dwordx4 v[160:161], off
	v_lshl_add_u64 v[160:161], s[30:31], 0, v[130:131]
	s_mov_b32 m0, s41
	s_nop 0
	global_load_lds_dwordx4 v[160:161], off
	s_waitcnt vmcnt(8)
	s_waitcnt lgkmcnt(0)
	s_barrier
	s_waitcnt lgkmcnt(0)
	v_mfma_f32_16x16x32_bf16 v[124:127], v[140:143], v[176:179], v[124:127]
	v_mfma_f32_16x16x32_bf16 v[124:127], v[144:147], v[180:183], v[124:127]
	v_mfma_f32_16x16x32_bf16 v[120:123], v[148:151], v[176:179], v[120:123]
	v_mfma_f32_16x16x32_bf16 v[120:123], v[152:155], v[180:183], v[120:123]
	v_mfma_f32_16x16x32_bf16 v[108:111], v[156:159], v[176:179], v[108:111]
	v_mfma_f32_16x16x32_bf16 v[108:111], v[164:167], v[180:183], v[108:111]
	v_mfma_f32_16x16x32_bf16 v[100:103], v[168:171], v[176:179], v[100:103]
	v_mfma_f32_16x16x32_bf16 v[100:103], v[172:175], v[180:183], v[100:103]
	v_mfma_f32_16x16x32_bf16 v[84:87], v[168:171], v[184:187], v[84:87]
	v_mfma_f32_16x16x32_bf16 v[84:87], v[172:175], v[188:191], v[84:87]
	v_mfma_f32_16x16x32_bf16 v[92:95], v[156:159], v[184:187], v[92:95]
	v_mfma_f32_16x16x32_bf16 v[92:95], v[164:167], v[188:191], v[92:95]
	v_mfma_f32_16x16x32_bf16 v[112:115], v[148:151], v[184:187], v[112:115]
	v_mfma_f32_16x16x32_bf16 v[112:115], v[152:155], v[188:191], v[112:115]
	v_mfma_f32_16x16x32_bf16 v[116:119], v[140:143], v[184:187], v[116:119]
	v_mfma_f32_16x16x32_bf16 v[116:119], v[144:147], v[188:191], v[116:119]
	v_mfma_f32_16x16x32_bf16 v[104:107], v[140:143], v[192:195], v[104:107]
	v_mfma_f32_16x16x32_bf16 v[104:107], v[144:147], v[196:199], v[104:107]
	v_mfma_f32_16x16x32_bf16 v[96:99], v[148:151], v[192:195], v[96:99]
	v_mfma_f32_16x16x32_bf16 v[96:99], v[152:155], v[196:199], v[96:99]
	v_mfma_f32_16x16x32_bf16 v[76:79], v[156:159], v[192:195], v[76:79]
	v_mfma_f32_16x16x32_bf16 v[76:79], v[164:167], v[196:199], v[76:79]
	v_mfma_f32_16x16x32_bf16 v[72:75], v[168:171], v[192:195], v[72:75]
	v_mfma_f32_16x16x32_bf16 v[72:75], v[172:175], v[196:199], v[72:75]
	v_mfma_f32_16x16x32_bf16 v[64:67], v[168:171], v[200:203], v[64:67]
	v_mfma_f32_16x16x32_bf16 v[64:67], v[172:175], v[204:207], v[64:67]
	v_mfma_f32_16x16x32_bf16 v[68:71], v[156:159], v[200:203], v[68:71]
	v_mfma_f32_16x16x32_bf16 v[68:71], v[164:167], v[204:207], v[68:71]
	v_mfma_f32_16x16x32_bf16 v[80:83], v[148:151], v[200:203], v[80:83]
	v_mfma_f32_16x16x32_bf16 v[80:83], v[152:155], v[204:207], v[80:83]
	v_mfma_f32_16x16x32_bf16 v[88:91], v[140:143], v[200:203], v[88:91]
	v_mfma_f32_16x16x32_bf16 v[88:91], v[144:147], v[204:207], v[88:91]
	s_barrier
	s_add_u32 s30, s28, 0x8000
	s_addc_u32 s31, s29, 0
	s_add_i32 s63, s63, s37
	v_lshl_add_u64 v[160:161], s[30:31], 0, v[128:129]
	s_mov_b32 m0, s63
	ds_read_b128 v[176:179], v222 offset:49152
	ds_read_b128 v[180:183], v222 offset:50176
	ds_read_b128 v[184:187], v222 offset:51200
	ds_read_b128 v[188:191], v222 offset:52224
	ds_read_b128 v[192:195], v222 offset:53248
	ds_read_b128 v[196:199], v222 offset:54272
	ds_read_b128 v[200:203], v222 offset:55296
	ds_read_b128 v[204:207], v222 offset:56320
	global_load_lds_dwordx4 v[160:161], off
	s_add_i32 m0, s63, 0x2000
	s_add_u32 s28, s28, 0xc000
	v_lshl_add_u64 v[160:161], s[30:31], 0, v[130:131]
	s_addc_u32 s29, s29, 0
	s_add_i32 s30, s64, s37
	global_load_lds_dwordx4 v[160:161], off
	v_lshl_add_u64 v[160:161], s[28:29], 0, v[128:129]
	s_mov_b32 m0, s30
	s_nop 0
	global_load_lds_dwordx4 v[160:161], off
	v_lshl_add_u64 v[160:161], s[28:29], 0, v[130:131]
	s_add_i32 m0, s30, 0x2000
	s_nop 0
	global_load_lds_dwordx4 v[160:161], off
	v_lshl_add_u64 v[160:161], s[26:27], 0, v[128:129]
	s_mov_b32 m0, s44
	s_nop 0
	global_load_lds_dwordx4 v[160:161], off
	v_lshl_add_u64 v[160:161], s[26:27], 0, v[130:131]
	s_mov_b32 m0, s45
	s_nop 0
	global_load_lds_dwordx4 v[160:161], off
	s_waitcnt vmcnt(8)
	s_waitcnt lgkmcnt(0)
	s_barrier
	s_waitcnt lgkmcnt(0)
	v_mfma_f32_16x16x32_bf16 v[60:63], v[140:143], v[176:179], v[60:63]
	v_mfma_f32_16x16x32_bf16 v[60:63], v[144:147], v[180:183], v[60:63]
	v_mfma_f32_16x16x32_bf16 v[56:59], v[148:151], v[176:179], v[56:59]
	v_mfma_f32_16x16x32_bf16 v[56:59], v[152:155], v[180:183], v[56:59]
	v_mfma_f32_16x16x32_bf16 v[44:47], v[156:159], v[176:179], v[44:47]
	v_mfma_f32_16x16x32_bf16 v[44:47], v[164:167], v[180:183], v[44:47]
	v_mfma_f32_16x16x32_bf16 v[36:39], v[168:171], v[176:179], v[36:39]
	v_mfma_f32_16x16x32_bf16 v[36:39], v[172:175], v[180:183], v[36:39]
	v_mfma_f32_16x16x32_bf16 v[20:23], v[168:171], v[184:187], v[20:23]
	v_mfma_f32_16x16x32_bf16 v[20:23], v[172:175], v[188:191], v[20:23]
	v_mfma_f32_16x16x32_bf16 v[28:31], v[156:159], v[184:187], v[28:31]
	v_mfma_f32_16x16x32_bf16 v[28:31], v[164:167], v[188:191], v[28:31]
	v_mfma_f32_16x16x32_bf16 v[48:51], v[148:151], v[184:187], v[48:51]
	v_mfma_f32_16x16x32_bf16 v[48:51], v[152:155], v[188:191], v[48:51]
	v_mfma_f32_16x16x32_bf16 v[52:55], v[140:143], v[184:187], v[52:55]
	v_mfma_f32_16x16x32_bf16 v[52:55], v[144:147], v[188:191], v[52:55]
	v_mfma_f32_16x16x32_bf16 v[40:43], v[140:143], v[192:195], v[40:43]
	v_mfma_f32_16x16x32_bf16 v[40:43], v[144:147], v[196:199], v[40:43]
	v_mfma_f32_16x16x32_bf16 v[32:35], v[148:151], v[192:195], v[32:35]
	v_mfma_f32_16x16x32_bf16 v[32:35], v[152:155], v[196:199], v[32:35]
	v_mfma_f32_16x16x32_bf16 v[12:15], v[156:159], v[192:195], v[12:15]
	v_mfma_f32_16x16x32_bf16 v[12:15], v[164:167], v[196:199], v[12:15]
	v_mfma_f32_16x16x32_bf16 v[8:11], v[168:171], v[192:195], v[8:11]
	v_mfma_f32_16x16x32_bf16 v[8:11], v[172:175], v[196:199], v[8:11]
	v_mfma_f32_16x16x32_bf16 v[0:3], v[168:171], v[200:203], v[0:3]
	v_mfma_f32_16x16x32_bf16 v[0:3], v[172:175], v[204:207], v[0:3]
	v_mfma_f32_16x16x32_bf16 v[4:7], v[156:159], v[200:203], v[4:7]
	v_mfma_f32_16x16x32_bf16 v[4:7], v[164:167], v[204:207], v[4:7]
	v_mfma_f32_16x16x32_bf16 v[16:19], v[148:151], v[200:203], v[16:19]
	v_mfma_f32_16x16x32_bf16 v[16:19], v[152:155], v[204:207], v[16:19]
	v_mfma_f32_16x16x32_bf16 v[24:27], v[140:143], v[200:203], v[24:27]
	v_mfma_f32_16x16x32_bf16 v[24:27], v[144:147], v[204:207], v[24:27]
	s_barrier
	s_add_u32 s24, s24, 0x10000
	s_addc_u32 s25, s25, 0
	s_add_u32 s60, s60, 0x10000
	s_addc_u32 s61, s61, 0
	s_cmp_ge_i32 s62, s43
	s_mov_b32 s26, s62
	s_cbranch_scc0 .LBB0_228
	v_pk_mul_f32 v[200:201], v[126:127], 0.5 op_sel_hi:[1,0]
	v_pk_mul_f32 v[202:203], v[124:125], 0.5 op_sel_hi:[1,0]
	v_pk_mul_f32 v[204:205], v[122:123], 0.5 op_sel_hi:[1,0]
	v_pk_mul_f32 v[206:207], v[120:121], 0.5 op_sel_hi:[1,0]
	v_pk_mul_f32 v[210:211], v[110:111], 0.5 op_sel_hi:[1,0]
	v_pk_mul_f32 v[208:209], v[108:109], 0.5 op_sel_hi:[1,0]
	v_pk_mul_f32 v[198:199], v[102:103], 0.5 op_sel_hi:[1,0]
	v_pk_mul_f32 v[196:197], v[100:101], 0.5 op_sel_hi:[1,0]
	v_pk_mul_f32 v[194:195], v[118:119], 0.5 op_sel_hi:[1,0]
	v_pk_mul_f32 v[192:193], v[116:117], 0.5 op_sel_hi:[1,0]
	v_pk_mul_f32 v[190:191], v[114:115], 0.5 op_sel_hi:[1,0]
	v_pk_mul_f32 v[188:189], v[112:113], 0.5 op_sel_hi:[1,0]
	v_pk_mul_f32 v[186:187], v[94:95], 0.5 op_sel_hi:[1,0]
	v_pk_mul_f32 v[184:185], v[92:93], 0.5 op_sel_hi:[1,0]
	v_pk_mul_f32 v[182:183], v[86:87], 0.5 op_sel_hi:[1,0]
	v_pk_mul_f32 v[180:181], v[84:85], 0.5 op_sel_hi:[1,0]
	v_pk_mul_f32 v[178:179], v[106:107], 0.5 op_sel_hi:[1,0]
	v_pk_mul_f32 v[176:177], v[104:105], 0.5 op_sel_hi:[1,0]
	v_pk_mul_f32 v[174:175], v[98:99], 0.5 op_sel_hi:[1,0]
	v_pk_mul_f32 v[172:173], v[96:97], 0.5 op_sel_hi:[1,0]
	v_pk_mul_f32 v[170:171], v[78:79], 0.5 op_sel_hi:[1,0]
	v_pk_mul_f32 v[168:169], v[76:77], 0.5 op_sel_hi:[1,0]
	v_pk_mul_f32 v[166:167], v[74:75], 0.5 op_sel_hi:[1,0]
	v_pk_mul_f32 v[164:165], v[72:73], 0.5 op_sel_hi:[1,0]
	v_pk_mul_f32 v[160:161], v[90:91], 0.5 op_sel_hi:[1,0]
	v_pk_mul_f32 v[158:159], v[88:89], 0.5 op_sel_hi:[1,0]
	v_pk_mul_f32 v[156:157], v[82:83], 0.5 op_sel_hi:[1,0]
	v_pk_mul_f32 v[154:155], v[80:81], 0.5 op_sel_hi:[1,0]
	v_pk_mul_f32 v[152:153], v[70:71], 0.5 op_sel_hi:[1,0]
	v_pk_mul_f32 v[150:151], v[68:69], 0.5 op_sel_hi:[1,0]
	v_pk_mul_f32 v[148:149], v[66:67], 0.5 op_sel_hi:[1,0]
	v_pk_mul_f32 v[146:147], v[64:65], 0.5 op_sel_hi:[1,0]
	v_pk_mul_f32 v[144:145], v[62:63], 0.5 op_sel_hi:[1,0]
	v_pk_mul_f32 v[142:143], v[60:61], 0.5 op_sel_hi:[1,0]
	v_pk_mul_f32 v[126:127], v[58:59], 0.5 op_sel_hi:[1,0]
	v_pk_mul_f32 v[124:125], v[56:57], 0.5 op_sel_hi:[1,0]
	v_pk_mul_f32 v[122:123], v[46:47], 0.5 op_sel_hi:[1,0]
	v_pk_mul_f32 v[120:121], v[44:45], 0.5 op_sel_hi:[1,0]
	v_pk_mul_f32 v[118:119], v[38:39], 0.5 op_sel_hi:[1,0]
	v_pk_mul_f32 v[116:117], v[36:37], 0.5 op_sel_hi:[1,0]
	v_pk_mul_f32 v[114:115], v[54:55], 0.5 op_sel_hi:[1,0]
	v_pk_mul_f32 v[112:113], v[52:53], 0.5 op_sel_hi:[1,0]
	v_pk_mul_f32 v[110:111], v[50:51], 0.5 op_sel_hi:[1,0]
	v_pk_mul_f32 v[108:109], v[48:49], 0.5 op_sel_hi:[1,0]
	v_pk_mul_f32 v[106:107], v[30:31], 0.5 op_sel_hi:[1,0]
	v_pk_mul_f32 v[104:105], v[28:29], 0.5 op_sel_hi:[1,0]
	v_pk_mul_f32 v[102:103], v[22:23], 0.5 op_sel_hi:[1,0]
	v_pk_mul_f32 v[100:101], v[20:21], 0.5 op_sel_hi:[1,0]
	v_pk_mul_f32 v[98:99], v[42:43], 0.5 op_sel_hi:[1,0]
	v_pk_mul_f32 v[96:97], v[40:41], 0.5 op_sel_hi:[1,0]
	v_pk_mul_f32 v[94:95], v[34:35], 0.5 op_sel_hi:[1,0]
	v_pk_mul_f32 v[92:93], v[32:33], 0.5 op_sel_hi:[1,0]
	v_pk_mul_f32 v[90:91], v[14:15], 0.5 op_sel_hi:[1,0]
	v_pk_mul_f32 v[88:89], v[12:13], 0.5 op_sel_hi:[1,0]
	v_pk_mul_f32 v[86:87], v[10:11], 0.5 op_sel_hi:[1,0]
	v_pk_mul_f32 v[84:85], v[8:9], 0.5 op_sel_hi:[1,0]
	v_pk_mul_f32 v[82:83], v[26:27], 0.5 op_sel_hi:[1,0]
	v_pk_mul_f32 v[80:81], v[24:25], 0.5 op_sel_hi:[1,0]
	v_pk_mul_f32 v[78:79], v[18:19], 0.5 op_sel_hi:[1,0]
	v_pk_mul_f32 v[76:77], v[16:17], 0.5 op_sel_hi:[1,0]
	v_pk_mul_f32 v[74:75], v[6:7], 0.5 op_sel_hi:[1,0]
	v_pk_mul_f32 v[72:73], v[4:5], 0.5 op_sel_hi:[1,0]
	v_pk_mul_f32 v[70:71], v[2:3], 0.5 op_sel_hi:[1,0]
	v_pk_mul_f32 v[68:69], v[0:1], 0.5 op_sel_hi:[1,0]

.LBB0_323:
	ds_read_b128 v[128:131], v222
	ds_read_b128 v[132:135], v222 offset:1024
	ds_read_b128 v[136:139], v222 offset:2048
	ds_read_b128 v[140:143], v222 offset:3072
	ds_read_b128 v[144:147], v223
	ds_read_b128 v[148:151], v223 offset:1024
	ds_read_b128 v[152:155], v223 offset:2048
	ds_read_b128 v[156:159], v223 offset:3072
	s_add_i32 s53, s50, 2
	s_add_u32 s54, s0, 0x80
	s_addc_u32 s51, s1, 0
	s_cmp_eq_u32 s78, s50
	s_cselect_b32 s50, s46, s54
	s_cselect_b32 s51, s47, s51
	s_cselect_b32 s55, s49, s52
	s_cselect_b32 s54, s48, s33
	v_lshl_add_u64 v[160:161], s[0:1], 0, v[176:177]
	s_add_i32 m0, s71, 0xc000
	ds_read_b128 v[184:187], v224
	ds_read_b128 v[188:191], v224 offset:1024
	ds_read_b128 v[192:195], v224 offset:2048
	ds_read_b128 v[196:199], v224 offset:3072
	ds_read_b128 v[200:203], v224 offset:4096
	ds_read_b128 v[204:207], v224 offset:5120
	ds_read_b128 v[208:211], v224 offset:6144
	ds_read_b128 v[212:215], v224 offset:7168
	global_load_lds_dwordx4 v[160:161], off
	v_lshl_add_u64 v[160:161], s[0:1], 0, v[178:179]
	s_add_i32 m0, s71, 0xe000
	s_nop 0
	global_load_lds_dwordx4 v[160:161], off
	s_waitcnt vmcnt(8)
	s_waitcnt lgkmcnt(0)
	s_barrier
	s_waitcnt lgkmcnt(0)
	v_mfma_f32_16x16x32_bf16 v[124:127], v[128:131], v[184:187], v[124:127]
	v_mfma_f32_16x16x32_bf16 v[124:127], v[132:135], v[188:191], v[124:127]
	v_mfma_f32_16x16x32_bf16 v[120:123], v[136:139], v[184:187], v[120:123]
	v_mfma_f32_16x16x32_bf16 v[120:123], v[140:143], v[188:191], v[120:123]
	v_mfma_f32_16x16x32_bf16 v[116:119], v[144:147], v[184:187], v[116:119]
	v_mfma_f32_16x16x32_bf16 v[116:119], v[148:151], v[188:191], v[116:119]
	v_mfma_f32_16x16x32_bf16 v[112:115], v[152:155], v[184:187], v[112:115]
	v_mfma_f32_16x16x32_bf16 v[112:115], v[156:159], v[188:191], v[112:115]
	v_mfma_f32_16x16x32_bf16 v[96:99], v[152:155], v[192:195], v[96:99]
	v_mfma_f32_16x16x32_bf16 v[96:99], v[156:159], v[196:199], v[96:99]
	v_mfma_f32_16x16x32_bf16 v[100:103], v[144:147], v[192:195], v[100:103]
	v_mfma_f32_16x16x32_bf16 v[100:103], v[148:151], v[196:199], v[100:103]
	v_mfma_f32_16x16x32_bf16 v[104:107], v[136:139], v[192:195], v[104:107]
	v_mfma_f32_16x16x32_bf16 v[104:107], v[140:143], v[196:199], v[104:107]
	v_mfma_f32_16x16x32_bf16 v[108:111], v[128:131], v[192:195], v[108:111]
	v_mfma_f32_16x16x32_bf16 v[108:111], v[132:135], v[196:199], v[108:111]
	v_mfma_f32_16x16x32_bf16 v[92:95], v[128:131], v[200:203], v[92:95]
	v_mfma_f32_16x16x32_bf16 v[92:95], v[132:135], v[204:207], v[92:95]
	v_mfma_f32_16x16x32_bf16 v[88:91], v[136:139], v[200:203], v[88:91]
	v_mfma_f32_16x16x32_bf16 v[88:91], v[140:143], v[204:207], v[88:91]
	v_mfma_f32_16x16x32_bf16 v[84:87], v[144:147], v[200:203], v[84:87]
	v_mfma_f32_16x16x32_bf16 v[84:87], v[148:151], v[204:207], v[84:87]
	v_mfma_f32_16x16x32_bf16 v[80:83], v[152:155], v[200:203], v[80:83]
	v_mfma_f32_16x16x32_bf16 v[80:83], v[156:159], v[204:207], v[80:83]
	v_mfma_f32_16x16x32_bf16 v[64:67], v[152:155], v[208:211], v[64:67]
	v_mfma_f32_16x16x32_bf16 v[64:67], v[156:159], v[212:215], v[64:67]
	v_mfma_f32_16x16x32_bf16 v[68:71], v[144:147], v[208:211], v[68:71]
	v_mfma_f32_16x16x32_bf16 v[68:71], v[148:151], v[212:215], v[68:71]
	v_mfma_f32_16x16x32_bf16 v[72:75], v[136:139], v[208:211], v[72:75]
	v_mfma_f32_16x16x32_bf16 v[72:75], v[140:143], v[212:215], v[72:75]
	v_mfma_f32_16x16x32_bf16 v[76:79], v[128:131], v[208:211], v[76:79]
	v_mfma_f32_16x16x32_bf16 v[76:79], v[132:135], v[212:215], v[76:79]
	s_barrier
	s_add_i32 s60, s82, s70
	v_lshl_add_u64 v[160:161], s[54:55], 0, v[166:167]
	s_mov_b32 m0, s60
	ds_read_b128 v[184:187], v224 offset:16384
	ds_read_b128 v[188:191], v224 offset:17408
	ds_read_b128 v[192:195], v224 offset:18432
	ds_read_b128 v[196:199], v224 offset:19456
	ds_read_b128 v[200:203], v224 offset:20480
	ds_read_b128 v[204:207], v224 offset:21504
	ds_read_b128 v[208:211], v224 offset:22528
	ds_read_b128 v[212:215], v224 offset:23552
	global_load_lds_dwordx4 v[160:161], off
	s_add_i32 m0, s60, 0x2000
	v_lshl_add_u64 v[216:217], s[54:55], 0, v[170:171]
	s_add_u32 s54, s54, s10
	s_addc_u32 s55, s55, s11
	s_add_i32 s60, s83, s70
	global_load_lds_dwordx4 v[216:217], off
	v_lshl_add_u64 v[218:219], s[54:55], 0, v[166:167]
	s_mov_b32 m0, s60
	v_lshl_add_u64 v[230:231], s[54:55], 0, v[170:171]
	global_load_lds_dwordx4 v[218:219], off
	s_add_i32 m0, s60, 0x2000
	v_lshl_add_u64 v[232:233], s[50:51], 0, v[164:165]
	global_load_lds_dwordx4 v[230:231], off
	s_mov_b32 m0, s71
	v_lshl_add_u64 v[234:235], s[50:51], 0, v[168:169]
	global_load_lds_dwordx4 v[232:233], off
	s_mov_b32 m0, s72
	s_nop 0
	global_load_lds_dwordx4 v[234:235], off
	s_waitcnt vmcnt(8)
	s_waitcnt lgkmcnt(0)
	s_barrier
	s_waitcnt lgkmcnt(0)
	v_mfma_f32_16x16x32_bf16 v[60:63], v[128:131], v[184:187], v[60:63]
	v_mfma_f32_16x16x32_bf16 v[60:63], v[132:135], v[188:191], v[60:63]
	v_mfma_f32_16x16x32_bf16 v[56:59], v[136:139], v[184:187], v[56:59]
	v_mfma_f32_16x16x32_bf16 v[56:59], v[140:143], v[188:191], v[56:59]
	v_mfma_f32_16x16x32_bf16 v[52:55], v[144:147], v[184:187], v[52:55]
	v_mfma_f32_16x16x32_bf16 v[52:55], v[148:151], v[188:191], v[52:55]
	v_mfma_f32_16x16x32_bf16 v[48:51], v[152:155], v[184:187], v[48:51]
	v_mfma_f32_16x16x32_bf16 v[48:51], v[156:159], v[188:191], v[48:51]
	v_mfma_f32_16x16x32_bf16 v[32:35], v[152:155], v[192:195], v[32:35]
	v_mfma_f32_16x16x32_bf16 v[32:35], v[156:159], v[196:199], v[32:35]
	v_mfma_f32_16x16x32_bf16 v[36:39], v[144:147], v[192:195], v[36:39]
	v_mfma_f32_16x16x32_bf16 v[36:39], v[148:151], v[196:199], v[36:39]
	v_mfma_f32_16x16x32_bf16 v[40:43], v[136:139], v[192:195], v[40:43]
	v_mfma_f32_16x16x32_bf16 v[40:43], v[140:143], v[196:199], v[40:43]
	v_mfma_f32_16x16x32_bf16 v[44:47], v[128:131], v[192:195], v[44:47]
	v_mfma_f32_16x16x32_bf16 v[44:47], v[132:135], v[196:199], v[44:47]
	v_mfma_f32_16x16x32_bf16 v[28:31], v[128:131], v[200:203], v[28:31]
	v_mfma_f32_16x16x32_bf16 v[28:31], v[132:135], v[204:207], v[28:31]
	v_mfma_f32_16x16x32_bf16 v[24:27], v[136:139], v[200:203], v[24:27]
	v_mfma_f32_16x16x32_bf16 v[24:27], v[140:143], v[204:207], v[24:27]
	v_mfma_f32_16x16x32_bf16 v[20:23], v[144:147], v[200:203], v[20:23]
	v_mfma_f32_16x16x32_bf16 v[20:23], v[148:151], v[204:207], v[20:23]
	v_mfma_f32_16x16x32_bf16 v[16:19], v[152:155], v[200:203], v[16:19]
	v_mfma_f32_16x16x32_bf16 v[16:19], v[156:159], v[204:207], v[16:19]
	v_mfma_f32_16x16x32_bf16 v[0:3], v[152:155], v[208:211], v[0:3]
	v_mfma_f32_16x16x32_bf16 v[0:3], v[156:159], v[212:215], v[0:3]
	v_mfma_f32_16x16x32_bf16 v[4:7], v[144:147], v[208:211], v[4:7]
	v_mfma_f32_16x16x32_bf16 v[4:7], v[148:151], v[212:215], v[4:7]
	v_mfma_f32_16x16x32_bf16 v[8:11], v[136:139], v[208:211], v[8:11]
	v_mfma_f32_16x16x32_bf16 v[8:11], v[140:143], v[212:215], v[8:11]
	v_mfma_f32_16x16x32_bf16 v[12:15], v[128:131], v[208:211], v[12:15]
	v_mfma_f32_16x16x32_bf16 v[12:15], v[132:135], v[212:215], v[12:15]
	s_barrier
	s_add_i32 s54, 0, 0x18000
	s_add_i32 s55, 0, 0x1c000
	v_add_u32_e32 v140, s54, v221
	v_add_u32_e32 v156, s55, v221
	ds_read_b128 v[128:131], v140
	ds_read_b128 v[132:135], v140 offset:1024
	ds_read_b128 v[136:139], v140 offset:2048
	ds_read_b128 v[140:143], v140 offset:3072
	ds_read_b128 v[144:147], v156
	ds_read_b128 v[148:151], v156 offset:1024
	ds_read_b128 v[152:155], v156 offset:2048
	ds_read_b128 v[156:159], v156 offset:3072
	s_add_u32 s50, s50, s10
	s_addc_u32 s51, s51, s11
	s_mov_b32 m0, s73
	v_lshl_add_u64 v[236:237], s[50:51], 0, v[164:165]
	ds_read_b128 v[184:187], v224 offset:32768
	ds_read_b128 v[188:191], v224 offset:33792
	ds_read_b128 v[192:195], v224 offset:34816
	ds_read_b128 v[196:199], v224 offset:35840
	ds_read_b128 v[200:203], v224 offset:36864
	ds_read_b128 v[204:207], v224 offset:37888
	ds_read_b128 v[208:211], v224 offset:38912
	ds_read_b128 v[212:215], v224 offset:39936
	global_load_lds_dwordx4 v[236:237], off
	v_lshl_add_u64 v[236:237], s[50:51], 0, v[168:169]
	s_mov_b32 m0, s74
	s_nop 0
	global_load_lds_dwordx4 v[236:237], off
	s_waitcnt vmcnt(8)
	s_waitcnt lgkmcnt(0)
	s_barrier
	s_waitcnt lgkmcnt(0)
	v_mfma_f32_16x16x32_bf16 v[124:127], v[128:131], v[184:187], v[124:127]
	v_mfma_f32_16x16x32_bf16 v[124:127], v[132:135], v[188:191], v[124:127]
	v_mfma_f32_16x16x32_bf16 v[120:123], v[136:139], v[184:187], v[120:123]
	v_mfma_f32_16x16x32_bf16 v[120:123], v[140:143], v[188:191], v[120:123]
	v_mfma_f32_16x16x32_bf16 v[116:119], v[144:147], v[184:187], v[116:119]
	v_mfma_f32_16x16x32_bf16 v[116:119], v[148:151], v[188:191], v[116:119]
	v_mfma_f32_16x16x32_bf16 v[112:115], v[152:155], v[184:187], v[112:115]
	v_mfma_f32_16x16x32_bf16 v[112:115], v[156:159], v[188:191], v[112:115]
	v_mfma_f32_16x16x32_bf16 v[96:99], v[152:155], v[192:195], v[96:99]
	v_mfma_f32_16x16x32_bf16 v[96:99], v[156:159], v[196:199], v[96:99]
	v_mfma_f32_16x16x32_bf16 v[100:103], v[144:147], v[192:195], v[100:103]
	v_mfma_f32_16x16x32_bf16 v[100:103], v[148:151], v[196:199], v[100:103]
	v_mfma_f32_16x16x32_bf16 v[104:107], v[136:139], v[192:195], v[104:107]
	v_mfma_f32_16x16x32_bf16 v[104:107], v[140:143], v[196:199], v[104:107]
	v_mfma_f32_16x16x32_bf16 v[108:111], v[128:131], v[192:195], v[108:111]
	v_mfma_f32_16x16x32_bf16 v[108:111], v[132:135], v[196:199], v[108:111]
	v_mfma_f32_16x16x32_bf16 v[92:95], v[128:131], v[200:203], v[92:95]
	v_mfma_f32_16x16x32_bf16 v[92:95], v[132:135], v[204:207], v[92:95]
	v_mfma_f32_16x16x32_bf16 v[88:91], v[136:139], v[200:203], v[88:91]
	v_mfma_f32_16x16x32_bf16 v[88:91], v[140:143], v[204:207], v[88:91]
	v_mfma_f32_16x16x32_bf16 v[84:87], v[144:147], v[200:203], v[84:87]
	v_mfma_f32_16x16x32_bf16 v[84:87], v[148:151], v[204:207], v[84:87]
	v_mfma_f32_16x16x32_bf16 v[80:83], v[152:155], v[200:203], v[80:83]
	v_mfma_f32_16x16x32_bf16 v[80:83], v[156:159], v[204:207], v[80:83]
	v_mfma_f32_16x16x32_bf16 v[64:67], v[152:155], v[208:211], v[64:67]
	v_mfma_f32_16x16x32_bf16 v[64:67], v[156:159], v[212:215], v[64:67]
	v_mfma_f32_16x16x32_bf16 v[68:71], v[144:147], v[208:211], v[68:71]
	v_mfma_f32_16x16x32_bf16 v[68:71], v[148:151], v[212:215], v[68:71]
	v_mfma_f32_16x16x32_bf16 v[72:75], v[136:139], v[208:211], v[72:75]
	v_mfma_f32_16x16x32_bf16 v[72:75], v[140:143], v[212:215], v[72:75]
	v_mfma_f32_16x16x32_bf16 v[76:79], v[128:131], v[208:211], v[76:79]
	v_mfma_f32_16x16x32_bf16 v[76:79], v[132:135], v[212:215], v[76:79]
	s_barrier
	s_add_i32 s50, s54, s70
	v_lshl_add_u64 v[160:161], v[160:161], 0, s[36:37]
	s_mov_b32 m0, s50
	ds_read_b128 v[184:187], v224 offset:49152
	ds_read_b128 v[188:191], v224 offset:50176
	ds_read_b128 v[192:195], v224 offset:51200
	ds_read_b128 v[196:199], v224 offset:52224
	ds_read_b128 v[200:203], v224 offset:53248
	ds_read_b128 v[204:207], v224 offset:54272
	ds_read_b128 v[208:211], v224 offset:55296
	ds_read_b128 v[212:215], v224 offset:56320
	global_load_lds_dwordx4 v[160:161], off
	v_lshl_add_u64 v[160:161], v[216:217], 0, s[36:37]
	s_add_i32 m0, s50, 0x2000
	s_add_i32 s50, s55, s70
	global_load_lds_dwordx4 v[160:161], off
	v_lshl_add_u64 v[160:161], v[218:219], 0, s[36:37]
	s_mov_b32 m0, s50
	s_nop 0
	global_load_lds_dwordx4 v[160:161], off
	v_lshl_add_u64 v[160:161], v[230:231], 0, s[36:37]
	s_add_i32 m0, s50, 0x2000
	s_nop 0
	global_load_lds_dwordx4 v[160:161], off
	v_lshl_add_u64 v[160:161], v[232:233], 0, s[36:37]
	s_mov_b32 m0, s76
	s_nop 0
	global_load_lds_dwordx4 v[160:161], off
	v_lshl_add_u64 v[160:161], v[234:235], 0, s[36:37]
	s_mov_b32 m0, s77
	s_nop 0
	global_load_lds_dwordx4 v[160:161], off
	s_waitcnt vmcnt(8)
	s_waitcnt lgkmcnt(0)
	s_barrier
	s_waitcnt lgkmcnt(0)
	v_mfma_f32_16x16x32_bf16 v[60:63], v[128:131], v[184:187], v[60:63]
	v_mfma_f32_16x16x32_bf16 v[60:63], v[132:135], v[188:191], v[60:63]
	v_mfma_f32_16x16x32_bf16 v[56:59], v[136:139], v[184:187], v[56:59]
	v_mfma_f32_16x16x32_bf16 v[56:59], v[140:143], v[188:191], v[56:59]
	v_mfma_f32_16x16x32_bf16 v[52:55], v[144:147], v[184:187], v[52:55]
	v_mfma_f32_16x16x32_bf16 v[52:55], v[148:151], v[188:191], v[52:55]
	v_mfma_f32_16x16x32_bf16 v[48:51], v[152:155], v[184:187], v[48:51]
	v_mfma_f32_16x16x32_bf16 v[48:51], v[156:159], v[188:191], v[48:51]
	v_mfma_f32_16x16x32_bf16 v[32:35], v[152:155], v[192:195], v[32:35]
	v_mfma_f32_16x16x32_bf16 v[32:35], v[156:159], v[196:199], v[32:35]
	v_mfma_f32_16x16x32_bf16 v[36:39], v[144:147], v[192:195], v[36:39]
	v_mfma_f32_16x16x32_bf16 v[36:39], v[148:151], v[196:199], v[36:39]
	v_mfma_f32_16x16x32_bf16 v[40:43], v[136:139], v[192:195], v[40:43]
	v_mfma_f32_16x16x32_bf16 v[40:43], v[140:143], v[196:199], v[40:43]
	v_mfma_f32_16x16x32_bf16 v[44:47], v[128:131], v[192:195], v[44:47]
	v_mfma_f32_16x16x32_bf16 v[44:47], v[132:135], v[196:199], v[44:47]
	v_mfma_f32_16x16x32_bf16 v[28:31], v[128:131], v[200:203], v[28:31]
	v_mfma_f32_16x16x32_bf16 v[28:31], v[132:135], v[204:207], v[28:31]
	v_mfma_f32_16x16x32_bf16 v[24:27], v[136:139], v[200:203], v[24:27]
	v_mfma_f32_16x16x32_bf16 v[24:27], v[140:143], v[204:207], v[24:27]
	v_mfma_f32_16x16x32_bf16 v[20:23], v[144:147], v[200:203], v[20:23]
	v_mfma_f32_16x16x32_bf16 v[20:23], v[148:151], v[204:207], v[20:23]
	v_mfma_f32_16x16x32_bf16 v[16:19], v[152:155], v[200:203], v[16:19]
	v_mfma_f32_16x16x32_bf16 v[16:19], v[156:159], v[204:207], v[16:19]
	v_mfma_f32_16x16x32_bf16 v[0:3], v[152:155], v[208:211], v[0:3]
	v_mfma_f32_16x16x32_bf16 v[0:3], v[156:159], v[212:215], v[0:3]
	v_mfma_f32_16x16x32_bf16 v[4:7], v[144:147], v[208:211], v[4:7]
	v_mfma_f32_16x16x32_bf16 v[4:7], v[148:151], v[212:215], v[4:7]
	v_mfma_f32_16x16x32_bf16 v[8:11], v[136:139], v[208:211], v[8:11]
	v_mfma_f32_16x16x32_bf16 v[8:11], v[140:143], v[212:215], v[8:11]
	v_mfma_f32_16x16x32_bf16 v[12:15], v[128:131], v[208:211], v[12:15]
	v_mfma_f32_16x16x32_bf16 v[12:15], v[132:135], v[212:215], v[12:15]
	s_barrier
	s_add_u32 s0, s0, 0x100
	s_addc_u32 s1, s1, 0
	s_add_u32 s33, s33, 0x100
	s_addc_u32 s52, s52, 0
	s_cmp_ge_i32 s53, s75
	s_mov_b32 s50, s53
	s_cbranch_scc0 .LBB0_323

.LBB0_592:
	ds_read_b128 v[144:147], v157
	ds_read_b128 v[148:151], v157 offset:1024
	ds_read_b128 v[164:167], v157 offset:2048
	ds_read_b128 v[168:171], v157 offset:3072
	ds_read_b128 v[172:175], v158
	ds_read_b128 v[176:179], v158 offset:1024
	ds_read_b128 v[180:183], v158 offset:2048
	ds_read_b128 v[184:187], v158 offset:3072
	s_add_i32 s64, s34, 2
	s_add_u32 s65, s30, 0x80
	s_addc_u32 s35, s31, 0
	s_cmp_eq_u32 s49, s34
	s_cselect_b32 s34, s2, s65
	s_cselect_b32 s35, s3, s35
	s_cselect_b32 s67, s29, s63
	s_cselect_b32 s66, s28, s62
	v_lshl_add_u64 v[152:153], s[30:31], 0, v[136:137]
	s_add_i32 m0, s41, 0xc000
	ds_read_b128 v[188:191], v159
	ds_read_b128 v[192:195], v159 offset:1024
	ds_read_b128 v[196:199], v159 offset:2048
	ds_read_b128 v[200:203], v159 offset:3072
	ds_read_b128 v[204:207], v159 offset:4096
	ds_read_b128 v[208:211], v159 offset:5120
	ds_read_b128 v[212:215], v159 offset:6144
	ds_read_b128 v[216:219], v159 offset:7168
	global_load_lds_dwordx4 v[152:153], off
	v_lshl_add_u64 v[152:153], s[30:31], 0, v[138:139]
	s_add_i32 m0, s41, 0xe000
	s_nop 0
	global_load_lds_dwordx4 v[152:153], off
	s_waitcnt vmcnt(8)
	s_waitcnt lgkmcnt(0)
	s_barrier
	s_waitcnt lgkmcnt(0)
	v_mfma_f32_16x16x32_bf16 v[120:123], v[144:147], v[188:191], v[120:123]
	v_mfma_f32_16x16x32_bf16 v[120:123], v[148:151], v[192:195], v[120:123]
	v_mfma_f32_16x16x32_bf16 v[124:127], v[164:167], v[188:191], v[124:127]
	v_mfma_f32_16x16x32_bf16 v[124:127], v[168:171], v[192:195], v[124:127]
	v_mfma_f32_16x16x32_bf16 v[116:119], v[172:175], v[188:191], v[116:119]
	v_mfma_f32_16x16x32_bf16 v[116:119], v[176:179], v[192:195], v[116:119]
	v_mfma_f32_16x16x32_bf16 v[112:115], v[180:183], v[188:191], v[112:115]
	v_mfma_f32_16x16x32_bf16 v[112:115], v[184:187], v[192:195], v[112:115]
	v_mfma_f32_16x16x32_bf16 v[96:99], v[180:183], v[196:199], v[96:99]
	v_mfma_f32_16x16x32_bf16 v[96:99], v[184:187], v[200:203], v[96:99]
	v_mfma_f32_16x16x32_bf16 v[100:103], v[172:175], v[196:199], v[100:103]
	v_mfma_f32_16x16x32_bf16 v[100:103], v[176:179], v[200:203], v[100:103]
	v_mfma_f32_16x16x32_bf16 v[104:107], v[164:167], v[196:199], v[104:107]
	v_mfma_f32_16x16x32_bf16 v[104:107], v[168:171], v[200:203], v[104:107]
	v_mfma_f32_16x16x32_bf16 v[108:111], v[144:147], v[196:199], v[108:111]
	v_mfma_f32_16x16x32_bf16 v[108:111], v[148:151], v[200:203], v[108:111]
	v_mfma_f32_16x16x32_bf16 v[92:95], v[144:147], v[204:207], v[92:95]
	v_mfma_f32_16x16x32_bf16 v[92:95], v[148:151], v[208:211], v[92:95]
	v_mfma_f32_16x16x32_bf16 v[88:91], v[164:167], v[204:207], v[88:91]
	v_mfma_f32_16x16x32_bf16 v[88:91], v[168:171], v[208:211], v[88:91]
	v_mfma_f32_16x16x32_bf16 v[84:87], v[172:175], v[204:207], v[84:87]
	v_mfma_f32_16x16x32_bf16 v[84:87], v[176:179], v[208:211], v[84:87]
	v_mfma_f32_16x16x32_bf16 v[80:83], v[180:183], v[204:207], v[80:83]
	v_mfma_f32_16x16x32_bf16 v[80:83], v[184:187], v[208:211], v[80:83]
	v_mfma_f32_16x16x32_bf16 v[64:67], v[180:183], v[212:215], v[64:67]
	v_mfma_f32_16x16x32_bf16 v[64:67], v[184:187], v[216:219], v[64:67]
	v_mfma_f32_16x16x32_bf16 v[68:71], v[172:175], v[212:215], v[68:71]
	v_mfma_f32_16x16x32_bf16 v[68:71], v[176:179], v[216:219], v[68:71]
	v_mfma_f32_16x16x32_bf16 v[72:75], v[164:167], v[212:215], v[72:75]
	v_mfma_f32_16x16x32_bf16 v[72:75], v[168:171], v[216:219], v[72:75]
	v_mfma_f32_16x16x32_bf16 v[76:79], v[144:147], v[212:215], v[76:79]
	v_mfma_f32_16x16x32_bf16 v[76:79], v[148:151], v[216:219], v[76:79]
	s_barrier
	s_add_i32 s65, s52, s40
	v_lshl_add_u64 v[152:153], s[66:67], 0, v[130:131]
	s_mov_b32 m0, s65
	ds_read_b128 v[188:191], v159 offset:16384
	ds_read_b128 v[192:195], v159 offset:17408
	ds_read_b128 v[196:199], v159 offset:18432
	ds_read_b128 v[200:203], v159 offset:19456
	ds_read_b128 v[204:207], v159 offset:20480
	ds_read_b128 v[208:211], v159 offset:21504
	ds_read_b128 v[212:215], v159 offset:22528
	ds_read_b128 v[216:219], v159 offset:23552
	global_load_lds_dwordx4 v[152:153], off
	s_add_i32 m0, s65, 0x2000
	v_lshl_add_u64 v[160:161], s[66:67], 0, v[134:135]
	s_add_u32 s66, s66, s8
	s_addc_u32 s67, s67, s9
	s_add_i32 s65, s53, s40
	global_load_lds_dwordx4 v[160:161], off
	v_lshl_add_u64 v[222:223], s[66:67], 0, v[130:131]
	s_mov_b32 m0, s65
	v_lshl_add_u64 v[224:225], s[66:67], 0, v[134:135]
	global_load_lds_dwordx4 v[222:223], off
	s_add_i32 m0, s65, 0x2000
	v_lshl_add_u64 v[226:227], s[34:35], 0, v[128:129]
	global_load_lds_dwordx4 v[224:225], off
	s_mov_b32 m0, s41
	v_lshl_add_u64 v[228:229], s[34:35], 0, v[132:133]
	global_load_lds_dwordx4 v[226:227], off
	s_mov_b32 m0, s42
	s_nop 0
	global_load_lds_dwordx4 v[228:229], off
	s_waitcnt vmcnt(8)
	s_waitcnt lgkmcnt(0)
	s_barrier
	s_waitcnt lgkmcnt(0)
	v_mfma_f32_16x16x32_bf16 v[60:63], v[144:147], v[188:191], v[60:63]
	v_mfma_f32_16x16x32_bf16 v[60:63], v[148:151], v[192:195], v[60:63]
	v_mfma_f32_16x16x32_bf16 v[56:59], v[164:167], v[188:191], v[56:59]
	v_mfma_f32_16x16x32_bf16 v[56:59], v[168:171], v[192:195], v[56:59]
	v_mfma_f32_16x16x32_bf16 v[52:55], v[172:175], v[188:191], v[52:55]
	v_mfma_f32_16x16x32_bf16 v[52:55], v[176:179], v[192:195], v[52:55]
	v_mfma_f32_16x16x32_bf16 v[48:51], v[180:183], v[188:191], v[48:51]
	v_mfma_f32_16x16x32_bf16 v[48:51], v[184:187], v[192:195], v[48:51]
	v_mfma_f32_16x16x32_bf16 v[32:35], v[180:183], v[196:199], v[32:35]
	v_mfma_f32_16x16x32_bf16 v[32:35], v[184:187], v[200:203], v[32:35]
	v_mfma_f32_16x16x32_bf16 v[36:39], v[172:175], v[196:199], v[36:39]
	v_mfma_f32_16x16x32_bf16 v[36:39], v[176:179], v[200:203], v[36:39]
	v_mfma_f32_16x16x32_bf16 v[40:43], v[164:167], v[196:199], v[40:43]
	v_mfma_f32_16x16x32_bf16 v[40:43], v[168:171], v[200:203], v[40:43]
	v_mfma_f32_16x16x32_bf16 v[44:47], v[144:147], v[196:199], v[44:47]
	v_mfma_f32_16x16x32_bf16 v[44:47], v[148:151], v[200:203], v[44:47]
	v_mfma_f32_16x16x32_bf16 v[28:31], v[144:147], v[204:207], v[28:31]
	v_mfma_f32_16x16x32_bf16 v[28:31], v[148:151], v[208:211], v[28:31]
	v_mfma_f32_16x16x32_bf16 v[24:27], v[164:167], v[204:207], v[24:27]
	v_mfma_f32_16x16x32_bf16 v[24:27], v[168:171], v[208:211], v[24:27]
	v_mfma_f32_16x16x32_bf16 v[20:23], v[172:175], v[204:207], v[20:23]
	v_mfma_f32_16x16x32_bf16 v[20:23], v[176:179], v[208:211], v[20:23]
	v_mfma_f32_16x16x32_bf16 v[16:19], v[180:183], v[204:207], v[16:19]
	v_mfma_f32_16x16x32_bf16 v[16:19], v[184:187], v[208:211], v[16:19]
	v_mfma_f32_16x16x32_bf16 v[0:3], v[180:183], v[212:215], v[0:3]
	v_mfma_f32_16x16x32_bf16 v[0:3], v[184:187], v[216:219], v[0:3]
	v_mfma_f32_16x16x32_bf16 v[4:7], v[172:175], v[212:215], v[4:7]
	v_mfma_f32_16x16x32_bf16 v[4:7], v[176:179], v[216:219], v[4:7]
	v_mfma_f32_16x16x32_bf16 v[8:11], v[164:167], v[212:215], v[8:11]
	v_mfma_f32_16x16x32_bf16 v[8:11], v[168:171], v[216:219], v[8:11]
	v_mfma_f32_16x16x32_bf16 v[12:15], v[144:147], v[212:215], v[12:15]
	v_mfma_f32_16x16x32_bf16 v[12:15], v[148:151], v[216:219], v[12:15]
	s_barrier
	s_add_i32 s65, 0, 0x18000
	s_add_i32 s66, 0, 0x1c000
	v_add_u32_e32 v168, s65, v155
	v_add_u32_e32 v184, s66, v155
	ds_read_b128 v[144:147], v168
	ds_read_b128 v[148:151], v168 offset:1024
	ds_read_b128 v[164:167], v168 offset:2048
	ds_read_b128 v[168:171], v168 offset:3072
	ds_read_b128 v[172:175], v184
	ds_read_b128 v[176:179], v184 offset:1024
	ds_read_b128 v[180:183], v184 offset:2048
	ds_read_b128 v[184:187], v184 offset:3072
	s_add_u32 s34, s34, s8
	s_addc_u32 s35, s35, s9
	s_mov_b32 m0, s43
	v_lshl_add_u64 v[230:231], s[34:35], 0, v[128:129]
	ds_read_b128 v[188:191], v159 offset:32768
	ds_read_b128 v[192:195], v159 offset:33792
	ds_read_b128 v[196:199], v159 offset:34816
	ds_read_b128 v[200:203], v159 offset:35840
	ds_read_b128 v[204:207], v159 offset:36864
	ds_read_b128 v[208:211], v159 offset:37888
	ds_read_b128 v[212:215], v159 offset:38912
	ds_read_b128 v[216:219], v159 offset:39936
	global_load_lds_dwordx4 v[230:231], off
	v_lshl_add_u64 v[230:231], s[34:35], 0, v[132:133]
	s_mov_b32 m0, s44
	s_nop 0
	global_load_lds_dwordx4 v[230:231], off
	s_waitcnt vmcnt(8)
	s_waitcnt lgkmcnt(0)
	s_barrier
	s_waitcnt lgkmcnt(0)
	v_mfma_f32_16x16x32_bf16 v[120:123], v[144:147], v[188:191], v[120:123]
	v_mfma_f32_16x16x32_bf16 v[120:123], v[148:151], v[192:195], v[120:123]
	v_mfma_f32_16x16x32_bf16 v[124:127], v[164:167], v[188:191], v[124:127]
	v_mfma_f32_16x16x32_bf16 v[124:127], v[168:171], v[192:195], v[124:127]
	v_mfma_f32_16x16x32_bf16 v[116:119], v[172:175], v[188:191], v[116:119]
	v_mfma_f32_16x16x32_bf16 v[116:119], v[176:179], v[192:195], v[116:119]
	v_mfma_f32_16x16x32_bf16 v[112:115], v[180:183], v[188:191], v[112:115]
	v_mfma_f32_16x16x32_bf16 v[112:115], v[184:187], v[192:195], v[112:115]
	v_mfma_f32_16x16x32_bf16 v[96:99], v[180:183], v[196:199], v[96:99]
	v_mfma_f32_16x16x32_bf16 v[96:99], v[184:187], v[200:203], v[96:99]
	v_mfma_f32_16x16x32_bf16 v[100:103], v[172:175], v[196:199], v[100:103]
	v_mfma_f32_16x16x32_bf16 v[100:103], v[176:179], v[200:203], v[100:103]
	v_mfma_f32_16x16x32_bf16 v[104:107], v[164:167], v[196:199], v[104:107]
	v_mfma_f32_16x16x32_bf16 v[104:107], v[168:171], v[200:203], v[104:107]
	v_mfma_f32_16x16x32_bf16 v[108:111], v[144:147], v[196:199], v[108:111]
	v_mfma_f32_16x16x32_bf16 v[108:111], v[148:151], v[200:203], v[108:111]
	v_mfma_f32_16x16x32_bf16 v[92:95], v[144:147], v[204:207], v[92:95]
	v_mfma_f32_16x16x32_bf16 v[92:95], v[148:151], v[208:211], v[92:95]
	v_mfma_f32_16x16x32_bf16 v[88:91], v[164:167], v[204:207], v[88:91]
	v_mfma_f32_16x16x32_bf16 v[88:91], v[168:171], v[208:211], v[88:91]
	v_mfma_f32_16x16x32_bf16 v[84:87], v[172:175], v[204:207], v[84:87]
	v_mfma_f32_16x16x32_bf16 v[84:87], v[176:179], v[208:211], v[84:87]
	v_mfma_f32_16x16x32_bf16 v[80:83], v[180:183], v[204:207], v[80:83]
	v_mfma_f32_16x16x32_bf16 v[80:83], v[184:187], v[208:211], v[80:83]
	v_mfma_f32_16x16x32_bf16 v[64:67], v[180:183], v[212:215], v[64:67]
	v_mfma_f32_16x16x32_bf16 v[64:67], v[184:187], v[216:219], v[64:67]
	v_mfma_f32_16x16x32_bf16 v[68:71], v[172:175], v[212:215], v[68:71]
	v_mfma_f32_16x16x32_bf16 v[68:71], v[176:179], v[216:219], v[68:71]
	v_mfma_f32_16x16x32_bf16 v[72:75], v[164:167], v[212:215], v[72:75]
	v_mfma_f32_16x16x32_bf16 v[72:75], v[168:171], v[216:219], v[72:75]
	v_mfma_f32_16x16x32_bf16 v[76:79], v[144:147], v[212:215], v[76:79]
	v_mfma_f32_16x16x32_bf16 v[76:79], v[148:151], v[216:219], v[76:79]
	s_barrier
	s_add_i32 s34, s65, s40
	v_lshl_add_u64 v[152:153], v[152:153], 0, s[14:15]
	s_mov_b32 m0, s34
	ds_read_b128 v[188:191], v159 offset:49152
	ds_read_b128 v[192:195], v159 offset:50176
	ds_read_b128 v[196:199], v159 offset:51200
	ds_read_b128 v[200:203], v159 offset:52224
	ds_read_b128 v[204:207], v159 offset:53248
	ds_read_b128 v[208:211], v159 offset:54272
	ds_read_b128 v[212:215], v159 offset:55296
	ds_read_b128 v[216:219], v159 offset:56320
	global_load_lds_dwordx4 v[152:153], off
	v_lshl_add_u64 v[152:153], v[160:161], 0, s[14:15]
	s_add_i32 m0, s34, 0x2000
	s_add_i32 s34, s66, s40
	global_load_lds_dwordx4 v[152:153], off
	v_lshl_add_u64 v[152:153], v[222:223], 0, s[14:15]
	s_mov_b32 m0, s34
	s_nop 0
	global_load_lds_dwordx4 v[152:153], off
	v_lshl_add_u64 v[152:153], v[224:225], 0, s[14:15]
	s_add_i32 m0, s34, 0x2000
	s_nop 0
	global_load_lds_dwordx4 v[152:153], off
	v_lshl_add_u64 v[152:153], v[226:227], 0, s[14:15]
	s_mov_b32 m0, s46
	s_nop 0
	global_load_lds_dwordx4 v[152:153], off
	v_lshl_add_u64 v[152:153], v[228:229], 0, s[14:15]
	s_mov_b32 m0, s47
	s_nop 0
	global_load_lds_dwordx4 v[152:153], off
	s_waitcnt vmcnt(8)
	s_waitcnt lgkmcnt(0)
	s_barrier
	s_waitcnt lgkmcnt(0)
	v_mfma_f32_16x16x32_bf16 v[60:63], v[144:147], v[188:191], v[60:63]
	v_mfma_f32_16x16x32_bf16 v[60:63], v[148:151], v[192:195], v[60:63]
	v_mfma_f32_16x16x32_bf16 v[56:59], v[164:167], v[188:191], v[56:59]
	v_mfma_f32_16x16x32_bf16 v[56:59], v[168:171], v[192:195], v[56:59]
	v_mfma_f32_16x16x32_bf16 v[52:55], v[172:175], v[188:191], v[52:55]
	v_mfma_f32_16x16x32_bf16 v[52:55], v[176:179], v[192:195], v[52:55]
	v_mfma_f32_16x16x32_bf16 v[48:51], v[180:183], v[188:191], v[48:51]
	v_mfma_f32_16x16x32_bf16 v[48:51], v[184:187], v[192:195], v[48:51]
	v_mfma_f32_16x16x32_bf16 v[32:35], v[180:183], v[196:199], v[32:35]
	v_mfma_f32_16x16x32_bf16 v[32:35], v[184:187], v[200:203], v[32:35]
	v_mfma_f32_16x16x32_bf16 v[36:39], v[172:175], v[196:199], v[36:39]
	v_mfma_f32_16x16x32_bf16 v[36:39], v[176:179], v[200:203], v[36:39]
	v_mfma_f32_16x16x32_bf16 v[40:43], v[164:167], v[196:199], v[40:43]
	v_mfma_f32_16x16x32_bf16 v[40:43], v[168:171], v[200:203], v[40:43]
	v_mfma_f32_16x16x32_bf16 v[44:47], v[144:147], v[196:199], v[44:47]
	v_mfma_f32_16x16x32_bf16 v[44:47], v[148:151], v[200:203], v[44:47]
	v_mfma_f32_16x16x32_bf16 v[28:31], v[144:147], v[204:207], v[28:31]
	v_mfma_f32_16x16x32_bf16 v[28:31], v[148:151], v[208:211], v[28:31]
	v_mfma_f32_16x16x32_bf16 v[24:27], v[164:167], v[204:207], v[24:27]
	v_mfma_f32_16x16x32_bf16 v[24:27], v[168:171], v[208:211], v[24:27]
	v_mfma_f32_16x16x32_bf16 v[20:23], v[172:175], v[204:207], v[20:23]
	v_mfma_f32_16x16x32_bf16 v[20:23], v[176:179], v[208:211], v[20:23]
	v_mfma_f32_16x16x32_bf16 v[16:19], v[180:183], v[204:207], v[16:19]
	v_mfma_f32_16x16x32_bf16 v[16:19], v[184:187], v[208:211], v[16:19]
	v_mfma_f32_16x16x32_bf16 v[0:3], v[180:183], v[212:215], v[0:3]
	v_mfma_f32_16x16x32_bf16 v[0:3], v[184:187], v[216:219], v[0:3]
	v_mfma_f32_16x16x32_bf16 v[4:7], v[172:175], v[212:215], v[4:7]
	v_mfma_f32_16x16x32_bf16 v[4:7], v[176:179], v[216:219], v[4:7]
	v_mfma_f32_16x16x32_bf16 v[8:11], v[164:167], v[212:215], v[8:11]
	v_mfma_f32_16x16x32_bf16 v[8:11], v[168:171], v[216:219], v[8:11]
	v_mfma_f32_16x16x32_bf16 v[12:15], v[144:147], v[212:215], v[12:15]
	v_mfma_f32_16x16x32_bf16 v[12:15], v[148:151], v[216:219], v[12:15]
	s_barrier
	s_add_u32 s30, s30, 0x100
	s_addc_u32 s31, s31, 0
	s_add_u32 s62, s62, 0x100
	s_addc_u32 s63, s63, 0
	s_cmp_ge_i32 s64, s48
	s_mov_b32 s34, s64
	s_cbranch_scc0 .LBB0_592

.LBB0_763:
	ds_read_b128 v[128:131], v181
	ds_read_b128 v[132:135], v181 offset:1024
	ds_read_b128 v[136:139], v181 offset:2048
	ds_read_b128 v[140:143], v181 offset:3072
	ds_read_b128 v[144:147], v182
	ds_read_b128 v[148:151], v182 offset:1024
	ds_read_b128 v[168:171], v182 offset:2048
	ds_read_b128 v[172:175], v182 offset:3072
	s_add_i32 s54, s26, 2
	s_add_u32 s55, s24, 0x80
	s_addc_u32 s27, s25, 0
	s_cmp_eq_u32 s43, s26
	s_cselect_b32 s26, s2, s55
	s_cselect_b32 s27, s3, s27
	s_cselect_b32 s61, s23, s53
	s_cselect_b32 s60, s22, s52
	v_lshl_add_u64 v[176:177], s[24:25], 0, v[160:161]
	s_add_i32 m0, s35, 0xc000
	ds_read_b128 v[184:187], v183
	ds_read_b128 v[188:191], v183 offset:1024
	ds_read_b128 v[192:195], v183 offset:2048
	ds_read_b128 v[196:199], v183 offset:3072
	ds_read_b128 v[200:203], v183 offset:4096
	ds_read_b128 v[204:207], v183 offset:5120
	ds_read_b128 v[208:211], v183 offset:6144
	ds_read_b128 v[212:215], v183 offset:7168
	global_load_lds_dwordx4 v[176:177], off
	v_lshl_add_u64 v[176:177], s[24:25], 0, v[162:163]
	s_add_i32 m0, s35, 0xe000
	s_nop 0
	global_load_lds_dwordx4 v[176:177], off
	s_waitcnt vmcnt(8)
	s_waitcnt lgkmcnt(0)
	s_barrier
	s_waitcnt lgkmcnt(0)
	v_mfma_f32_16x16x32_bf16 v[120:123], v[128:131], v[184:187], v[120:123]
	v_mfma_f32_16x16x32_bf16 v[120:123], v[132:135], v[188:191], v[120:123]
	v_mfma_f32_16x16x32_bf16 v[124:127], v[136:139], v[184:187], v[124:127]
	v_mfma_f32_16x16x32_bf16 v[124:127], v[140:143], v[188:191], v[124:127]
	v_mfma_f32_16x16x32_bf16 v[116:119], v[144:147], v[184:187], v[116:119]
	v_mfma_f32_16x16x32_bf16 v[116:119], v[148:151], v[188:191], v[116:119]
	v_mfma_f32_16x16x32_bf16 v[112:115], v[168:171], v[184:187], v[112:115]
	v_mfma_f32_16x16x32_bf16 v[112:115], v[172:175], v[188:191], v[112:115]
	v_mfma_f32_16x16x32_bf16 v[96:99], v[168:171], v[192:195], v[96:99]
	v_mfma_f32_16x16x32_bf16 v[96:99], v[172:175], v[196:199], v[96:99]
	v_mfma_f32_16x16x32_bf16 v[100:103], v[144:147], v[192:195], v[100:103]
	v_mfma_f32_16x16x32_bf16 v[100:103], v[148:151], v[196:199], v[100:103]
	v_mfma_f32_16x16x32_bf16 v[104:107], v[136:139], v[192:195], v[104:107]
	v_mfma_f32_16x16x32_bf16 v[104:107], v[140:143], v[196:199], v[104:107]
	v_mfma_f32_16x16x32_bf16 v[108:111], v[128:131], v[192:195], v[108:111]
	v_mfma_f32_16x16x32_bf16 v[108:111], v[132:135], v[196:199], v[108:111]
	v_mfma_f32_16x16x32_bf16 v[92:95], v[128:131], v[200:203], v[92:95]
	v_mfma_f32_16x16x32_bf16 v[92:95], v[132:135], v[204:207], v[92:95]
	v_mfma_f32_16x16x32_bf16 v[88:91], v[136:139], v[200:203], v[88:91]
	v_mfma_f32_16x16x32_bf16 v[88:91], v[140:143], v[204:207], v[88:91]
	v_mfma_f32_16x16x32_bf16 v[84:87], v[144:147], v[200:203], v[84:87]
	v_mfma_f32_16x16x32_bf16 v[84:87], v[148:151], v[204:207], v[84:87]
	v_mfma_f32_16x16x32_bf16 v[80:83], v[168:171], v[200:203], v[80:83]
	v_mfma_f32_16x16x32_bf16 v[80:83], v[172:175], v[204:207], v[80:83]
	v_mfma_f32_16x16x32_bf16 v[64:67], v[168:171], v[208:211], v[64:67]
	v_mfma_f32_16x16x32_bf16 v[64:67], v[172:175], v[212:215], v[64:67]
	v_mfma_f32_16x16x32_bf16 v[68:71], v[144:147], v[208:211], v[68:71]
	v_mfma_f32_16x16x32_bf16 v[68:71], v[148:151], v[212:215], v[68:71]
	v_mfma_f32_16x16x32_bf16 v[72:75], v[136:139], v[208:211], v[72:75]
	v_mfma_f32_16x16x32_bf16 v[72:75], v[140:143], v[212:215], v[72:75]
	v_mfma_f32_16x16x32_bf16 v[76:79], v[128:131], v[208:211], v[76:79]
	v_mfma_f32_16x16x32_bf16 v[76:79], v[132:135], v[212:215], v[76:79]
	s_barrier
	s_add_i32 s55, s46, s34
	v_lshl_add_u64 v[176:177], s[60:61], 0, v[154:155]
	s_mov_b32 m0, s55
	ds_read_b128 v[184:187], v183 offset:16384
	ds_read_b128 v[188:191], v183 offset:17408
	ds_read_b128 v[192:195], v183 offset:18432
	ds_read_b128 v[196:199], v183 offset:19456
	ds_read_b128 v[200:203], v183 offset:20480
	ds_read_b128 v[204:207], v183 offset:21504
	ds_read_b128 v[208:211], v183 offset:22528
	ds_read_b128 v[212:215], v183 offset:23552
	global_load_lds_dwordx4 v[176:177], off
	s_add_i32 m0, s55, 0x2000
	v_lshl_add_u64 v[216:217], s[60:61], 0, v[158:159]
	s_add_u32 s60, s60, s8
	s_addc_u32 s61, s61, s9
	s_add_i32 s55, s47, s34
	global_load_lds_dwordx4 v[216:217], off
	v_lshl_add_u64 v[218:219], s[60:61], 0, v[154:155]
	s_mov_b32 m0, s55
	v_lshl_add_u64 v[222:223], s[60:61], 0, v[158:159]
	global_load_lds_dwordx4 v[218:219], off
	s_add_i32 m0, s55, 0x2000
	v_lshl_add_u64 v[224:225], s[26:27], 0, v[152:153]
	global_load_lds_dwordx4 v[222:223], off
	s_mov_b32 m0, s35
	v_lshl_add_u64 v[226:227], s[26:27], 0, v[156:157]
	global_load_lds_dwordx4 v[224:225], off
	s_mov_b32 m0, s36
	s_nop 0
	global_load_lds_dwordx4 v[226:227], off
	s_waitcnt vmcnt(8)
	s_waitcnt lgkmcnt(0)
	s_barrier
	s_waitcnt lgkmcnt(0)
	v_mfma_f32_16x16x32_bf16 v[60:63], v[128:131], v[184:187], v[60:63]
	v_mfma_f32_16x16x32_bf16 v[60:63], v[132:135], v[188:191], v[60:63]
	v_mfma_f32_16x16x32_bf16 v[56:59], v[136:139], v[184:187], v[56:59]
	v_mfma_f32_16x16x32_bf16 v[56:59], v[140:143], v[188:191], v[56:59]
	v_mfma_f32_16x16x32_bf16 v[52:55], v[144:147], v[184:187], v[52:55]
	v_mfma_f32_16x16x32_bf16 v[52:55], v[148:151], v[188:191], v[52:55]
	v_mfma_f32_16x16x32_bf16 v[48:51], v[168:171], v[184:187], v[48:51]
	v_mfma_f32_16x16x32_bf16 v[48:51], v[172:175], v[188:191], v[48:51]
	v_mfma_f32_16x16x32_bf16 v[32:35], v[168:171], v[192:195], v[32:35]
	v_mfma_f32_16x16x32_bf16 v[32:35], v[172:175], v[196:199], v[32:35]
	v_mfma_f32_16x16x32_bf16 v[36:39], v[144:147], v[192:195], v[36:39]
	v_mfma_f32_16x16x32_bf16 v[36:39], v[148:151], v[196:199], v[36:39]
	v_mfma_f32_16x16x32_bf16 v[40:43], v[136:139], v[192:195], v[40:43]
	v_mfma_f32_16x16x32_bf16 v[40:43], v[140:143], v[196:199], v[40:43]
	v_mfma_f32_16x16x32_bf16 v[44:47], v[128:131], v[192:195], v[44:47]
	v_mfma_f32_16x16x32_bf16 v[44:47], v[132:135], v[196:199], v[44:47]
	v_mfma_f32_16x16x32_bf16 v[28:31], v[128:131], v[200:203], v[28:31]
	v_mfma_f32_16x16x32_bf16 v[28:31], v[132:135], v[204:207], v[28:31]
	v_mfma_f32_16x16x32_bf16 v[24:27], v[136:139], v[200:203], v[24:27]
	v_mfma_f32_16x16x32_bf16 v[24:27], v[140:143], v[204:207], v[24:27]
	v_mfma_f32_16x16x32_bf16 v[20:23], v[144:147], v[200:203], v[20:23]
	v_mfma_f32_16x16x32_bf16 v[20:23], v[148:151], v[204:207], v[20:23]
	v_mfma_f32_16x16x32_bf16 v[16:19], v[168:171], v[200:203], v[16:19]
	v_mfma_f32_16x16x32_bf16 v[16:19], v[172:175], v[204:207], v[16:19]
	v_mfma_f32_16x16x32_bf16 v[0:3], v[168:171], v[208:211], v[0:3]
	v_mfma_f32_16x16x32_bf16 v[0:3], v[172:175], v[212:215], v[0:3]
	v_mfma_f32_16x16x32_bf16 v[4:7], v[144:147], v[208:211], v[4:7]
	v_mfma_f32_16x16x32_bf16 v[4:7], v[148:151], v[212:215], v[4:7]
	v_mfma_f32_16x16x32_bf16 v[8:11], v[136:139], v[208:211], v[8:11]
	v_mfma_f32_16x16x32_bf16 v[8:11], v[140:143], v[212:215], v[8:11]
	v_mfma_f32_16x16x32_bf16 v[12:15], v[128:131], v[208:211], v[12:15]
	v_mfma_f32_16x16x32_bf16 v[12:15], v[132:135], v[212:215], v[12:15]
	s_barrier
	s_add_i32 s55, 0, 0x18000
	s_add_i32 s60, 0, 0x1c000
	v_add_u32_e32 v140, s55, v179
	v_add_u32_e32 v172, s60, v179
	ds_read_b128 v[128:131], v140
	ds_read_b128 v[132:135], v140 offset:1024
	ds_read_b128 v[136:139], v140 offset:2048
	ds_read_b128 v[140:143], v140 offset:3072
	ds_read_b128 v[144:147], v172
	ds_read_b128 v[148:151], v172 offset:1024
	ds_read_b128 v[168:171], v172 offset:2048
	ds_read_b128 v[172:175], v172 offset:3072
	s_add_u32 s26, s26, s8
	s_addc_u32 s27, s27, s9
	s_mov_b32 m0, s37
	v_lshl_add_u64 v[228:229], s[26:27], 0, v[152:153]
	ds_read_b128 v[184:187], v183 offset:32768
	ds_read_b128 v[188:191], v183 offset:33792
	ds_read_b128 v[192:195], v183 offset:34816
	ds_read_b128 v[196:199], v183 offset:35840
	ds_read_b128 v[200:203], v183 offset:36864
	ds_read_b128 v[204:207], v183 offset:37888
	ds_read_b128 v[208:211], v183 offset:38912
	ds_read_b128 v[212:215], v183 offset:39936
	global_load_lds_dwordx4 v[228:229], off
	v_lshl_add_u64 v[228:229], s[26:27], 0, v[156:157]
	s_mov_b32 m0, s38
	s_nop 0
	global_load_lds_dwordx4 v[228:229], off
	s_waitcnt vmcnt(8)
	s_waitcnt lgkmcnt(0)
	s_barrier
	s_waitcnt lgkmcnt(0)
	v_mfma_f32_16x16x32_bf16 v[120:123], v[128:131], v[184:187], v[120:123]
	v_mfma_f32_16x16x32_bf16 v[120:123], v[132:135], v[188:191], v[120:123]
	v_mfma_f32_16x16x32_bf16 v[124:127], v[136:139], v[184:187], v[124:127]
	v_mfma_f32_16x16x32_bf16 v[124:127], v[140:143], v[188:191], v[124:127]
	v_mfma_f32_16x16x32_bf16 v[116:119], v[144:147], v[184:187], v[116:119]
	v_mfma_f32_16x16x32_bf16 v[116:119], v[148:151], v[188:191], v[116:119]
	v_mfma_f32_16x16x32_bf16 v[112:115], v[168:171], v[184:187], v[112:115]
	v_mfma_f32_16x16x32_bf16 v[112:115], v[172:175], v[188:191], v[112:115]
	v_mfma_f32_16x16x32_bf16 v[96:99], v[168:171], v[192:195], v[96:99]
	v_mfma_f32_16x16x32_bf16 v[96:99], v[172:175], v[196:199], v[96:99]
	v_mfma_f32_16x16x32_bf16 v[100:103], v[144:147], v[192:195], v[100:103]
	v_mfma_f32_16x16x32_bf16 v[100:103], v[148:151], v[196:199], v[100:103]
	v_mfma_f32_16x16x32_bf16 v[104:107], v[136:139], v[192:195], v[104:107]
	v_mfma_f32_16x16x32_bf16 v[104:107], v[140:143], v[196:199], v[104:107]
	v_mfma_f32_16x16x32_bf16 v[108:111], v[128:131], v[192:195], v[108:111]
	v_mfma_f32_16x16x32_bf16 v[108:111], v[132:135], v[196:199], v[108:111]
	v_mfma_f32_16x16x32_bf16 v[92:95], v[128:131], v[200:203], v[92:95]
	v_mfma_f32_16x16x32_bf16 v[92:95], v[132:135], v[204:207], v[92:95]
	v_mfma_f32_16x16x32_bf16 v[88:91], v[136:139], v[200:203], v[88:91]
	v_mfma_f32_16x16x32_bf16 v[88:91], v[140:143], v[204:207], v[88:91]
	v_mfma_f32_16x16x32_bf16 v[84:87], v[144:147], v[200:203], v[84:87]
	v_mfma_f32_16x16x32_bf16 v[84:87], v[148:151], v[204:207], v[84:87]
	v_mfma_f32_16x16x32_bf16 v[80:83], v[168:171], v[200:203], v[80:83]
	v_mfma_f32_16x16x32_bf16 v[80:83], v[172:175], v[204:207], v[80:83]
	v_mfma_f32_16x16x32_bf16 v[64:67], v[168:171], v[208:211], v[64:67]
	v_mfma_f32_16x16x32_bf16 v[64:67], v[172:175], v[212:215], v[64:67]
	v_mfma_f32_16x16x32_bf16 v[68:71], v[144:147], v[208:211], v[68:71]
	v_mfma_f32_16x16x32_bf16 v[68:71], v[148:151], v[212:215], v[68:71]
	v_mfma_f32_16x16x32_bf16 v[72:75], v[136:139], v[208:211], v[72:75]
	v_mfma_f32_16x16x32_bf16 v[72:75], v[140:143], v[212:215], v[72:75]
	v_mfma_f32_16x16x32_bf16 v[76:79], v[128:131], v[208:211], v[76:79]
	v_mfma_f32_16x16x32_bf16 v[76:79], v[132:135], v[212:215], v[76:79]
	s_barrier
	s_add_i32 s26, s55, s34
	v_lshl_add_u64 v[176:177], v[176:177], 0, s[16:17]
	s_mov_b32 m0, s26
	ds_read_b128 v[184:187], v183 offset:49152
	ds_read_b128 v[188:191], v183 offset:50176
	ds_read_b128 v[192:195], v183 offset:51200
	ds_read_b128 v[196:199], v183 offset:52224
	ds_read_b128 v[200:203], v183 offset:53248
	ds_read_b128 v[204:207], v183 offset:54272
	ds_read_b128 v[208:211], v183 offset:55296
	ds_read_b128 v[212:215], v183 offset:56320
	global_load_lds_dwordx4 v[176:177], off
	v_lshl_add_u64 v[176:177], v[216:217], 0, s[16:17]
	s_add_i32 m0, s26, 0x2000
	s_add_i32 s26, s60, s34
	global_load_lds_dwordx4 v[176:177], off
	v_lshl_add_u64 v[176:177], v[218:219], 0, s[16:17]
	s_mov_b32 m0, s26
	s_nop 0
	global_load_lds_dwordx4 v[176:177], off
	v_lshl_add_u64 v[176:177], v[222:223], 0, s[16:17]
	s_add_i32 m0, s26, 0x2000
	s_nop 0
	global_load_lds_dwordx4 v[176:177], off
	v_lshl_add_u64 v[176:177], v[224:225], 0, s[16:17]
	s_mov_b32 m0, s40
	s_nop 0
	global_load_lds_dwordx4 v[176:177], off
	v_lshl_add_u64 v[176:177], v[226:227], 0, s[16:17]
	s_mov_b32 m0, s41
	s_nop 0
	global_load_lds_dwordx4 v[176:177], off
	s_waitcnt vmcnt(8)
	s_waitcnt lgkmcnt(0)
	s_barrier
	s_waitcnt lgkmcnt(0)
	v_mfma_f32_16x16x32_bf16 v[60:63], v[128:131], v[184:187], v[60:63]
	v_mfma_f32_16x16x32_bf16 v[60:63], v[132:135], v[188:191], v[60:63]
	v_mfma_f32_16x16x32_bf16 v[56:59], v[136:139], v[184:187], v[56:59]
	v_mfma_f32_16x16x32_bf16 v[56:59], v[140:143], v[188:191], v[56:59]
	v_mfma_f32_16x16x32_bf16 v[52:55], v[144:147], v[184:187], v[52:55]
	v_mfma_f32_16x16x32_bf16 v[52:55], v[148:151], v[188:191], v[52:55]
	v_mfma_f32_16x16x32_bf16 v[48:51], v[168:171], v[184:187], v[48:51]
	v_mfma_f32_16x16x32_bf16 v[48:51], v[172:175], v[188:191], v[48:51]
	v_mfma_f32_16x16x32_bf16 v[32:35], v[168:171], v[192:195], v[32:35]
	v_mfma_f32_16x16x32_bf16 v[32:35], v[172:175], v[196:199], v[32:35]
	v_mfma_f32_16x16x32_bf16 v[36:39], v[144:147], v[192:195], v[36:39]
	v_mfma_f32_16x16x32_bf16 v[36:39], v[148:151], v[196:199], v[36:39]
	v_mfma_f32_16x16x32_bf16 v[40:43], v[136:139], v[192:195], v[40:43]
	v_mfma_f32_16x16x32_bf16 v[40:43], v[140:143], v[196:199], v[40:43]
	v_mfma_f32_16x16x32_bf16 v[44:47], v[128:131], v[192:195], v[44:47]
	v_mfma_f32_16x16x32_bf16 v[44:47], v[132:135], v[196:199], v[44:47]
	v_mfma_f32_16x16x32_bf16 v[28:31], v[128:131], v[200:203], v[28:31]
	v_mfma_f32_16x16x32_bf16 v[28:31], v[132:135], v[204:207], v[28:31]
	v_mfma_f32_16x16x32_bf16 v[24:27], v[136:139], v[200:203], v[24:27]
	v_mfma_f32_16x16x32_bf16 v[24:27], v[140:143], v[204:207], v[24:27]
	v_mfma_f32_16x16x32_bf16 v[20:23], v[144:147], v[200:203], v[20:23]
	v_mfma_f32_16x16x32_bf16 v[20:23], v[148:151], v[204:207], v[20:23]
	v_mfma_f32_16x16x32_bf16 v[16:19], v[168:171], v[200:203], v[16:19]
	v_mfma_f32_16x16x32_bf16 v[16:19], v[172:175], v[204:207], v[16:19]
	v_mfma_f32_16x16x32_bf16 v[0:3], v[168:171], v[208:211], v[0:3]
	v_mfma_f32_16x16x32_bf16 v[0:3], v[172:175], v[212:215], v[0:3]
	v_mfma_f32_16x16x32_bf16 v[4:7], v[144:147], v[208:211], v[4:7]
	v_mfma_f32_16x16x32_bf16 v[4:7], v[148:151], v[212:215], v[4:7]
	v_mfma_f32_16x16x32_bf16 v[8:11], v[136:139], v[208:211], v[8:11]
	v_mfma_f32_16x16x32_bf16 v[8:11], v[140:143], v[212:215], v[8:11]
	v_mfma_f32_16x16x32_bf16 v[12:15], v[128:131], v[208:211], v[12:15]
	v_mfma_f32_16x16x32_bf16 v[12:15], v[132:135], v[212:215], v[12:15]
	s_barrier
	s_add_u32 s24, s24, 0x100
	s_addc_u32 s25, s25, 0
	s_add_u32 s52, s52, 0x100
	s_addc_u32 s53, s53, 0
	s_cmp_ge_i32 s54, s42
	s_mov_b32 s26, s54
	s_cbranch_scc0 .LBB0_763

.LBB0_849:
	ds_read_b128 v[112:115], v209
	ds_read_b128 v[116:119], v209 offset:1024
	ds_read_b128 v[120:123], v209 offset:2048
	ds_read_b128 v[128:131], v209 offset:3072
	ds_read_b128 v[144:147], v210
	ds_read_b128 v[148:151], v210 offset:1024
	ds_read_b128 v[152:155], v210 offset:2048
	ds_read_b128 v[156:159], v210 offset:3072
	s_add_i32 s62, s30, 2
	s_add_u32 s63, s28, 0x80
	s_addc_u32 s31, s29, 0
	s_cmp_eq_u32 s46, s30
	s_cselect_b32 s30, s4, s63
	s_cselect_b32 s31, s5, s31
	s_cselect_b32 s65, s27, s61
	s_cselect_b32 s64, s26, s60
	v_lshl_add_u64 v[204:205], s[28:29], 0, v[180:181]
	s_add_i32 m0, s38, 0xc000
	ds_read_b128 v[160:163], v211
	ds_read_b128 v[164:167], v211 offset:1024
	ds_read_b128 v[168:171], v211 offset:2048
	ds_read_b128 v[172:175], v211 offset:3072
	ds_read_b128 v[188:191], v211 offset:4096
	ds_read_b128 v[192:195], v211 offset:5120
	ds_read_b128 v[196:199], v211 offset:6144
	ds_read_b128 v[200:203], v211 offset:7168
	global_load_lds_dwordx4 v[204:205], off
	v_lshl_add_u64 v[204:205], s[28:29], 0, v[182:183]
	s_add_i32 m0, s38, 0xe000
	s_nop 0
	global_load_lds_dwordx4 v[204:205], off
	s_waitcnt vmcnt(8)
	s_waitcnt lgkmcnt(0)
	s_barrier
	s_waitcnt lgkmcnt(0)
	v_mfma_f32_16x16x32_bf16 v[136:139], v[112:115], v[160:163], v[136:139]
	v_mfma_f32_16x16x32_bf16 v[136:139], v[116:119], v[164:167], v[136:139]
	v_mfma_f32_16x16x32_bf16 v[140:143], v[120:123], v[160:163], v[140:143]
	v_mfma_f32_16x16x32_bf16 v[140:143], v[128:131], v[164:167], v[140:143]
	v_mfma_f32_16x16x32_bf16 v[132:135], v[144:147], v[160:163], v[132:135]
	v_mfma_f32_16x16x32_bf16 v[132:135], v[148:151], v[164:167], v[132:135]
	v_mfma_f32_16x16x32_bf16 v[124:127], v[152:155], v[160:163], v[124:127]
	v_mfma_f32_16x16x32_bf16 v[124:127], v[156:159], v[164:167], v[124:127]
	v_mfma_f32_16x16x32_bf16 v[96:99], v[152:155], v[168:171], v[96:99]
	v_mfma_f32_16x16x32_bf16 v[96:99], v[156:159], v[172:175], v[96:99]
	v_mfma_f32_16x16x32_bf16 v[100:103], v[144:147], v[168:171], v[100:103]
	v_mfma_f32_16x16x32_bf16 v[100:103], v[148:151], v[172:175], v[100:103]
	v_mfma_f32_16x16x32_bf16 v[104:107], v[120:123], v[168:171], v[104:107]
	v_mfma_f32_16x16x32_bf16 v[104:107], v[128:131], v[172:175], v[104:107]
	v_mfma_f32_16x16x32_bf16 v[108:111], v[112:115], v[168:171], v[108:111]
	v_mfma_f32_16x16x32_bf16 v[108:111], v[116:119], v[172:175], v[108:111]
	v_mfma_f32_16x16x32_bf16 v[92:95], v[112:115], v[188:191], v[92:95]
	v_mfma_f32_16x16x32_bf16 v[92:95], v[116:119], v[192:195], v[92:95]
	v_mfma_f32_16x16x32_bf16 v[88:91], v[120:123], v[188:191], v[88:91]
	v_mfma_f32_16x16x32_bf16 v[88:91], v[128:131], v[192:195], v[88:91]
	v_mfma_f32_16x16x32_bf16 v[84:87], v[144:147], v[188:191], v[84:87]
	v_mfma_f32_16x16x32_bf16 v[84:87], v[148:151], v[192:195], v[84:87]
	v_mfma_f32_16x16x32_bf16 v[80:83], v[152:155], v[188:191], v[80:83]
	v_mfma_f32_16x16x32_bf16 v[80:83], v[156:159], v[192:195], v[80:83]
	v_mfma_f32_16x16x32_bf16 v[64:67], v[152:155], v[196:199], v[64:67]
	v_mfma_f32_16x16x32_bf16 v[64:67], v[156:159], v[200:203], v[64:67]
	v_mfma_f32_16x16x32_bf16 v[68:71], v[144:147], v[196:199], v[68:71]
	v_mfma_f32_16x16x32_bf16 v[68:71], v[148:151], v[200:203], v[68:71]
	v_mfma_f32_16x16x32_bf16 v[72:75], v[120:123], v[196:199], v[72:75]
	v_mfma_f32_16x16x32_bf16 v[72:75], v[128:131], v[200:203], v[72:75]
	v_mfma_f32_16x16x32_bf16 v[76:79], v[112:115], v[196:199], v[76:79]
	v_mfma_f32_16x16x32_bf16 v[76:79], v[116:119], v[200:203], v[76:79]
	s_barrier
	s_add_i32 s63, s50, s37
	v_lshl_add_u64 v[204:205], s[64:65], 0, v[176:177]
	s_mov_b32 m0, s63
	ds_read_b128 v[160:163], v211 offset:16384
	ds_read_b128 v[164:167], v211 offset:17408
	ds_read_b128 v[168:171], v211 offset:18432
	ds_read_b128 v[172:175], v211 offset:19456
	ds_read_b128 v[188:191], v211 offset:20480
	ds_read_b128 v[192:195], v211 offset:21504
	ds_read_b128 v[196:199], v211 offset:22528
	ds_read_b128 v[200:203], v211 offset:23552
	global_load_lds_dwordx4 v[204:205], off
	s_add_i32 m0, s63, 0x2000
	v_lshl_add_u64 v[214:215], s[64:65], 0, v[178:179]
	s_add_u32 s64, s64, s10
	s_addc_u32 s65, s65, s11
	s_add_i32 s63, s51, s37
	global_load_lds_dwordx4 v[214:215], off
	v_lshl_add_u64 v[216:217], s[64:65], 0, v[176:177]
	s_mov_b32 m0, s63
	v_lshl_add_u64 v[218:219], s[64:65], 0, v[178:179]
	global_load_lds_dwordx4 v[216:217], off
	s_add_i32 m0, s63, 0x2000
	v_lshl_add_u64 v[222:223], s[30:31], 0, v[176:177]
	global_load_lds_dwordx4 v[218:219], off
	s_mov_b32 m0, s38
	v_lshl_add_u64 v[224:225], s[30:31], 0, v[178:179]
	global_load_lds_dwordx4 v[222:223], off
	s_mov_b32 m0, s39
	s_nop 0
	global_load_lds_dwordx4 v[224:225], off
	s_waitcnt vmcnt(8)
	s_waitcnt lgkmcnt(0)
	s_barrier
	s_waitcnt lgkmcnt(0)
	v_mfma_f32_16x16x32_bf16 v[60:63], v[112:115], v[160:163], v[60:63]
	v_mfma_f32_16x16x32_bf16 v[60:63], v[116:119], v[164:167], v[60:63]
	v_mfma_f32_16x16x32_bf16 v[56:59], v[120:123], v[160:163], v[56:59]
	v_mfma_f32_16x16x32_bf16 v[56:59], v[128:131], v[164:167], v[56:59]
	v_mfma_f32_16x16x32_bf16 v[52:55], v[144:147], v[160:163], v[52:55]
	v_mfma_f32_16x16x32_bf16 v[52:55], v[148:151], v[164:167], v[52:55]
	v_mfma_f32_16x16x32_bf16 v[48:51], v[152:155], v[160:163], v[48:51]
	v_mfma_f32_16x16x32_bf16 v[48:51], v[156:159], v[164:167], v[48:51]
	v_mfma_f32_16x16x32_bf16 v[32:35], v[152:155], v[168:171], v[32:35]
	v_mfma_f32_16x16x32_bf16 v[32:35], v[156:159], v[172:175], v[32:35]
	v_mfma_f32_16x16x32_bf16 v[36:39], v[144:147], v[168:171], v[36:39]
	v_mfma_f32_16x16x32_bf16 v[36:39], v[148:151], v[172:175], v[36:39]
	v_mfma_f32_16x16x32_bf16 v[40:43], v[120:123], v[168:171], v[40:43]
	v_mfma_f32_16x16x32_bf16 v[40:43], v[128:131], v[172:175], v[40:43]
	v_mfma_f32_16x16x32_bf16 v[44:47], v[112:115], v[168:171], v[44:47]
	v_mfma_f32_16x16x32_bf16 v[44:47], v[116:119], v[172:175], v[44:47]
	v_mfma_f32_16x16x32_bf16 v[28:31], v[112:115], v[188:191], v[28:31]
	v_mfma_f32_16x16x32_bf16 v[28:31], v[116:119], v[192:195], v[28:31]
	v_mfma_f32_16x16x32_bf16 v[24:27], v[120:123], v[188:191], v[24:27]
	v_mfma_f32_16x16x32_bf16 v[24:27], v[128:131], v[192:195], v[24:27]
	v_mfma_f32_16x16x32_bf16 v[20:23], v[144:147], v[188:191], v[20:23]
	v_mfma_f32_16x16x32_bf16 v[20:23], v[148:151], v[192:195], v[20:23]
	v_mfma_f32_16x16x32_bf16 v[16:19], v[152:155], v[188:191], v[16:19]
	v_mfma_f32_16x16x32_bf16 v[16:19], v[156:159], v[192:195], v[16:19]
	v_mfma_f32_16x16x32_bf16 v[0:3], v[152:155], v[196:199], v[0:3]
	v_mfma_f32_16x16x32_bf16 v[0:3], v[156:159], v[200:203], v[0:3]
	v_mfma_f32_16x16x32_bf16 v[4:7], v[144:147], v[196:199], v[4:7]
	v_mfma_f32_16x16x32_bf16 v[4:7], v[148:151], v[200:203], v[4:7]
	v_mfma_f32_16x16x32_bf16 v[8:11], v[120:123], v[196:199], v[8:11]
	v_mfma_f32_16x16x32_bf16 v[8:11], v[128:131], v[200:203], v[8:11]
	v_mfma_f32_16x16x32_bf16 v[12:15], v[112:115], v[196:199], v[12:15]
	v_mfma_f32_16x16x32_bf16 v[12:15], v[116:119], v[200:203], v[12:15]
	s_barrier
	s_add_i32 s63, 0, 0x18000
	s_add_i32 s64, 0, 0x1c000
	v_add_u32_e32 v128, s63, v207
	v_add_u32_e32 v156, s64, v207
	ds_read_b128 v[112:115], v128
	ds_read_b128 v[116:119], v128 offset:1024
	ds_read_b128 v[120:123], v128 offset:2048
	ds_read_b128 v[128:131], v128 offset:3072
	ds_read_b128 v[144:147], v156
	ds_read_b128 v[148:151], v156 offset:1024
	ds_read_b128 v[152:155], v156 offset:2048
	ds_read_b128 v[156:159], v156 offset:3072
	s_add_u32 s30, s30, s10
	s_addc_u32 s31, s31, s11
	s_mov_b32 m0, s40
	v_lshl_add_u64 v[226:227], s[30:31], 0, v[176:177]
	ds_read_b128 v[160:163], v211 offset:32768
	ds_read_b128 v[164:167], v211 offset:33792
	ds_read_b128 v[168:171], v211 offset:34816
	ds_read_b128 v[172:175], v211 offset:35840
	ds_read_b128 v[188:191], v211 offset:36864
	ds_read_b128 v[192:195], v211 offset:37888
	ds_read_b128 v[196:199], v211 offset:38912
	ds_read_b128 v[200:203], v211 offset:39936
	global_load_lds_dwordx4 v[226:227], off
	v_lshl_add_u64 v[226:227], s[30:31], 0, v[178:179]
	s_mov_b32 m0, s41
	s_nop 0
	global_load_lds_dwordx4 v[226:227], off
	s_waitcnt vmcnt(8)
	s_waitcnt lgkmcnt(0)
	s_barrier
	s_waitcnt lgkmcnt(0)
	v_mfma_f32_16x16x32_bf16 v[136:139], v[112:115], v[160:163], v[136:139]
	v_mfma_f32_16x16x32_bf16 v[136:139], v[116:119], v[164:167], v[136:139]
	v_mfma_f32_16x16x32_bf16 v[140:143], v[120:123], v[160:163], v[140:143]
	v_mfma_f32_16x16x32_bf16 v[140:143], v[128:131], v[164:167], v[140:143]
	v_mfma_f32_16x16x32_bf16 v[132:135], v[144:147], v[160:163], v[132:135]
	v_mfma_f32_16x16x32_bf16 v[132:135], v[148:151], v[164:167], v[132:135]
	v_mfma_f32_16x16x32_bf16 v[124:127], v[152:155], v[160:163], v[124:127]
	v_mfma_f32_16x16x32_bf16 v[124:127], v[156:159], v[164:167], v[124:127]
	v_mfma_f32_16x16x32_bf16 v[96:99], v[152:155], v[168:171], v[96:99]
	v_mfma_f32_16x16x32_bf16 v[96:99], v[156:159], v[172:175], v[96:99]
	v_mfma_f32_16x16x32_bf16 v[100:103], v[144:147], v[168:171], v[100:103]
	v_mfma_f32_16x16x32_bf16 v[100:103], v[148:151], v[172:175], v[100:103]
	v_mfma_f32_16x16x32_bf16 v[104:107], v[120:123], v[168:171], v[104:107]
	v_mfma_f32_16x16x32_bf16 v[104:107], v[128:131], v[172:175], v[104:107]
	v_mfma_f32_16x16x32_bf16 v[108:111], v[112:115], v[168:171], v[108:111]
	v_mfma_f32_16x16x32_bf16 v[108:111], v[116:119], v[172:175], v[108:111]
	v_mfma_f32_16x16x32_bf16 v[92:95], v[112:115], v[188:191], v[92:95]
	v_mfma_f32_16x16x32_bf16 v[92:95], v[116:119], v[192:195], v[92:95]
	v_mfma_f32_16x16x32_bf16 v[88:91], v[120:123], v[188:191], v[88:91]
	v_mfma_f32_16x16x32_bf16 v[88:91], v[128:131], v[192:195], v[88:91]
	v_mfma_f32_16x16x32_bf16 v[84:87], v[144:147], v[188:191], v[84:87]
	v_mfma_f32_16x16x32_bf16 v[84:87], v[148:151], v[192:195], v[84:87]
	v_mfma_f32_16x16x32_bf16 v[80:83], v[152:155], v[188:191], v[80:83]
	v_mfma_f32_16x16x32_bf16 v[80:83], v[156:159], v[192:195], v[80:83]
	v_mfma_f32_16x16x32_bf16 v[64:67], v[152:155], v[196:199], v[64:67]
	v_mfma_f32_16x16x32_bf16 v[64:67], v[156:159], v[200:203], v[64:67]
	v_mfma_f32_16x16x32_bf16 v[68:71], v[144:147], v[196:199], v[68:71]
	v_mfma_f32_16x16x32_bf16 v[68:71], v[148:151], v[200:203], v[68:71]
	v_mfma_f32_16x16x32_bf16 v[72:75], v[120:123], v[196:199], v[72:75]
	v_mfma_f32_16x16x32_bf16 v[72:75], v[128:131], v[200:203], v[72:75]
	v_mfma_f32_16x16x32_bf16 v[76:79], v[112:115], v[196:199], v[76:79]
	v_mfma_f32_16x16x32_bf16 v[76:79], v[116:119], v[200:203], v[76:79]
	s_barrier
	s_add_i32 s30, s63, s37
	v_lshl_add_u64 v[204:205], v[204:205], 0, s[18:19]
	s_mov_b32 m0, s30
	ds_read_b128 v[160:163], v211 offset:49152
	ds_read_b128 v[164:167], v211 offset:50176
	ds_read_b128 v[168:171], v211 offset:51200
	ds_read_b128 v[172:175], v211 offset:52224
	ds_read_b128 v[188:191], v211 offset:53248
	ds_read_b128 v[192:195], v211 offset:54272
	ds_read_b128 v[196:199], v211 offset:55296
	ds_read_b128 v[200:203], v211 offset:56320
	global_load_lds_dwordx4 v[204:205], off
	v_lshl_add_u64 v[204:205], v[214:215], 0, s[18:19]
	s_add_i32 m0, s30, 0x2000
	s_add_i32 s30, s64, s37
	global_load_lds_dwordx4 v[204:205], off
	v_lshl_add_u64 v[204:205], v[216:217], 0, s[18:19]
	s_mov_b32 m0, s30
	s_nop 0
	global_load_lds_dwordx4 v[204:205], off
	v_lshl_add_u64 v[204:205], v[218:219], 0, s[18:19]
	s_add_i32 m0, s30, 0x2000
	s_nop 0
	global_load_lds_dwordx4 v[204:205], off
	v_lshl_add_u64 v[204:205], v[222:223], 0, s[18:19]
	s_mov_b32 m0, s43
	s_nop 0
	global_load_lds_dwordx4 v[204:205], off
	v_lshl_add_u64 v[204:205], v[224:225], 0, s[18:19]
	s_mov_b32 m0, s44
	s_nop 0
	global_load_lds_dwordx4 v[204:205], off
	s_waitcnt vmcnt(8)
	s_waitcnt lgkmcnt(0)
	s_barrier
	s_waitcnt lgkmcnt(0)
	v_mfma_f32_16x16x32_bf16 v[60:63], v[112:115], v[160:163], v[60:63]
	v_mfma_f32_16x16x32_bf16 v[60:63], v[116:119], v[164:167], v[60:63]
	v_mfma_f32_16x16x32_bf16 v[56:59], v[120:123], v[160:163], v[56:59]
	v_mfma_f32_16x16x32_bf16 v[56:59], v[128:131], v[164:167], v[56:59]
	v_mfma_f32_16x16x32_bf16 v[52:55], v[144:147], v[160:163], v[52:55]
	v_mfma_f32_16x16x32_bf16 v[52:55], v[148:151], v[164:167], v[52:55]
	v_mfma_f32_16x16x32_bf16 v[48:51], v[152:155], v[160:163], v[48:51]
	v_mfma_f32_16x16x32_bf16 v[48:51], v[156:159], v[164:167], v[48:51]
	v_mfma_f32_16x16x32_bf16 v[32:35], v[152:155], v[168:171], v[32:35]
	v_mfma_f32_16x16x32_bf16 v[32:35], v[156:159], v[172:175], v[32:35]
	v_mfma_f32_16x16x32_bf16 v[36:39], v[144:147], v[168:171], v[36:39]
	v_mfma_f32_16x16x32_bf16 v[36:39], v[148:151], v[172:175], v[36:39]
	v_mfma_f32_16x16x32_bf16 v[40:43], v[120:123], v[168:171], v[40:43]
	v_mfma_f32_16x16x32_bf16 v[40:43], v[128:131], v[172:175], v[40:43]
	v_mfma_f32_16x16x32_bf16 v[44:47], v[112:115], v[168:171], v[44:47]
	v_mfma_f32_16x16x32_bf16 v[44:47], v[116:119], v[172:175], v[44:47]
	v_mfma_f32_16x16x32_bf16 v[28:31], v[112:115], v[188:191], v[28:31]
	v_mfma_f32_16x16x32_bf16 v[28:31], v[116:119], v[192:195], v[28:31]
	v_mfma_f32_16x16x32_bf16 v[24:27], v[120:123], v[188:191], v[24:27]
	v_mfma_f32_16x16x32_bf16 v[24:27], v[128:131], v[192:195], v[24:27]
	v_mfma_f32_16x16x32_bf16 v[20:23], v[144:147], v[188:191], v[20:23]
	v_mfma_f32_16x16x32_bf16 v[20:23], v[148:151], v[192:195], v[20:23]
	v_mfma_f32_16x16x32_bf16 v[16:19], v[152:155], v[188:191], v[16:19]
	v_mfma_f32_16x16x32_bf16 v[16:19], v[156:159], v[192:195], v[16:19]
	v_mfma_f32_16x16x32_bf16 v[0:3], v[152:155], v[196:199], v[0:3]
	v_mfma_f32_16x16x32_bf16 v[0:3], v[156:159], v[200:203], v[0:3]
	v_mfma_f32_16x16x32_bf16 v[4:7], v[144:147], v[196:199], v[4:7]
	v_mfma_f32_16x16x32_bf16 v[4:7], v[148:151], v[200:203], v[4:7]
	v_mfma_f32_16x16x32_bf16 v[8:11], v[120:123], v[196:199], v[8:11]
	v_mfma_f32_16x16x32_bf16 v[8:11], v[128:131], v[200:203], v[8:11]
	v_mfma_f32_16x16x32_bf16 v[12:15], v[112:115], v[196:199], v[12:15]
	v_mfma_f32_16x16x32_bf16 v[12:15], v[116:119], v[200:203], v[12:15]
	s_barrier
	s_add_u32 s28, s28, 0x100
	s_addc_u32 s29, s29, 0
	s_add_u32 s60, s60, 0x100
	s_addc_u32 s61, s61, 0
	s_cmp_ge_i32 s62, s45
	s_mov_b32 s30, s62
	s_cbranch_scc0 .LBB0_849

.LBB0_949:
	ds_read_b128 v[164:167], v157
	ds_read_b128 v[168:171], v157 offset:1024
	ds_read_b128 v[172:175], v157 offset:2048
	ds_read_b128 v[176:179], v157 offset:3072
	ds_read_b128 v[180:183], v162
	ds_read_b128 v[184:187], v162 offset:1024
	ds_read_b128 v[188:191], v162 offset:2048
	ds_read_b128 v[192:195], v162 offset:3072
	s_add_i32 s68, s34, 2
	s_add_u32 s69, s30, 0x80
	s_addc_u32 s35, s31, 0
	s_cmp_eq_u32 s49, s34
	s_cselect_b32 s34, s2, s69
	s_cselect_b32 s35, s3, s35
	s_cselect_b32 s71, s29, s67
	s_cselect_b32 s70, s28, s66
	v_lshl_add_u64 v[230:231], s[30:31], 0, v[136:137]
	s_add_i32 m0, s41, 0xc000
	ds_read_b128 v[196:199], v163
	ds_read_b128 v[200:203], v163 offset:1024
	ds_read_b128 v[204:207], v163 offset:2048
	ds_read_b128 v[208:211], v163 offset:3072
	ds_read_b128 v[212:215], v163 offset:4096
	ds_read_b128 v[216:219], v163 offset:5120
	ds_read_b128 v[222:225], v163 offset:6144
	ds_read_b128 v[226:229], v163 offset:7168
	global_load_lds_dwordx4 v[230:231], off
	v_lshl_add_u64 v[230:231], s[30:31], 0, v[138:139]
	s_add_i32 m0, s41, 0xe000
	s_nop 0
	global_load_lds_dwordx4 v[230:231], off
	s_waitcnt vmcnt(8)
	s_waitcnt lgkmcnt(0)
	s_barrier
	s_waitcnt lgkmcnt(0)
	v_mfma_f32_16x16x32_bf16 v[120:123], v[164:167], v[196:199], v[120:123]
	v_mfma_f32_16x16x32_bf16 v[120:123], v[168:171], v[200:203], v[120:123]
	v_mfma_f32_16x16x32_bf16 v[124:127], v[172:175], v[196:199], v[124:127]
	v_mfma_f32_16x16x32_bf16 v[124:127], v[176:179], v[200:203], v[124:127]
	v_mfma_f32_16x16x32_bf16 v[116:119], v[180:183], v[196:199], v[116:119]
	v_mfma_f32_16x16x32_bf16 v[116:119], v[184:187], v[200:203], v[116:119]
	v_mfma_f32_16x16x32_bf16 v[112:115], v[188:191], v[196:199], v[112:115]
	v_mfma_f32_16x16x32_bf16 v[112:115], v[192:195], v[200:203], v[112:115]
	v_mfma_f32_16x16x32_bf16 v[96:99], v[188:191], v[204:207], v[96:99]
	v_mfma_f32_16x16x32_bf16 v[96:99], v[192:195], v[208:211], v[96:99]
	v_mfma_f32_16x16x32_bf16 v[100:103], v[180:183], v[204:207], v[100:103]
	v_mfma_f32_16x16x32_bf16 v[100:103], v[184:187], v[208:211], v[100:103]
	v_mfma_f32_16x16x32_bf16 v[104:107], v[172:175], v[204:207], v[104:107]
	v_mfma_f32_16x16x32_bf16 v[104:107], v[176:179], v[208:211], v[104:107]
	v_mfma_f32_16x16x32_bf16 v[108:111], v[164:167], v[204:207], v[108:111]
	v_mfma_f32_16x16x32_bf16 v[108:111], v[168:171], v[208:211], v[108:111]
	v_mfma_f32_16x16x32_bf16 v[92:95], v[164:167], v[212:215], v[92:95]
	v_mfma_f32_16x16x32_bf16 v[92:95], v[168:171], v[216:219], v[92:95]
	v_mfma_f32_16x16x32_bf16 v[88:91], v[172:175], v[212:215], v[88:91]
	v_mfma_f32_16x16x32_bf16 v[88:91], v[176:179], v[216:219], v[88:91]
	v_mfma_f32_16x16x32_bf16 v[84:87], v[180:183], v[212:215], v[84:87]
	v_mfma_f32_16x16x32_bf16 v[84:87], v[184:187], v[216:219], v[84:87]
	v_mfma_f32_16x16x32_bf16 v[80:83], v[188:191], v[212:215], v[80:83]
	v_mfma_f32_16x16x32_bf16 v[80:83], v[192:195], v[216:219], v[80:83]
	v_mfma_f32_16x16x32_bf16 v[64:67], v[188:191], v[222:225], v[64:67]
	v_mfma_f32_16x16x32_bf16 v[64:67], v[192:195], v[226:229], v[64:67]
	v_mfma_f32_16x16x32_bf16 v[68:71], v[180:183], v[222:225], v[68:71]
	v_mfma_f32_16x16x32_bf16 v[68:71], v[184:187], v[226:229], v[68:71]
	v_mfma_f32_16x16x32_bf16 v[72:75], v[172:175], v[222:225], v[72:75]
	v_mfma_f32_16x16x32_bf16 v[72:75], v[176:179], v[226:229], v[72:75]
	v_mfma_f32_16x16x32_bf16 v[76:79], v[164:167], v[222:225], v[76:79]
	v_mfma_f32_16x16x32_bf16 v[76:79], v[168:171], v[226:229], v[76:79]
	s_barrier
	s_add_i32 s69, s52, s40
	v_lshl_add_u64 v[230:231], s[70:71], 0, v[130:131]
	s_mov_b32 m0, s69
	ds_read_b128 v[196:199], v163 offset:16384
	ds_read_b128 v[200:203], v163 offset:17408
	ds_read_b128 v[204:207], v163 offset:18432
	ds_read_b128 v[208:211], v163 offset:19456
	ds_read_b128 v[212:215], v163 offset:20480
	ds_read_b128 v[216:219], v163 offset:21504
	ds_read_b128 v[222:225], v163 offset:22528
	ds_read_b128 v[226:229], v163 offset:23552
	global_load_lds_dwordx4 v[230:231], off
	s_add_i32 m0, s69, 0x2000
	v_lshl_add_u64 v[232:233], s[70:71], 0, v[134:135]
	s_add_u32 s70, s70, s6
	s_addc_u32 s71, s71, s7
	s_add_i32 s69, s53, s40
	global_load_lds_dwordx4 v[232:233], off
	v_lshl_add_u64 v[234:235], s[70:71], 0, v[130:131]
	s_mov_b32 m0, s69
	v_lshl_add_u64 v[236:237], s[70:71], 0, v[134:135]
	global_load_lds_dwordx4 v[234:235], off
	s_add_i32 m0, s69, 0x2000
	v_lshl_add_u64 v[238:239], s[34:35], 0, v[128:129]
	global_load_lds_dwordx4 v[236:237], off
	s_mov_b32 m0, s41
	v_lshl_add_u64 v[240:241], s[34:35], 0, v[132:133]
	global_load_lds_dwordx4 v[238:239], off
	s_mov_b32 m0, s42
	s_nop 0
	global_load_lds_dwordx4 v[240:241], off
	s_waitcnt vmcnt(8)
	s_waitcnt lgkmcnt(0)
	s_barrier
	s_waitcnt lgkmcnt(0)
	v_mfma_f32_16x16x32_bf16 v[60:63], v[164:167], v[196:199], v[60:63]
	v_mfma_f32_16x16x32_bf16 v[60:63], v[168:171], v[200:203], v[60:63]
	v_mfma_f32_16x16x32_bf16 v[56:59], v[172:175], v[196:199], v[56:59]
	v_mfma_f32_16x16x32_bf16 v[56:59], v[176:179], v[200:203], v[56:59]
	v_mfma_f32_16x16x32_bf16 v[52:55], v[180:183], v[196:199], v[52:55]
	v_mfma_f32_16x16x32_bf16 v[52:55], v[184:187], v[200:203], v[52:55]
	v_mfma_f32_16x16x32_bf16 v[48:51], v[188:191], v[196:199], v[48:51]
	v_mfma_f32_16x16x32_bf16 v[48:51], v[192:195], v[200:203], v[48:51]
	v_mfma_f32_16x16x32_bf16 v[32:35], v[188:191], v[204:207], v[32:35]
	v_mfma_f32_16x16x32_bf16 v[32:35], v[192:195], v[208:211], v[32:35]
	v_mfma_f32_16x16x32_bf16 v[36:39], v[180:183], v[204:207], v[36:39]
	v_mfma_f32_16x16x32_bf16 v[36:39], v[184:187], v[208:211], v[36:39]
	v_mfma_f32_16x16x32_bf16 v[40:43], v[172:175], v[204:207], v[40:43]
	v_mfma_f32_16x16x32_bf16 v[40:43], v[176:179], v[208:211], v[40:43]
	v_mfma_f32_16x16x32_bf16 v[44:47], v[164:167], v[204:207], v[44:47]
	v_mfma_f32_16x16x32_bf16 v[44:47], v[168:171], v[208:211], v[44:47]
	v_mfma_f32_16x16x32_bf16 v[28:31], v[164:167], v[212:215], v[28:31]
	v_mfma_f32_16x16x32_bf16 v[28:31], v[168:171], v[216:219], v[28:31]
	v_mfma_f32_16x16x32_bf16 v[24:27], v[172:175], v[212:215], v[24:27]
	v_mfma_f32_16x16x32_bf16 v[24:27], v[176:179], v[216:219], v[24:27]
	v_mfma_f32_16x16x32_bf16 v[20:23], v[180:183], v[212:215], v[20:23]
	v_mfma_f32_16x16x32_bf16 v[20:23], v[184:187], v[216:219], v[20:23]
	v_mfma_f32_16x16x32_bf16 v[16:19], v[188:191], v[212:215], v[16:19]
	v_mfma_f32_16x16x32_bf16 v[16:19], v[192:195], v[216:219], v[16:19]
	v_mfma_f32_16x16x32_bf16 v[0:3], v[188:191], v[222:225], v[0:3]
	v_mfma_f32_16x16x32_bf16 v[0:3], v[192:195], v[226:229], v[0:3]
	v_mfma_f32_16x16x32_bf16 v[4:7], v[180:183], v[222:225], v[4:7]
	v_mfma_f32_16x16x32_bf16 v[4:7], v[184:187], v[226:229], v[4:7]
	v_mfma_f32_16x16x32_bf16 v[8:11], v[172:175], v[222:225], v[8:11]
	v_mfma_f32_16x16x32_bf16 v[8:11], v[176:179], v[226:229], v[8:11]
	v_mfma_f32_16x16x32_bf16 v[12:15], v[164:167], v[222:225], v[12:15]
	v_mfma_f32_16x16x32_bf16 v[12:15], v[168:171], v[226:229], v[12:15]
	s_barrier
	s_add_i32 s69, 0, 0x18000
	s_add_i32 s70, 0, 0x1c000
	v_add_u32_e32 v176, s69, v154
	v_add_u32_e32 v192, s70, v154
	ds_read_b128 v[164:167], v176
	ds_read_b128 v[168:171], v176 offset:1024
	ds_read_b128 v[172:175], v176 offset:2048
	ds_read_b128 v[176:179], v176 offset:3072
	ds_read_b128 v[180:183], v192
	ds_read_b128 v[184:187], v192 offset:1024
	ds_read_b128 v[188:191], v192 offset:2048
	ds_read_b128 v[192:195], v192 offset:3072
	s_add_u32 s34, s34, s6
	s_addc_u32 s35, s35, s7
	s_mov_b32 m0, s43
	v_lshl_add_u64 v[242:243], s[34:35], 0, v[128:129]
	ds_read_b128 v[196:199], v163 offset:32768
	ds_read_b128 v[200:203], v163 offset:33792
	ds_read_b128 v[204:207], v163 offset:34816
	ds_read_b128 v[208:211], v163 offset:35840
	ds_read_b128 v[212:215], v163 offset:36864
	ds_read_b128 v[216:219], v163 offset:37888
	ds_read_b128 v[222:225], v163 offset:38912
	ds_read_b128 v[226:229], v163 offset:39936
	global_load_lds_dwordx4 v[242:243], off
	v_lshl_add_u64 v[242:243], s[34:35], 0, v[132:133]
	s_mov_b32 m0, s44
	s_nop 0
	global_load_lds_dwordx4 v[242:243], off
	s_waitcnt vmcnt(8)
	s_waitcnt lgkmcnt(0)
	s_barrier
	s_waitcnt lgkmcnt(0)
	v_mfma_f32_16x16x32_bf16 v[120:123], v[164:167], v[196:199], v[120:123]
	v_mfma_f32_16x16x32_bf16 v[120:123], v[168:171], v[200:203], v[120:123]
	v_mfma_f32_16x16x32_bf16 v[124:127], v[172:175], v[196:199], v[124:127]
	v_mfma_f32_16x16x32_bf16 v[124:127], v[176:179], v[200:203], v[124:127]
	v_mfma_f32_16x16x32_bf16 v[116:119], v[180:183], v[196:199], v[116:119]
	v_mfma_f32_16x16x32_bf16 v[116:119], v[184:187], v[200:203], v[116:119]
	v_mfma_f32_16x16x32_bf16 v[112:115], v[188:191], v[196:199], v[112:115]
	v_mfma_f32_16x16x32_bf16 v[112:115], v[192:195], v[200:203], v[112:115]
	v_mfma_f32_16x16x32_bf16 v[96:99], v[188:191], v[204:207], v[96:99]
	v_mfma_f32_16x16x32_bf16 v[96:99], v[192:195], v[208:211], v[96:99]
	v_mfma_f32_16x16x32_bf16 v[100:103], v[180:183], v[204:207], v[100:103]
	v_mfma_f32_16x16x32_bf16 v[100:103], v[184:187], v[208:211], v[100:103]
	v_mfma_f32_16x16x32_bf16 v[104:107], v[172:175], v[204:207], v[104:107]
	v_mfma_f32_16x16x32_bf16 v[104:107], v[176:179], v[208:211], v[104:107]
	v_mfma_f32_16x16x32_bf16 v[108:111], v[164:167], v[204:207], v[108:111]
	v_mfma_f32_16x16x32_bf16 v[108:111], v[168:171], v[208:211], v[108:111]
	v_mfma_f32_16x16x32_bf16 v[92:95], v[164:167], v[212:215], v[92:95]
	v_mfma_f32_16x16x32_bf16 v[92:95], v[168:171], v[216:219], v[92:95]
	v_mfma_f32_16x16x32_bf16 v[88:91], v[172:175], v[212:215], v[88:91]
	v_mfma_f32_16x16x32_bf16 v[88:91], v[176:179], v[216:219], v[88:91]
	v_mfma_f32_16x16x32_bf16 v[84:87], v[180:183], v[212:215], v[84:87]
	v_mfma_f32_16x16x32_bf16 v[84:87], v[184:187], v[216:219], v[84:87]
	v_mfma_f32_16x16x32_bf16 v[80:83], v[188:191], v[212:215], v[80:83]
	v_mfma_f32_16x16x32_bf16 v[80:83], v[192:195], v[216:219], v[80:83]
	v_mfma_f32_16x16x32_bf16 v[64:67], v[188:191], v[222:225], v[64:67]
	v_mfma_f32_16x16x32_bf16 v[64:67], v[192:195], v[226:229], v[64:67]
	v_mfma_f32_16x16x32_bf16 v[68:71], v[180:183], v[222:225], v[68:71]
	v_mfma_f32_16x16x32_bf16 v[68:71], v[184:187], v[226:229], v[68:71]
	v_mfma_f32_16x16x32_bf16 v[72:75], v[172:175], v[222:225], v[72:75]
	v_mfma_f32_16x16x32_bf16 v[72:75], v[176:179], v[226:229], v[72:75]
	v_mfma_f32_16x16x32_bf16 v[76:79], v[164:167], v[222:225], v[76:79]
	v_mfma_f32_16x16x32_bf16 v[76:79], v[168:171], v[226:229], v[76:79]
	s_barrier
	s_add_i32 s34, s69, s40
	v_lshl_add_u64 v[230:231], v[230:231], 0, s[12:13]
	s_mov_b32 m0, s34
	ds_read_b128 v[196:199], v163 offset:49152
	ds_read_b128 v[200:203], v163 offset:50176
	ds_read_b128 v[204:207], v163 offset:51200
	ds_read_b128 v[208:211], v163 offset:52224
	ds_read_b128 v[212:215], v163 offset:53248
	ds_read_b128 v[216:219], v163 offset:54272
	ds_read_b128 v[222:225], v163 offset:55296
	ds_read_b128 v[226:229], v163 offset:56320
	global_load_lds_dwordx4 v[230:231], off
	v_lshl_add_u64 v[230:231], v[232:233], 0, s[12:13]
	s_add_i32 m0, s34, 0x2000
	s_add_i32 s34, s70, s40
	global_load_lds_dwordx4 v[230:231], off
	v_lshl_add_u64 v[230:231], v[234:235], 0, s[12:13]
	s_mov_b32 m0, s34
	s_nop 0
	global_load_lds_dwordx4 v[230:231], off
	v_lshl_add_u64 v[230:231], v[236:237], 0, s[12:13]
	s_add_i32 m0, s34, 0x2000
	s_nop 0
	global_load_lds_dwordx4 v[230:231], off
	v_lshl_add_u64 v[230:231], v[238:239], 0, s[12:13]
	s_mov_b32 m0, s46
	s_nop 0
	global_load_lds_dwordx4 v[230:231], off
	v_lshl_add_u64 v[230:231], v[240:241], 0, s[12:13]
	s_mov_b32 m0, s47
	s_nop 0
	global_load_lds_dwordx4 v[230:231], off
	s_waitcnt vmcnt(8)
	s_waitcnt lgkmcnt(0)
	s_barrier
	s_waitcnt lgkmcnt(0)
	v_mfma_f32_16x16x32_bf16 v[60:63], v[164:167], v[196:199], v[60:63]
	v_mfma_f32_16x16x32_bf16 v[60:63], v[168:171], v[200:203], v[60:63]
	v_mfma_f32_16x16x32_bf16 v[56:59], v[172:175], v[196:199], v[56:59]
	v_mfma_f32_16x16x32_bf16 v[56:59], v[176:179], v[200:203], v[56:59]
	v_mfma_f32_16x16x32_bf16 v[52:55], v[180:183], v[196:199], v[52:55]
	v_mfma_f32_16x16x32_bf16 v[52:55], v[184:187], v[200:203], v[52:55]
	v_mfma_f32_16x16x32_bf16 v[48:51], v[188:191], v[196:199], v[48:51]
	v_mfma_f32_16x16x32_bf16 v[48:51], v[192:195], v[200:203], v[48:51]
	v_mfma_f32_16x16x32_bf16 v[32:35], v[188:191], v[204:207], v[32:35]
	v_mfma_f32_16x16x32_bf16 v[32:35], v[192:195], v[208:211], v[32:35]
	v_mfma_f32_16x16x32_bf16 v[36:39], v[180:183], v[204:207], v[36:39]
	v_mfma_f32_16x16x32_bf16 v[36:39], v[184:187], v[208:211], v[36:39]
	v_mfma_f32_16x16x32_bf16 v[40:43], v[172:175], v[204:207], v[40:43]
	v_mfma_f32_16x16x32_bf16 v[40:43], v[176:179], v[208:211], v[40:43]
	v_mfma_f32_16x16x32_bf16 v[44:47], v[164:167], v[204:207], v[44:47]
	v_mfma_f32_16x16x32_bf16 v[44:47], v[168:171], v[208:211], v[44:47]
	v_mfma_f32_16x16x32_bf16 v[28:31], v[164:167], v[212:215], v[28:31]
	v_mfma_f32_16x16x32_bf16 v[28:31], v[168:171], v[216:219], v[28:31]
	v_mfma_f32_16x16x32_bf16 v[24:27], v[172:175], v[212:215], v[24:27]
	v_mfma_f32_16x16x32_bf16 v[24:27], v[176:179], v[216:219], v[24:27]
	v_mfma_f32_16x16x32_bf16 v[20:23], v[180:183], v[212:215], v[20:23]
	v_mfma_f32_16x16x32_bf16 v[20:23], v[184:187], v[216:219], v[20:23]
	v_mfma_f32_16x16x32_bf16 v[16:19], v[188:191], v[212:215], v[16:19]
	v_mfma_f32_16x16x32_bf16 v[16:19], v[192:195], v[216:219], v[16:19]
	v_mfma_f32_16x16x32_bf16 v[0:3], v[188:191], v[222:225], v[0:3]
	v_mfma_f32_16x16x32_bf16 v[0:3], v[192:195], v[226:229], v[0:3]
	v_mfma_f32_16x16x32_bf16 v[4:7], v[180:183], v[222:225], v[4:7]
	v_mfma_f32_16x16x32_bf16 v[4:7], v[184:187], v[226:229], v[4:7]
	v_mfma_f32_16x16x32_bf16 v[8:11], v[172:175], v[222:225], v[8:11]
	v_mfma_f32_16x16x32_bf16 v[8:11], v[176:179], v[226:229], v[8:11]
	v_mfma_f32_16x16x32_bf16 v[12:15], v[164:167], v[222:225], v[12:15]
	v_mfma_f32_16x16x32_bf16 v[12:15], v[168:171], v[226:229], v[12:15]
	s_barrier
	s_add_u32 s30, s30, 0x100
	s_addc_u32 s31, s31, 0
	s_add_u32 s66, s66, 0x100
	s_addc_u32 s67, s67, 0
	s_cmp_ge_i32 s68, s48
	s_mov_b32 s34, s68
	s_cbranch_scc0 .LBB0_949

.LBB0_970:
	ds_read_b128 v[170:173], v139
	ds_read_b128 v[174:177], v139 offset:1024
	ds_read_b128 v[178:181], v139 offset:2048
	ds_read_b128 v[182:185], v139 offset:3072
	ds_read_b128 v[186:189], v165
	ds_read_b128 v[190:193], v165 offset:1024
	ds_read_b128 v[194:197], v165 offset:2048
	ds_read_b128 v[198:201], v165 offset:3072
	s_add_i32 s8, s4, 2
	s_add_u32 s9, s2, 0x80
	s_addc_u32 s5, s3, 0
	s_cmp_eq_u32 s52, s4
	s_cselect_b32 s4, s30, s9
	s_cselect_b32 s5, s31, s5
	s_cselect_b32 s11, s35, s7
	s_cselect_b32 s10, s34, s6
	v_lshl_add_u64 v[218:219], s[2:3], 0, v[156:157]
	s_add_i32 m0, s42, 0xc000
	ds_read_b128 v[202:205], v166
	ds_read_b128 v[206:209], v166 offset:1024
	ds_read_b128 v[210:213], v166 offset:2048
	ds_read_b128 v[214:217], v166 offset:3072
	ds_read_b128 v[222:225], v166 offset:4096
	ds_read_b128 v[226:229], v166 offset:5120
	ds_read_b128 v[230:233], v166 offset:6144
	ds_read_b128 v[234:237], v166 offset:7168
	global_load_lds_dwordx4 v[218:219], off
	v_lshl_add_u64 v[218:219], s[2:3], 0, v[158:159]
	s_add_i32 m0, s42, 0xe000
	s_nop 0
	global_load_lds_dwordx4 v[218:219], off
	s_waitcnt vmcnt(8)
	s_waitcnt lgkmcnt(0)
	s_barrier
	s_waitcnt lgkmcnt(0)
	v_mfma_f32_16x16x32_bf16 v[124:127], v[170:173], v[202:205], v[124:127]
	v_mfma_f32_16x16x32_bf16 v[124:127], v[174:177], v[206:209], v[124:127]
	v_mfma_f32_16x16x32_bf16 v[120:123], v[178:181], v[202:205], v[120:123]
	v_mfma_f32_16x16x32_bf16 v[120:123], v[182:185], v[206:209], v[120:123]
	v_mfma_f32_16x16x32_bf16 v[116:119], v[186:189], v[202:205], v[116:119]
	v_mfma_f32_16x16x32_bf16 v[116:119], v[190:193], v[206:209], v[116:119]
	v_mfma_f32_16x16x32_bf16 v[112:115], v[194:197], v[202:205], v[112:115]
	v_mfma_f32_16x16x32_bf16 v[112:115], v[198:201], v[206:209], v[112:115]
	v_mfma_f32_16x16x32_bf16 v[96:99], v[194:197], v[210:213], v[96:99]
	v_mfma_f32_16x16x32_bf16 v[96:99], v[198:201], v[214:217], v[96:99]
	v_mfma_f32_16x16x32_bf16 v[100:103], v[186:189], v[210:213], v[100:103]
	v_mfma_f32_16x16x32_bf16 v[100:103], v[190:193], v[214:217], v[100:103]
	v_mfma_f32_16x16x32_bf16 v[104:107], v[178:181], v[210:213], v[104:107]
	v_mfma_f32_16x16x32_bf16 v[104:107], v[182:185], v[214:217], v[104:107]
	v_mfma_f32_16x16x32_bf16 v[108:111], v[170:173], v[210:213], v[108:111]
	v_mfma_f32_16x16x32_bf16 v[108:111], v[174:177], v[214:217], v[108:111]
	v_mfma_f32_16x16x32_bf16 v[92:95], v[170:173], v[222:225], v[92:95]
	v_mfma_f32_16x16x32_bf16 v[92:95], v[174:177], v[226:229], v[92:95]
	v_mfma_f32_16x16x32_bf16 v[88:91], v[178:181], v[222:225], v[88:91]
	v_mfma_f32_16x16x32_bf16 v[88:91], v[182:185], v[226:229], v[88:91]
	v_mfma_f32_16x16x32_bf16 v[84:87], v[186:189], v[222:225], v[84:87]
	v_mfma_f32_16x16x32_bf16 v[84:87], v[190:193], v[226:229], v[84:87]
	v_mfma_f32_16x16x32_bf16 v[80:83], v[194:197], v[222:225], v[80:83]
	v_mfma_f32_16x16x32_bf16 v[80:83], v[198:201], v[226:229], v[80:83]
	v_mfma_f32_16x16x32_bf16 v[64:67], v[194:197], v[230:233], v[64:67]
	v_mfma_f32_16x16x32_bf16 v[64:67], v[198:201], v[234:237], v[64:67]
	v_mfma_f32_16x16x32_bf16 v[68:71], v[186:189], v[230:233], v[68:71]
	v_mfma_f32_16x16x32_bf16 v[68:71], v[190:193], v[234:237], v[68:71]
	v_mfma_f32_16x16x32_bf16 v[72:75], v[178:181], v[230:233], v[72:75]
	v_mfma_f32_16x16x32_bf16 v[72:75], v[182:185], v[234:237], v[72:75]
	v_mfma_f32_16x16x32_bf16 v[76:79], v[170:173], v[230:233], v[76:79]
	v_mfma_f32_16x16x32_bf16 v[76:79], v[174:177], v[234:237], v[76:79]
	s_barrier
	s_add_i32 s9, s60, s39
	v_lshl_add_u64 v[218:219], s[10:11], 0, v[132:133]
	s_mov_b32 m0, s9
	ds_read_b128 v[202:205], v166 offset:16384
	ds_read_b128 v[206:209], v166 offset:17408
	ds_read_b128 v[210:213], v166 offset:18432
	ds_read_b128 v[214:217], v166 offset:19456
	ds_read_b128 v[222:225], v166 offset:20480
	ds_read_b128 v[226:229], v166 offset:21504
	ds_read_b128 v[230:233], v166 offset:22528
	ds_read_b128 v[234:237], v166 offset:23552
	global_load_lds_dwordx4 v[218:219], off
	s_add_i32 m0, s9, 0x2000
	v_lshl_add_u64 v[238:239], s[10:11], 0, v[128:129]
	s_add_u32 s10, s10, s18
	s_addc_u32 s11, s11, s19
	s_add_i32 s9, s61, s39
	global_load_lds_dwordx4 v[238:239], off
	v_lshl_add_u64 v[240:241], s[10:11], 0, v[132:133]
	s_mov_b32 m0, s9
	v_lshl_add_u64 v[242:243], s[10:11], 0, v[128:129]
	global_load_lds_dwordx4 v[240:241], off
	s_add_i32 m0, s9, 0x2000
	v_lshl_add_u64 v[244:245], s[4:5], 0, v[134:135]
	global_load_lds_dwordx4 v[242:243], off
	s_mov_b32 m0, s42
	v_lshl_add_u64 v[246:247], s[4:5], 0, v[130:131]
	global_load_lds_dwordx4 v[244:245], off
	s_mov_b32 m0, s43
	s_nop 0
	global_load_lds_dwordx4 v[246:247], off
	s_waitcnt vmcnt(8)
	s_waitcnt lgkmcnt(0)
	s_barrier
	s_waitcnt lgkmcnt(0)
	v_mfma_f32_16x16x32_bf16 v[60:63], v[170:173], v[202:205], v[60:63]
	v_mfma_f32_16x16x32_bf16 v[60:63], v[174:177], v[206:209], v[60:63]
	v_mfma_f32_16x16x32_bf16 v[56:59], v[178:181], v[202:205], v[56:59]
	v_mfma_f32_16x16x32_bf16 v[56:59], v[182:185], v[206:209], v[56:59]
	v_mfma_f32_16x16x32_bf16 v[52:55], v[186:189], v[202:205], v[52:55]
	v_mfma_f32_16x16x32_bf16 v[52:55], v[190:193], v[206:209], v[52:55]
	v_mfma_f32_16x16x32_bf16 v[48:51], v[194:197], v[202:205], v[48:51]
	v_mfma_f32_16x16x32_bf16 v[48:51], v[198:201], v[206:209], v[48:51]
	v_mfma_f32_16x16x32_bf16 v[32:35], v[194:197], v[210:213], v[32:35]
	v_mfma_f32_16x16x32_bf16 v[32:35], v[198:201], v[214:217], v[32:35]
	v_mfma_f32_16x16x32_bf16 v[36:39], v[186:189], v[210:213], v[36:39]
	v_mfma_f32_16x16x32_bf16 v[36:39], v[190:193], v[214:217], v[36:39]
	v_mfma_f32_16x16x32_bf16 v[40:43], v[178:181], v[210:213], v[40:43]
	v_mfma_f32_16x16x32_bf16 v[40:43], v[182:185], v[214:217], v[40:43]
	v_mfma_f32_16x16x32_bf16 v[44:47], v[170:173], v[210:213], v[44:47]
	v_mfma_f32_16x16x32_bf16 v[44:47], v[174:177], v[214:217], v[44:47]
	v_mfma_f32_16x16x32_bf16 v[28:31], v[170:173], v[222:225], v[28:31]
	v_mfma_f32_16x16x32_bf16 v[28:31], v[174:177], v[226:229], v[28:31]
	v_mfma_f32_16x16x32_bf16 v[24:27], v[178:181], v[222:225], v[24:27]
	v_mfma_f32_16x16x32_bf16 v[24:27], v[182:185], v[226:229], v[24:27]
	v_mfma_f32_16x16x32_bf16 v[20:23], v[186:189], v[222:225], v[20:23]
	v_mfma_f32_16x16x32_bf16 v[20:23], v[190:193], v[226:229], v[20:23]
	v_mfma_f32_16x16x32_bf16 v[16:19], v[194:197], v[222:225], v[16:19]
	v_mfma_f32_16x16x32_bf16 v[16:19], v[198:201], v[226:229], v[16:19]
	v_mfma_f32_16x16x32_bf16 v[0:3], v[194:197], v[230:233], v[0:3]
	v_mfma_f32_16x16x32_bf16 v[0:3], v[198:201], v[234:237], v[0:3]
	v_mfma_f32_16x16x32_bf16 v[4:7], v[186:189], v[230:233], v[4:7]
	v_mfma_f32_16x16x32_bf16 v[4:7], v[190:193], v[234:237], v[4:7]
	v_mfma_f32_16x16x32_bf16 v[8:11], v[178:181], v[230:233], v[8:11]
	v_mfma_f32_16x16x32_bf16 v[8:11], v[182:185], v[234:237], v[8:11]
	v_mfma_f32_16x16x32_bf16 v[12:15], v[170:173], v[230:233], v[12:15]
	v_mfma_f32_16x16x32_bf16 v[12:15], v[174:177], v[234:237], v[12:15]
	s_barrier
	s_add_i32 s9, 0, 0x18000
	v_add_u32_e32 v169, s9, v164
	s_add_i32 s10, 0, 0x1c000
	ds_read_b128 v[170:173], v169
	ds_read_b128 v[174:177], v169 offset:1024
	ds_read_b128 v[178:181], v169 offset:2048
	ds_read_b128 v[182:185], v169 offset:3072
	v_add_u32_e32 v169, s10, v164
	ds_read_b128 v[186:189], v169
	ds_read_b128 v[190:193], v169 offset:1024
	ds_read_b128 v[194:197], v169 offset:2048
	ds_read_b128 v[198:201], v169 offset:3072
	s_add_u32 s4, s4, s18
	s_addc_u32 s5, s5, s19
	s_mov_b32 m0, s44
	v_lshl_add_u64 v[248:249], s[4:5], 0, v[134:135]
	ds_read_b128 v[202:205], v166 offset:32768
	ds_read_b128 v[206:209], v166 offset:33792
	ds_read_b128 v[210:213], v166 offset:34816
	ds_read_b128 v[214:217], v166 offset:35840
	ds_read_b128 v[222:225], v166 offset:36864
	ds_read_b128 v[226:229], v166 offset:37888
	ds_read_b128 v[230:233], v166 offset:38912
	ds_read_b128 v[234:237], v166 offset:39936
	global_load_lds_dwordx4 v[248:249], off
	v_lshl_add_u64 v[248:249], s[4:5], 0, v[130:131]
	s_mov_b32 m0, s45
	s_nop 0
	global_load_lds_dwordx4 v[248:249], off
	s_waitcnt vmcnt(8)
	s_waitcnt lgkmcnt(0)
	s_barrier
	s_waitcnt lgkmcnt(0)
	v_mfma_f32_16x16x32_bf16 v[124:127], v[170:173], v[202:205], v[124:127]
	v_mfma_f32_16x16x32_bf16 v[124:127], v[174:177], v[206:209], v[124:127]
	v_mfma_f32_16x16x32_bf16 v[120:123], v[178:181], v[202:205], v[120:123]
	v_mfma_f32_16x16x32_bf16 v[120:123], v[182:185], v[206:209], v[120:123]
	v_mfma_f32_16x16x32_bf16 v[116:119], v[186:189], v[202:205], v[116:119]
	v_mfma_f32_16x16x32_bf16 v[116:119], v[190:193], v[206:209], v[116:119]
	v_mfma_f32_16x16x32_bf16 v[112:115], v[194:197], v[202:205], v[112:115]
	v_mfma_f32_16x16x32_bf16 v[112:115], v[198:201], v[206:209], v[112:115]
	v_mfma_f32_16x16x32_bf16 v[96:99], v[194:197], v[210:213], v[96:99]
	v_mfma_f32_16x16x32_bf16 v[96:99], v[198:201], v[214:217], v[96:99]
	v_mfma_f32_16x16x32_bf16 v[100:103], v[186:189], v[210:213], v[100:103]
	v_mfma_f32_16x16x32_bf16 v[100:103], v[190:193], v[214:217], v[100:103]
	v_mfma_f32_16x16x32_bf16 v[104:107], v[178:181], v[210:213], v[104:107]
	v_mfma_f32_16x16x32_bf16 v[104:107], v[182:185], v[214:217], v[104:107]
	v_mfma_f32_16x16x32_bf16 v[108:111], v[170:173], v[210:213], v[108:111]
	v_mfma_f32_16x16x32_bf16 v[108:111], v[174:177], v[214:217], v[108:111]
	v_mfma_f32_16x16x32_bf16 v[92:95], v[170:173], v[222:225], v[92:95]
	v_mfma_f32_16x16x32_bf16 v[92:95], v[174:177], v[226:229], v[92:95]
	v_mfma_f32_16x16x32_bf16 v[88:91], v[178:181], v[222:225], v[88:91]
	v_mfma_f32_16x16x32_bf16 v[88:91], v[182:185], v[226:229], v[88:91]
	v_mfma_f32_16x16x32_bf16 v[84:87], v[186:189], v[222:225], v[84:87]
	v_mfma_f32_16x16x32_bf16 v[84:87], v[190:193], v[226:229], v[84:87]
	v_mfma_f32_16x16x32_bf16 v[80:83], v[194:197], v[222:225], v[80:83]
	v_mfma_f32_16x16x32_bf16 v[80:83], v[198:201], v[226:229], v[80:83]
	v_mfma_f32_16x16x32_bf16 v[64:67], v[194:197], v[230:233], v[64:67]
	v_mfma_f32_16x16x32_bf16 v[64:67], v[198:201], v[234:237], v[64:67]
	v_mfma_f32_16x16x32_bf16 v[68:71], v[186:189], v[230:233], v[68:71]
	v_mfma_f32_16x16x32_bf16 v[68:71], v[190:193], v[234:237], v[68:71]
	v_mfma_f32_16x16x32_bf16 v[72:75], v[178:181], v[230:233], v[72:75]
	v_mfma_f32_16x16x32_bf16 v[72:75], v[182:185], v[234:237], v[72:75]
	v_mfma_f32_16x16x32_bf16 v[76:79], v[170:173], v[230:233], v[76:79]
	v_mfma_f32_16x16x32_bf16 v[76:79], v[174:177], v[234:237], v[76:79]
	s_barrier
	s_add_i32 s4, s9, s39
	v_lshl_add_u64 v[218:219], v[218:219], 0, s[24:25]
	s_mov_b32 m0, s4
	ds_read_b128 v[202:205], v166 offset:49152
	ds_read_b128 v[206:209], v166 offset:50176
	ds_read_b128 v[210:213], v166 offset:51200
	ds_read_b128 v[214:217], v166 offset:52224
	ds_read_b128 v[222:225], v166 offset:53248
	ds_read_b128 v[226:229], v166 offset:54272
	ds_read_b128 v[230:233], v166 offset:55296
	ds_read_b128 v[234:237], v166 offset:56320
	global_load_lds_dwordx4 v[218:219], off
	v_lshl_add_u64 v[218:219], v[238:239], 0, s[24:25]
	s_add_i32 m0, s4, 0x2000
	s_add_i32 s4, s10, s39
	global_load_lds_dwordx4 v[218:219], off
	v_lshl_add_u64 v[218:219], v[240:241], 0, s[24:25]
	s_mov_b32 m0, s4
	s_nop 0
	global_load_lds_dwordx4 v[218:219], off
	v_lshl_add_u64 v[218:219], v[242:243], 0, s[24:25]
	s_add_i32 m0, s4, 0x2000
	s_nop 0
	global_load_lds_dwordx4 v[218:219], off
	v_lshl_add_u64 v[218:219], v[244:245], 0, s[24:25]
	s_mov_b32 m0, s49
	s_nop 0
	global_load_lds_dwordx4 v[218:219], off
	v_lshl_add_u64 v[218:219], v[246:247], 0, s[24:25]
	s_mov_b32 m0, s50
	s_nop 0
	global_load_lds_dwordx4 v[218:219], off
	s_waitcnt vmcnt(8)
	s_waitcnt lgkmcnt(0)
	s_barrier
	s_waitcnt lgkmcnt(0)
	v_mfma_f32_16x16x32_bf16 v[60:63], v[170:173], v[202:205], v[60:63]
	v_mfma_f32_16x16x32_bf16 v[60:63], v[174:177], v[206:209], v[60:63]
	v_mfma_f32_16x16x32_bf16 v[56:59], v[178:181], v[202:205], v[56:59]
	v_mfma_f32_16x16x32_bf16 v[56:59], v[182:185], v[206:209], v[56:59]
	v_mfma_f32_16x16x32_bf16 v[52:55], v[186:189], v[202:205], v[52:55]
	v_mfma_f32_16x16x32_bf16 v[52:55], v[190:193], v[206:209], v[52:55]
	v_mfma_f32_16x16x32_bf16 v[48:51], v[194:197], v[202:205], v[48:51]
	v_mfma_f32_16x16x32_bf16 v[48:51], v[198:201], v[206:209], v[48:51]
	v_mfma_f32_16x16x32_bf16 v[32:35], v[194:197], v[210:213], v[32:35]
	v_mfma_f32_16x16x32_bf16 v[32:35], v[198:201], v[214:217], v[32:35]
	v_mfma_f32_16x16x32_bf16 v[36:39], v[186:189], v[210:213], v[36:39]
	v_mfma_f32_16x16x32_bf16 v[36:39], v[190:193], v[214:217], v[36:39]
	v_mfma_f32_16x16x32_bf16 v[40:43], v[178:181], v[210:213], v[40:43]
	v_mfma_f32_16x16x32_bf16 v[40:43], v[182:185], v[214:217], v[40:43]
	v_mfma_f32_16x16x32_bf16 v[44:47], v[170:173], v[210:213], v[44:47]
	v_mfma_f32_16x16x32_bf16 v[44:47], v[174:177], v[214:217], v[44:47]
	v_mfma_f32_16x16x32_bf16 v[28:31], v[170:173], v[222:225], v[28:31]
	v_mfma_f32_16x16x32_bf16 v[28:31], v[174:177], v[226:229], v[28:31]
	v_mfma_f32_16x16x32_bf16 v[24:27], v[178:181], v[222:225], v[24:27]
	v_mfma_f32_16x16x32_bf16 v[24:27], v[182:185], v[226:229], v[24:27]
	v_mfma_f32_16x16x32_bf16 v[20:23], v[186:189], v[222:225], v[20:23]
	v_mfma_f32_16x16x32_bf16 v[20:23], v[190:193], v[226:229], v[20:23]
	v_mfma_f32_16x16x32_bf16 v[16:19], v[194:197], v[222:225], v[16:19]
	v_mfma_f32_16x16x32_bf16 v[16:19], v[198:201], v[226:229], v[16:19]
	v_mfma_f32_16x16x32_bf16 v[0:3], v[194:197], v[230:233], v[0:3]
	v_mfma_f32_16x16x32_bf16 v[0:3], v[198:201], v[234:237], v[0:3]
	v_mfma_f32_16x16x32_bf16 v[4:7], v[186:189], v[230:233], v[4:7]
	v_mfma_f32_16x16x32_bf16 v[4:7], v[190:193], v[234:237], v[4:7]
	v_mfma_f32_16x16x32_bf16 v[8:11], v[178:181], v[230:233], v[8:11]
	v_mfma_f32_16x16x32_bf16 v[8:11], v[182:185], v[234:237], v[8:11]
	v_mfma_f32_16x16x32_bf16 v[12:15], v[170:173], v[230:233], v[12:15]
	v_mfma_f32_16x16x32_bf16 v[12:15], v[174:177], v[234:237], v[12:15]
	s_barrier
	s_add_u32 s2, s2, 0x100
	s_addc_u32 s3, s3, 0
	s_add_u32 s6, s6, 0x100
	s_addc_u32 s7, s7, 0
	s_cmp_ge_i32 s8, s51
	s_mov_b32 s4, s8
	s_cbranch_scc0 .LBB0_970

.LBB0_1056:
	ds_read_b128 v[140:143], v222
	ds_read_b128 v[144:147], v222 offset:1024
	ds_read_b128 v[148:151], v222 offset:2048
	ds_read_b128 v[152:155], v222 offset:3072
	ds_read_b128 v[156:159], v223
	ds_read_b128 v[160:163], v223 offset:1024
	ds_read_b128 v[164:167], v223 offset:2048
	ds_read_b128 v[168:171], v223 offset:3072
	s_add_i32 s62, s26, 2
	s_add_u32 s27, s24, 0x4000
	s_addc_u32 s28, s25, 0
	s_cmp_eq_u32 s46, s26
	s_cselect_b32 s30, s0, s27
	s_cselect_b32 s31, s1, s28
	s_cselect_b32 s28, s22, s60
	s_cselect_b32 s29, s23, s61
	s_add_u32 s26, s30, 0x8000
	s_addc_u32 s27, s31, 0
	v_lshl_add_u64 v[204:205], s[24:25], 0, v[132:133]
	s_add_i32 m0, s38, 0xc000
	ds_read_b128 v[172:175], v224
	ds_read_b128 v[176:179], v224 offset:1024
	ds_read_b128 v[180:183], v224 offset:2048
	ds_read_b128 v[184:187], v224 offset:3072
	ds_read_b128 v[188:191], v224 offset:4096
	ds_read_b128 v[192:195], v224 offset:5120
	ds_read_b128 v[196:199], v224 offset:6144
	ds_read_b128 v[200:203], v224 offset:7168
	global_load_lds_dwordx4 v[204:205], off
	v_lshl_add_u64 v[204:205], s[24:25], 0, v[134:135]
	s_add_i32 m0, s38, 0xe000
	s_nop 0
	global_load_lds_dwordx4 v[204:205], off
	s_waitcnt vmcnt(8)
	s_waitcnt lgkmcnt(0)
	s_barrier
	s_waitcnt lgkmcnt(0)
	v_mfma_f32_16x16x32_bf16 v[124:127], v[140:143], v[172:175], v[124:127]
	v_mfma_f32_16x16x32_bf16 v[124:127], v[144:147], v[176:179], v[124:127]
	v_mfma_f32_16x16x32_bf16 v[120:123], v[148:151], v[172:175], v[120:123]
	v_mfma_f32_16x16x32_bf16 v[120:123], v[152:155], v[176:179], v[120:123]
	v_mfma_f32_16x16x32_bf16 v[108:111], v[156:159], v[172:175], v[108:111]
	v_mfma_f32_16x16x32_bf16 v[108:111], v[160:163], v[176:179], v[108:111]
	v_mfma_f32_16x16x32_bf16 v[100:103], v[164:167], v[172:175], v[100:103]
	v_mfma_f32_16x16x32_bf16 v[100:103], v[168:171], v[176:179], v[100:103]
	v_mfma_f32_16x16x32_bf16 v[84:87], v[164:167], v[180:183], v[84:87]
	v_mfma_f32_16x16x32_bf16 v[84:87], v[168:171], v[184:187], v[84:87]
	v_mfma_f32_16x16x32_bf16 v[92:95], v[156:159], v[180:183], v[92:95]
	v_mfma_f32_16x16x32_bf16 v[92:95], v[160:163], v[184:187], v[92:95]
	v_mfma_f32_16x16x32_bf16 v[112:115], v[148:151], v[180:183], v[112:115]
	v_mfma_f32_16x16x32_bf16 v[112:115], v[152:155], v[184:187], v[112:115]
	v_mfma_f32_16x16x32_bf16 v[116:119], v[140:143], v[180:183], v[116:119]
	v_mfma_f32_16x16x32_bf16 v[116:119], v[144:147], v[184:187], v[116:119]
	v_mfma_f32_16x16x32_bf16 v[104:107], v[140:143], v[188:191], v[104:107]
	v_mfma_f32_16x16x32_bf16 v[104:107], v[144:147], v[192:195], v[104:107]
	v_mfma_f32_16x16x32_bf16 v[96:99], v[148:151], v[188:191], v[96:99]
	v_mfma_f32_16x16x32_bf16 v[96:99], v[152:155], v[192:195], v[96:99]
	v_mfma_f32_16x16x32_bf16 v[76:79], v[156:159], v[188:191], v[76:79]
	v_mfma_f32_16x16x32_bf16 v[76:79], v[160:163], v[192:195], v[76:79]
	v_mfma_f32_16x16x32_bf16 v[72:75], v[164:167], v[188:191], v[72:75]
	v_mfma_f32_16x16x32_bf16 v[72:75], v[168:171], v[192:195], v[72:75]
	v_mfma_f32_16x16x32_bf16 v[64:67], v[164:167], v[196:199], v[64:67]
	v_mfma_f32_16x16x32_bf16 v[64:67], v[168:171], v[200:203], v[64:67]
	v_mfma_f32_16x16x32_bf16 v[68:71], v[156:159], v[196:199], v[68:71]
	v_mfma_f32_16x16x32_bf16 v[68:71], v[160:163], v[200:203], v[68:71]
	v_mfma_f32_16x16x32_bf16 v[80:83], v[148:151], v[196:199], v[80:83]
	v_mfma_f32_16x16x32_bf16 v[80:83], v[152:155], v[200:203], v[80:83]
	v_mfma_f32_16x16x32_bf16 v[88:91], v[140:143], v[196:199], v[88:91]
	v_mfma_f32_16x16x32_bf16 v[88:91], v[144:147], v[200:203], v[88:91]
	s_barrier
	s_add_i32 s63, s50, s37
	v_lshl_add_u64 v[204:205], s[28:29], 0, v[128:129]
	s_mov_b32 m0, s63
	ds_read_b128 v[172:175], v224 offset:16384
	ds_read_b128 v[176:179], v224 offset:17408
	ds_read_b128 v[180:183], v224 offset:18432
	ds_read_b128 v[184:187], v224 offset:19456
	ds_read_b128 v[188:191], v224 offset:20480
	ds_read_b128 v[192:195], v224 offset:21504
	ds_read_b128 v[196:199], v224 offset:22528
	ds_read_b128 v[200:203], v224 offset:23552
	global_load_lds_dwordx4 v[204:205], off
	s_add_i32 m0, s63, 0x2000
	s_add_u32 s64, s28, 0x4000
	v_lshl_add_u64 v[204:205], s[28:29], 0, v[130:131]
	s_addc_u32 s65, s29, 0
	s_add_i32 s63, s51, s37
	global_load_lds_dwordx4 v[204:205], off
	v_lshl_add_u64 v[204:205], s[64:65], 0, v[128:129]
	s_mov_b32 m0, s63
	s_nop 0
	global_load_lds_dwordx4 v[204:205], off
	v_lshl_add_u64 v[204:205], s[64:65], 0, v[130:131]
	s_add_i32 m0, s63, 0x2000
	s_nop 0
	global_load_lds_dwordx4 v[204:205], off
	v_lshl_add_u64 v[204:205], s[30:31], 0, v[128:129]
	s_mov_b32 m0, s38
	s_nop 0
	global_load_lds_dwordx4 v[204:205], off
	v_lshl_add_u64 v[204:205], s[30:31], 0, v[130:131]
	s_mov_b32 m0, s39
	s_nop 0
	global_load_lds_dwordx4 v[204:205], off
	s_waitcnt vmcnt(8)
	s_waitcnt lgkmcnt(0)
	s_barrier
	s_waitcnt lgkmcnt(0)
	v_mfma_f32_16x16x32_bf16 v[60:63], v[140:143], v[172:175], v[60:63]
	v_mfma_f32_16x16x32_bf16 v[60:63], v[144:147], v[176:179], v[60:63]
	v_mfma_f32_16x16x32_bf16 v[56:59], v[148:151], v[172:175], v[56:59]
	v_mfma_f32_16x16x32_bf16 v[56:59], v[152:155], v[176:179], v[56:59]
	v_mfma_f32_16x16x32_bf16 v[44:47], v[156:159], v[172:175], v[44:47]
	v_mfma_f32_16x16x32_bf16 v[44:47], v[160:163], v[176:179], v[44:47]
	v_mfma_f32_16x16x32_bf16 v[36:39], v[164:167], v[172:175], v[36:39]
	v_mfma_f32_16x16x32_bf16 v[36:39], v[168:171], v[176:179], v[36:39]
	v_mfma_f32_16x16x32_bf16 v[20:23], v[164:167], v[180:183], v[20:23]
	v_mfma_f32_16x16x32_bf16 v[20:23], v[168:171], v[184:187], v[20:23]
	v_mfma_f32_16x16x32_bf16 v[28:31], v[156:159], v[180:183], v[28:31]
	v_mfma_f32_16x16x32_bf16 v[28:31], v[160:163], v[184:187], v[28:31]
	v_mfma_f32_16x16x32_bf16 v[48:51], v[148:151], v[180:183], v[48:51]
	v_mfma_f32_16x16x32_bf16 v[48:51], v[152:155], v[184:187], v[48:51]
	v_mfma_f32_16x16x32_bf16 v[52:55], v[140:143], v[180:183], v[52:55]
	v_mfma_f32_16x16x32_bf16 v[52:55], v[144:147], v[184:187], v[52:55]
	v_mfma_f32_16x16x32_bf16 v[40:43], v[140:143], v[188:191], v[40:43]
	v_mfma_f32_16x16x32_bf16 v[40:43], v[144:147], v[192:195], v[40:43]
	v_mfma_f32_16x16x32_bf16 v[32:35], v[148:151], v[188:191], v[32:35]
	v_mfma_f32_16x16x32_bf16 v[32:35], v[152:155], v[192:195], v[32:35]
	v_mfma_f32_16x16x32_bf16 v[12:15], v[156:159], v[188:191], v[12:15]
	v_mfma_f32_16x16x32_bf16 v[12:15], v[160:163], v[192:195], v[12:15]
	v_mfma_f32_16x16x32_bf16 v[8:11], v[164:167], v[188:191], v[8:11]
	v_mfma_f32_16x16x32_bf16 v[8:11], v[168:171], v[192:195], v[8:11]
	v_mfma_f32_16x16x32_bf16 v[0:3], v[164:167], v[196:199], v[0:3]
	v_mfma_f32_16x16x32_bf16 v[0:3], v[168:171], v[200:203], v[0:3]
	v_mfma_f32_16x16x32_bf16 v[4:7], v[156:159], v[196:199], v[4:7]
	v_mfma_f32_16x16x32_bf16 v[4:7], v[160:163], v[200:203], v[4:7]
	v_mfma_f32_16x16x32_bf16 v[16:19], v[148:151], v[196:199], v[16:19]
	v_mfma_f32_16x16x32_bf16 v[16:19], v[152:155], v[200:203], v[16:19]
	v_mfma_f32_16x16x32_bf16 v[24:27], v[140:143], v[196:199], v[24:27]
	v_mfma_f32_16x16x32_bf16 v[24:27], v[144:147], v[200:203], v[24:27]
	s_barrier
	s_add_i32 s63, 0, 0x18000
	s_add_i32 s64, 0, 0x1c000
	v_add_u32_e32 v152, s63, v219
	v_add_u32_e32 v168, s64, v219
	ds_read_b128 v[140:143], v152
	ds_read_b128 v[144:147], v152 offset:1024
	ds_read_b128 v[148:151], v152 offset:2048
	ds_read_b128 v[152:155], v152 offset:3072
	ds_read_b128 v[156:159], v168
	ds_read_b128 v[160:163], v168 offset:1024
	ds_read_b128 v[164:167], v168 offset:2048
	ds_read_b128 v[168:171], v168 offset:3072
	s_add_u32 s30, s30, 0x4000
	s_addc_u32 s31, s31, 0
	s_mov_b32 m0, s40
	v_lshl_add_u64 v[204:205], s[30:31], 0, v[128:129]
	ds_read_b128 v[172:175], v224 offset:32768
	ds_read_b128 v[176:179], v224 offset:33792
	ds_read_b128 v[180:183], v224 offset:34816
	ds_read_b128 v[184:187], v224 offset:35840
	ds_read_b128 v[188:191], v224 offset:36864
	ds_read_b128 v[192:195], v224 offset:37888
	ds_read_b128 v[196:199], v224 offset:38912
	ds_read_b128 v[200:203], v224 offset:39936
	global_load_lds_dwordx4 v[204:205], off
	v_lshl_add_u64 v[204:205], s[30:31], 0, v[130:131]
	s_mov_b32 m0, s41
	s_nop 0
	global_load_lds_dwordx4 v[204:205], off
	s_waitcnt vmcnt(8)
	s_waitcnt lgkmcnt(0)
	s_barrier
	s_waitcnt lgkmcnt(0)
	v_mfma_f32_16x16x32_bf16 v[124:127], v[140:143], v[172:175], v[124:127]
	v_mfma_f32_16x16x32_bf16 v[124:127], v[144:147], v[176:179], v[124:127]
	v_mfma_f32_16x16x32_bf16 v[120:123], v[148:151], v[172:175], v[120:123]
	v_mfma_f32_16x16x32_bf16 v[120:123], v[152:155], v[176:179], v[120:123]
	v_mfma_f32_16x16x32_bf16 v[108:111], v[156:159], v[172:175], v[108:111]
	v_mfma_f32_16x16x32_bf16 v[108:111], v[160:163], v[176:179], v[108:111]
	v_mfma_f32_16x16x32_bf16 v[100:103], v[164:167], v[172:175], v[100:103]
	v_mfma_f32_16x16x32_bf16 v[100:103], v[168:171], v[176:179], v[100:103]
	v_mfma_f32_16x16x32_bf16 v[84:87], v[164:167], v[180:183], v[84:87]
	v_mfma_f32_16x16x32_bf16 v[84:87], v[168:171], v[184:187], v[84:87]
	v_mfma_f32_16x16x32_bf16 v[92:95], v[156:159], v[180:183], v[92:95]
	v_mfma_f32_16x16x32_bf16 v[92:95], v[160:163], v[184:187], v[92:95]
	v_mfma_f32_16x16x32_bf16 v[112:115], v[148:151], v[180:183], v[112:115]
	v_mfma_f32_16x16x32_bf16 v[112:115], v[152:155], v[184:187], v[112:115]
	v_mfma_f32_16x16x32_bf16 v[116:119], v[140:143], v[180:183], v[116:119]
	v_mfma_f32_16x16x32_bf16 v[116:119], v[144:147], v[184:187], v[116:119]
	v_mfma_f32_16x16x32_bf16 v[104:107], v[140:143], v[188:191], v[104:107]
	v_mfma_f32_16x16x32_bf16 v[104:107], v[144:147], v[192:195], v[104:107]
	v_mfma_f32_16x16x32_bf16 v[96:99], v[148:151], v[188:191], v[96:99]
	v_mfma_f32_16x16x32_bf16 v[96:99], v[152:155], v[192:195], v[96:99]
	v_mfma_f32_16x16x32_bf16 v[76:79], v[156:159], v[188:191], v[76:79]
	v_mfma_f32_16x16x32_bf16 v[76:79], v[160:163], v[192:195], v[76:79]
	v_mfma_f32_16x16x32_bf16 v[72:75], v[164:167], v[188:191], v[72:75]
	v_mfma_f32_16x16x32_bf16 v[72:75], v[168:171], v[192:195], v[72:75]
	v_mfma_f32_16x16x32_bf16 v[64:67], v[164:167], v[196:199], v[64:67]
	v_mfma_f32_16x16x32_bf16 v[64:67], v[168:171], v[200:203], v[64:67]
	v_mfma_f32_16x16x32_bf16 v[68:71], v[156:159], v[196:199], v[68:71]
	v_mfma_f32_16x16x32_bf16 v[68:71], v[160:163], v[200:203], v[68:71]
	v_mfma_f32_16x16x32_bf16 v[80:83], v[148:151], v[196:199], v[80:83]
	v_mfma_f32_16x16x32_bf16 v[80:83], v[152:155], v[200:203], v[80:83]
	v_mfma_f32_16x16x32_bf16 v[88:91], v[140:143], v[196:199], v[88:91]
	v_mfma_f32_16x16x32_bf16 v[88:91], v[144:147], v[200:203], v[88:91]
	s_barrier
	s_add_u32 s30, s28, 0x8000
	s_addc_u32 s31, s29, 0
	s_add_i32 s63, s63, s37
	v_lshl_add_u64 v[204:205], s[30:31], 0, v[128:129]
	s_mov_b32 m0, s63
	ds_read_b128 v[172:175], v224 offset:49152
	ds_read_b128 v[176:179], v224 offset:50176
	ds_read_b128 v[180:183], v224 offset:51200
	ds_read_b128 v[184:187], v224 offset:52224
	ds_read_b128 v[188:191], v224 offset:53248
	ds_read_b128 v[192:195], v224 offset:54272
	ds_read_b128 v[196:199], v224 offset:55296
	ds_read_b128 v[200:203], v224 offset:56320
	global_load_lds_dwordx4 v[204:205], off
	s_add_i32 m0, s63, 0x2000
	s_add_u32 s28, s28, 0xc000
	v_lshl_add_u64 v[204:205], s[30:31], 0, v[130:131]
	s_addc_u32 s29, s29, 0
	s_add_i32 s30, s64, s37
	global_load_lds_dwordx4 v[204:205], off
	v_lshl_add_u64 v[204:205], s[28:29], 0, v[128:129]
	s_mov_b32 m0, s30
	s_nop 0
	global_load_lds_dwordx4 v[204:205], off
	v_lshl_add_u64 v[204:205], s[28:29], 0, v[130:131]
	s_add_i32 m0, s30, 0x2000
	s_nop 0
	global_load_lds_dwordx4 v[204:205], off
	v_lshl_add_u64 v[204:205], s[26:27], 0, v[128:129]
	s_mov_b32 m0, s44
	s_nop 0
	global_load_lds_dwordx4 v[204:205], off
	v_lshl_add_u64 v[204:205], s[26:27], 0, v[130:131]
	s_mov_b32 m0, s45
	s_nop 0
	global_load_lds_dwordx4 v[204:205], off
	s_waitcnt vmcnt(8)
	s_waitcnt lgkmcnt(0)
	s_barrier
	s_waitcnt lgkmcnt(0)
	v_mfma_f32_16x16x32_bf16 v[60:63], v[140:143], v[172:175], v[60:63]
	v_mfma_f32_16x16x32_bf16 v[60:63], v[144:147], v[176:179], v[60:63]
	v_mfma_f32_16x16x32_bf16 v[56:59], v[148:151], v[172:175], v[56:59]
	v_mfma_f32_16x16x32_bf16 v[56:59], v[152:155], v[176:179], v[56:59]
	v_mfma_f32_16x16x32_bf16 v[44:47], v[156:159], v[172:175], v[44:47]
	v_mfma_f32_16x16x32_bf16 v[44:47], v[160:163], v[176:179], v[44:47]
	v_mfma_f32_16x16x32_bf16 v[36:39], v[164:167], v[172:175], v[36:39]
	v_mfma_f32_16x16x32_bf16 v[36:39], v[168:171], v[176:179], v[36:39]
	v_mfma_f32_16x16x32_bf16 v[20:23], v[164:167], v[180:183], v[20:23]
	v_mfma_f32_16x16x32_bf16 v[20:23], v[168:171], v[184:187], v[20:23]
	v_mfma_f32_16x16x32_bf16 v[28:31], v[156:159], v[180:183], v[28:31]
	v_mfma_f32_16x16x32_bf16 v[28:31], v[160:163], v[184:187], v[28:31]
	v_mfma_f32_16x16x32_bf16 v[48:51], v[148:151], v[180:183], v[48:51]
	v_mfma_f32_16x16x32_bf16 v[48:51], v[152:155], v[184:187], v[48:51]
	v_mfma_f32_16x16x32_bf16 v[52:55], v[140:143], v[180:183], v[52:55]
	v_mfma_f32_16x16x32_bf16 v[52:55], v[144:147], v[184:187], v[52:55]
	v_mfma_f32_16x16x32_bf16 v[40:43], v[140:143], v[188:191], v[40:43]
	v_mfma_f32_16x16x32_bf16 v[40:43], v[144:147], v[192:195], v[40:43]
	v_mfma_f32_16x16x32_bf16 v[32:35], v[148:151], v[188:191], v[32:35]
	v_mfma_f32_16x16x32_bf16 v[32:35], v[152:155], v[192:195], v[32:35]
	v_mfma_f32_16x16x32_bf16 v[12:15], v[156:159], v[188:191], v[12:15]
	v_mfma_f32_16x16x32_bf16 v[12:15], v[160:163], v[192:195], v[12:15]
	v_mfma_f32_16x16x32_bf16 v[8:11], v[164:167], v[188:191], v[8:11]
	v_mfma_f32_16x16x32_bf16 v[8:11], v[168:171], v[192:195], v[8:11]
	v_mfma_f32_16x16x32_bf16 v[0:3], v[164:167], v[196:199], v[0:3]
	v_mfma_f32_16x16x32_bf16 v[0:3], v[168:171], v[200:203], v[0:3]
	v_mfma_f32_16x16x32_bf16 v[4:7], v[156:159], v[196:199], v[4:7]
	v_mfma_f32_16x16x32_bf16 v[4:7], v[160:163], v[200:203], v[4:7]
	v_mfma_f32_16x16x32_bf16 v[16:19], v[148:151], v[196:199], v[16:19]
	v_mfma_f32_16x16x32_bf16 v[16:19], v[152:155], v[200:203], v[16:19]
	v_mfma_f32_16x16x32_bf16 v[24:27], v[140:143], v[196:199], v[24:27]
	v_mfma_f32_16x16x32_bf16 v[24:27], v[144:147], v[200:203], v[24:27]
	s_barrier
	s_add_u32 s24, s24, 0x10000
	s_addc_u32 s25, s25, 0
	s_add_u32 s60, s60, 0x10000
	s_addc_u32 s61, s61, 0
	s_cmp_ge_i32 s62, s43
	s_mov_b32 s26, s62
	s_cbranch_scc0 .LBB0_1056
	v_pk_mul_f32 v[198:199], v[126:127], 0.5 op_sel_hi:[1,0]
	v_pk_mul_f32 v[200:201], v[124:125], 0.5 op_sel_hi:[1,0]
	v_pk_mul_f32 v[202:203], v[122:123], 0.5 op_sel_hi:[1,0]
	v_pk_mul_f32 v[204:205], v[120:121], 0.5 op_sel_hi:[1,0]
	v_pk_mul_f32 v[208:209], v[110:111], 0.5 op_sel_hi:[1,0]
	v_pk_mul_f32 v[206:207], v[108:109], 0.5 op_sel_hi:[1,0]
	v_pk_mul_f32 v[196:197], v[102:103], 0.5 op_sel_hi:[1,0]
	v_pk_mul_f32 v[194:195], v[100:101], 0.5 op_sel_hi:[1,0]
	v_pk_mul_f32 v[192:193], v[118:119], 0.5 op_sel_hi:[1,0]
	v_pk_mul_f32 v[190:191], v[116:117], 0.5 op_sel_hi:[1,0]
	v_pk_mul_f32 v[188:189], v[114:115], 0.5 op_sel_hi:[1,0]
	v_pk_mul_f32 v[186:187], v[112:113], 0.5 op_sel_hi:[1,0]
	v_pk_mul_f32 v[184:185], v[94:95], 0.5 op_sel_hi:[1,0]
	v_pk_mul_f32 v[182:183], v[92:93], 0.5 op_sel_hi:[1,0]
	v_pk_mul_f32 v[180:181], v[86:87], 0.5 op_sel_hi:[1,0]
	v_pk_mul_f32 v[178:179], v[84:85], 0.5 op_sel_hi:[1,0]
	v_pk_mul_f32 v[176:177], v[106:107], 0.5 op_sel_hi:[1,0]
	v_pk_mul_f32 v[174:175], v[104:105], 0.5 op_sel_hi:[1,0]
	v_pk_mul_f32 v[172:173], v[98:99], 0.5 op_sel_hi:[1,0]
	v_pk_mul_f32 v[170:171], v[96:97], 0.5 op_sel_hi:[1,0]
	v_pk_mul_f32 v[168:169], v[78:79], 0.5 op_sel_hi:[1,0]
	v_pk_mul_f32 v[166:167], v[76:77], 0.5 op_sel_hi:[1,0]
	v_pk_mul_f32 v[164:165], v[74:75], 0.5 op_sel_hi:[1,0]
	v_pk_mul_f32 v[162:163], v[72:73], 0.5 op_sel_hi:[1,0]
	v_pk_mul_f32 v[160:161], v[90:91], 0.5 op_sel_hi:[1,0]
	v_pk_mul_f32 v[158:159], v[88:89], 0.5 op_sel_hi:[1,0]
	v_pk_mul_f32 v[156:157], v[82:83], 0.5 op_sel_hi:[1,0]
	v_pk_mul_f32 v[154:155], v[80:81], 0.5 op_sel_hi:[1,0]
	v_pk_mul_f32 v[152:153], v[70:71], 0.5 op_sel_hi:[1,0]
	v_pk_mul_f32 v[150:151], v[68:69], 0.5 op_sel_hi:[1,0]
	v_pk_mul_f32 v[148:149], v[66:67], 0.5 op_sel_hi:[1,0]
	v_pk_mul_f32 v[146:147], v[64:65], 0.5 op_sel_hi:[1,0]
	v_pk_mul_f32 v[142:143], v[62:63], 0.5 op_sel_hi:[1,0]
	v_pk_mul_f32 v[140:141], v[60:61], 0.5 op_sel_hi:[1,0]
	v_pk_mul_f32 v[126:127], v[58:59], 0.5 op_sel_hi:[1,0]
	v_pk_mul_f32 v[124:125], v[56:57], 0.5 op_sel_hi:[1,0]
	v_pk_mul_f32 v[122:123], v[46:47], 0.5 op_sel_hi:[1,0]
	v_pk_mul_f32 v[120:121], v[44:45], 0.5 op_sel_hi:[1,0]
	v_pk_mul_f32 v[118:119], v[38:39], 0.5 op_sel_hi:[1,0]
	v_pk_mul_f32 v[116:117], v[36:37], 0.5 op_sel_hi:[1,0]
	v_pk_mul_f32 v[114:115], v[54:55], 0.5 op_sel_hi:[1,0]
	v_pk_mul_f32 v[112:113], v[52:53], 0.5 op_sel_hi:[1,0]
	v_pk_mul_f32 v[110:111], v[50:51], 0.5 op_sel_hi:[1,0]
	v_pk_mul_f32 v[108:109], v[48:49], 0.5 op_sel_hi:[1,0]
	v_pk_mul_f32 v[106:107], v[30:31], 0.5 op_sel_hi:[1,0]
	v_pk_mul_f32 v[104:105], v[28:29], 0.5 op_sel_hi:[1,0]
	v_pk_mul_f32 v[102:103], v[22:23], 0.5 op_sel_hi:[1,0]
	v_pk_mul_f32 v[100:101], v[20:21], 0.5 op_sel_hi:[1,0]
	v_pk_mul_f32 v[98:99], v[42:43], 0.5 op_sel_hi:[1,0]
	v_pk_mul_f32 v[96:97], v[40:41], 0.5 op_sel_hi:[1,0]
	v_pk_mul_f32 v[94:95], v[34:35], 0.5 op_sel_hi:[1,0]
	v_pk_mul_f32 v[92:93], v[32:33], 0.5 op_sel_hi:[1,0]
	v_pk_mul_f32 v[90:91], v[14:15], 0.5 op_sel_hi:[1,0]
	v_pk_mul_f32 v[88:89], v[12:13], 0.5 op_sel_hi:[1,0]
	v_pk_mul_f32 v[86:87], v[10:11], 0.5 op_sel_hi:[1,0]
	v_pk_mul_f32 v[84:85], v[8:9], 0.5 op_sel_hi:[1,0]
	v_pk_mul_f32 v[82:83], v[26:27], 0.5 op_sel_hi:[1,0]
	v_pk_mul_f32 v[80:81], v[24:25], 0.5 op_sel_hi:[1,0]
	v_pk_mul_f32 v[78:79], v[18:19], 0.5 op_sel_hi:[1,0]
	v_pk_mul_f32 v[76:77], v[16:17], 0.5 op_sel_hi:[1,0]
	v_pk_mul_f32 v[74:75], v[6:7], 0.5 op_sel_hi:[1,0]
	v_pk_mul_f32 v[72:73], v[4:5], 0.5 op_sel_hi:[1,0]
	v_pk_mul_f32 v[70:71], v[2:3], 0.5 op_sel_hi:[1,0]
	v_pk_mul_f32 v[68:69], v[0:1], 0.5 op_sel_hi:[1,0]

.LBB0_1159:
	ds_read_b128 v[128:131], v205
	ds_read_b128 v[132:135], v205 offset:1024
	ds_read_b128 v[136:139], v205 offset:2048
	ds_read_b128 v[140:143], v205 offset:3072
	ds_read_b128 v[144:147], v206
	ds_read_b128 v[160:163], v206 offset:1024
	ds_read_b128 v[164:167], v206 offset:2048
	ds_read_b128 v[168:171], v206 offset:3072
	s_add_i32 s41, s6, 2
	s_add_u32 s68, s0, 0x80
	s_addc_u32 s7, s1, 0
	s_cmp_eq_u32 s57, s6
	s_cselect_b32 s6, s34, s68
	s_cselect_b32 s7, s35, s7
	s_cselect_b32 s69, s37, s39
	s_cselect_b32 s68, s36, s38
	v_lshl_add_u64 v[200:201], s[0:1], 0, v[152:153]
	s_add_i32 m0, s47, 0xc000
	ds_read_b128 v[172:175], v207
	ds_read_b128 v[176:179], v207 offset:1024
	ds_read_b128 v[180:183], v207 offset:2048
	ds_read_b128 v[184:187], v207 offset:3072
	ds_read_b128 v[188:191], v207 offset:4096
	ds_read_b128 v[192:195], v207 offset:5120
	ds_read_b128 v[196:199], v207 offset:6144
	ds_read_b128 v[212:215], v207 offset:7168
	global_load_lds_dwordx4 v[200:201], off
	v_lshl_add_u64 v[200:201], s[0:1], 0, v[154:155]
	s_add_i32 m0, s47, 0xe000
	s_nop 0
	global_load_lds_dwordx4 v[200:201], off
	s_waitcnt vmcnt(8)
	s_waitcnt lgkmcnt(0)
	s_barrier
	s_waitcnt lgkmcnt(0)
	v_mfma_f32_16x16x32_bf16 v[124:127], v[128:131], v[172:175], v[124:127]
	v_mfma_f32_16x16x32_bf16 v[124:127], v[132:135], v[176:179], v[124:127]
	v_mfma_f32_16x16x32_bf16 v[120:123], v[136:139], v[172:175], v[120:123]
	v_mfma_f32_16x16x32_bf16 v[120:123], v[140:143], v[176:179], v[120:123]
	v_mfma_f32_16x16x32_bf16 v[116:119], v[144:147], v[172:175], v[116:119]
	v_mfma_f32_16x16x32_bf16 v[116:119], v[160:163], v[176:179], v[116:119]
	v_mfma_f32_16x16x32_bf16 v[112:115], v[164:167], v[172:175], v[112:115]
	v_mfma_f32_16x16x32_bf16 v[112:115], v[168:171], v[176:179], v[112:115]
	v_mfma_f32_16x16x32_bf16 v[96:99], v[164:167], v[180:183], v[96:99]
	v_mfma_f32_16x16x32_bf16 v[96:99], v[168:171], v[184:187], v[96:99]
	v_mfma_f32_16x16x32_bf16 v[100:103], v[144:147], v[180:183], v[100:103]
	v_mfma_f32_16x16x32_bf16 v[100:103], v[160:163], v[184:187], v[100:103]
	v_mfma_f32_16x16x32_bf16 v[104:107], v[136:139], v[180:183], v[104:107]
	v_mfma_f32_16x16x32_bf16 v[104:107], v[140:143], v[184:187], v[104:107]
	v_mfma_f32_16x16x32_bf16 v[108:111], v[128:131], v[180:183], v[108:111]
	v_mfma_f32_16x16x32_bf16 v[108:111], v[132:135], v[184:187], v[108:111]
	v_mfma_f32_16x16x32_bf16 v[92:95], v[128:131], v[188:191], v[92:95]
	v_mfma_f32_16x16x32_bf16 v[92:95], v[132:135], v[192:195], v[92:95]
	v_mfma_f32_16x16x32_bf16 v[88:91], v[136:139], v[188:191], v[88:91]
	v_mfma_f32_16x16x32_bf16 v[88:91], v[140:143], v[192:195], v[88:91]
	v_mfma_f32_16x16x32_bf16 v[84:87], v[144:147], v[188:191], v[84:87]
	v_mfma_f32_16x16x32_bf16 v[84:87], v[160:163], v[192:195], v[84:87]
	v_mfma_f32_16x16x32_bf16 v[80:83], v[164:167], v[188:191], v[80:83]
	v_mfma_f32_16x16x32_bf16 v[80:83], v[168:171], v[192:195], v[80:83]
	v_mfma_f32_16x16x32_bf16 v[64:67], v[164:167], v[196:199], v[64:67]
	v_mfma_f32_16x16x32_bf16 v[64:67], v[168:171], v[212:215], v[64:67]
	v_mfma_f32_16x16x32_bf16 v[68:71], v[144:147], v[196:199], v[68:71]
	v_mfma_f32_16x16x32_bf16 v[68:71], v[160:163], v[212:215], v[68:71]
	v_mfma_f32_16x16x32_bf16 v[72:75], v[136:139], v[196:199], v[72:75]
	v_mfma_f32_16x16x32_bf16 v[72:75], v[140:143], v[212:215], v[72:75]
	v_mfma_f32_16x16x32_bf16 v[76:79], v[128:131], v[196:199], v[76:79]
	v_mfma_f32_16x16x32_bf16 v[76:79], v[132:135], v[212:215], v[76:79]
	s_barrier
	s_add_i32 s70, s60, s46
	v_lshl_add_u64 v[200:201], s[68:69], 0, v[148:149]
	s_mov_b32 m0, s70
	ds_read_b128 v[172:175], v207 offset:16384
	ds_read_b128 v[176:179], v207 offset:17408
	ds_read_b128 v[180:183], v207 offset:18432
	ds_read_b128 v[184:187], v207 offset:19456
	ds_read_b128 v[188:191], v207 offset:20480
	ds_read_b128 v[192:195], v207 offset:21504
	ds_read_b128 v[196:199], v207 offset:22528
	ds_read_b128 v[212:215], v207 offset:23552
	global_load_lds_dwordx4 v[200:201], off
	s_add_i32 m0, s70, 0x2000
	v_lshl_add_u64 v[216:217], s[68:69], 0, v[150:151]
	s_add_u32 s68, s68, s10
	s_addc_u32 s69, s69, s11
	s_add_i32 s70, s61, s46
	global_load_lds_dwordx4 v[216:217], off
	v_lshl_add_u64 v[218:219], s[68:69], 0, v[148:149]
	s_mov_b32 m0, s70
	v_lshl_add_u64 v[220:221], s[68:69], 0, v[150:151]
	global_load_lds_dwordx4 v[218:219], off
	s_add_i32 m0, s70, 0x2000
	v_lshl_add_u64 v[222:223], s[6:7], 0, v[148:149]
	global_load_lds_dwordx4 v[220:221], off
	s_mov_b32 m0, s47
	v_lshl_add_u64 v[224:225], s[6:7], 0, v[150:151]
	global_load_lds_dwordx4 v[222:223], off
	s_mov_b32 m0, s48
	s_nop 0
	global_load_lds_dwordx4 v[224:225], off
	s_waitcnt vmcnt(8)
	s_waitcnt lgkmcnt(0)
	s_barrier
	s_waitcnt lgkmcnt(0)
	v_mfma_f32_16x16x32_bf16 v[60:63], v[128:131], v[172:175], v[60:63]
	v_mfma_f32_16x16x32_bf16 v[60:63], v[132:135], v[176:179], v[60:63]
	v_mfma_f32_16x16x32_bf16 v[56:59], v[136:139], v[172:175], v[56:59]
	v_mfma_f32_16x16x32_bf16 v[56:59], v[140:143], v[176:179], v[56:59]
	v_mfma_f32_16x16x32_bf16 v[52:55], v[144:147], v[172:175], v[52:55]
	v_mfma_f32_16x16x32_bf16 v[52:55], v[160:163], v[176:179], v[52:55]
	v_mfma_f32_16x16x32_bf16 v[48:51], v[164:167], v[172:175], v[48:51]
	v_mfma_f32_16x16x32_bf16 v[48:51], v[168:171], v[176:179], v[48:51]
	v_mfma_f32_16x16x32_bf16 v[32:35], v[164:167], v[180:183], v[32:35]
	v_mfma_f32_16x16x32_bf16 v[32:35], v[168:171], v[184:187], v[32:35]
	v_mfma_f32_16x16x32_bf16 v[36:39], v[144:147], v[180:183], v[36:39]
	v_mfma_f32_16x16x32_bf16 v[36:39], v[160:163], v[184:187], v[36:39]
	v_mfma_f32_16x16x32_bf16 v[40:43], v[136:139], v[180:183], v[40:43]
	v_mfma_f32_16x16x32_bf16 v[40:43], v[140:143], v[184:187], v[40:43]
	v_mfma_f32_16x16x32_bf16 v[44:47], v[128:131], v[180:183], v[44:47]
	v_mfma_f32_16x16x32_bf16 v[44:47], v[132:135], v[184:187], v[44:47]
	v_mfma_f32_16x16x32_bf16 v[28:31], v[128:131], v[188:191], v[28:31]
	v_mfma_f32_16x16x32_bf16 v[28:31], v[132:135], v[192:195], v[28:31]
	v_mfma_f32_16x16x32_bf16 v[24:27], v[136:139], v[188:191], v[24:27]
	v_mfma_f32_16x16x32_bf16 v[24:27], v[140:143], v[192:195], v[24:27]
	v_mfma_f32_16x16x32_bf16 v[20:23], v[144:147], v[188:191], v[20:23]
	v_mfma_f32_16x16x32_bf16 v[20:23], v[160:163], v[192:195], v[20:23]
	v_mfma_f32_16x16x32_bf16 v[16:19], v[164:167], v[188:191], v[16:19]
	v_mfma_f32_16x16x32_bf16 v[16:19], v[168:171], v[192:195], v[16:19]
	v_mfma_f32_16x16x32_bf16 v[0:3], v[164:167], v[196:199], v[0:3]
	v_mfma_f32_16x16x32_bf16 v[0:3], v[168:171], v[212:215], v[0:3]
	v_mfma_f32_16x16x32_bf16 v[4:7], v[144:147], v[196:199], v[4:7]
	v_mfma_f32_16x16x32_bf16 v[4:7], v[160:163], v[212:215], v[4:7]
	v_mfma_f32_16x16x32_bf16 v[8:11], v[136:139], v[196:199], v[8:11]
	v_mfma_f32_16x16x32_bf16 v[8:11], v[140:143], v[212:215], v[8:11]
	v_mfma_f32_16x16x32_bf16 v[12:15], v[128:131], v[196:199], v[12:15]
	v_mfma_f32_16x16x32_bf16 v[12:15], v[132:135], v[212:215], v[12:15]
	s_barrier
	s_add_i32 s68, 0, 0x18000
	s_add_i32 s69, 0, 0x1c000
	v_add_u32_e32 v140, s68, v203
	v_add_u32_e32 v168, s69, v203
	ds_read_b128 v[128:131], v140
	ds_read_b128 v[132:135], v140 offset:1024
	ds_read_b128 v[136:139], v140 offset:2048
	ds_read_b128 v[140:143], v140 offset:3072
	ds_read_b128 v[144:147], v168
	ds_read_b128 v[160:163], v168 offset:1024
	ds_read_b128 v[164:167], v168 offset:2048
	ds_read_b128 v[168:171], v168 offset:3072
	s_add_u32 s6, s6, s10
	s_addc_u32 s7, s7, s11
	s_mov_b32 m0, s49
	v_lshl_add_u64 v[226:227], s[6:7], 0, v[148:149]
	ds_read_b128 v[172:175], v207 offset:32768
	ds_read_b128 v[176:179], v207 offset:33792
	ds_read_b128 v[180:183], v207 offset:34816
	ds_read_b128 v[184:187], v207 offset:35840
	ds_read_b128 v[188:191], v207 offset:36864
	ds_read_b128 v[192:195], v207 offset:37888
	ds_read_b128 v[196:199], v207 offset:38912
	ds_read_b128 v[212:215], v207 offset:39936
	global_load_lds_dwordx4 v[226:227], off
	v_lshl_add_u64 v[226:227], s[6:7], 0, v[150:151]
	s_mov_b32 m0, s50
	s_nop 0
	global_load_lds_dwordx4 v[226:227], off
	s_waitcnt vmcnt(8)
	s_waitcnt lgkmcnt(0)
	s_barrier
	s_waitcnt lgkmcnt(0)
	v_mfma_f32_16x16x32_bf16 v[124:127], v[128:131], v[172:175], v[124:127]
	v_mfma_f32_16x16x32_bf16 v[124:127], v[132:135], v[176:179], v[124:127]
	v_mfma_f32_16x16x32_bf16 v[120:123], v[136:139], v[172:175], v[120:123]
	v_mfma_f32_16x16x32_bf16 v[120:123], v[140:143], v[176:179], v[120:123]
	v_mfma_f32_16x16x32_bf16 v[116:119], v[144:147], v[172:175], v[116:119]
	v_mfma_f32_16x16x32_bf16 v[116:119], v[160:163], v[176:179], v[116:119]
	v_mfma_f32_16x16x32_bf16 v[112:115], v[164:167], v[172:175], v[112:115]
	v_mfma_f32_16x16x32_bf16 v[112:115], v[168:171], v[176:179], v[112:115]
	v_mfma_f32_16x16x32_bf16 v[96:99], v[164:167], v[180:183], v[96:99]
	v_mfma_f32_16x16x32_bf16 v[96:99], v[168:171], v[184:187], v[96:99]
	v_mfma_f32_16x16x32_bf16 v[100:103], v[144:147], v[180:183], v[100:103]
	v_mfma_f32_16x16x32_bf16 v[100:103], v[160:163], v[184:187], v[100:103]
	v_mfma_f32_16x16x32_bf16 v[104:107], v[136:139], v[180:183], v[104:107]
	v_mfma_f32_16x16x32_bf16 v[104:107], v[140:143], v[184:187], v[104:107]
	v_mfma_f32_16x16x32_bf16 v[108:111], v[128:131], v[180:183], v[108:111]
	v_mfma_f32_16x16x32_bf16 v[108:111], v[132:135], v[184:187], v[108:111]
	v_mfma_f32_16x16x32_bf16 v[92:95], v[128:131], v[188:191], v[92:95]
	v_mfma_f32_16x16x32_bf16 v[92:95], v[132:135], v[192:195], v[92:95]
	v_mfma_f32_16x16x32_bf16 v[88:91], v[136:139], v[188:191], v[88:91]
	v_mfma_f32_16x16x32_bf16 v[88:91], v[140:143], v[192:195], v[88:91]
	v_mfma_f32_16x16x32_bf16 v[84:87], v[144:147], v[188:191], v[84:87]
	v_mfma_f32_16x16x32_bf16 v[84:87], v[160:163], v[192:195], v[84:87]
	v_mfma_f32_16x16x32_bf16 v[80:83], v[164:167], v[188:191], v[80:83]
	v_mfma_f32_16x16x32_bf16 v[80:83], v[168:171], v[192:195], v[80:83]
	v_mfma_f32_16x16x32_bf16 v[64:67], v[164:167], v[196:199], v[64:67]
	v_mfma_f32_16x16x32_bf16 v[64:67], v[168:171], v[212:215], v[64:67]
	v_mfma_f32_16x16x32_bf16 v[68:71], v[144:147], v[196:199], v[68:71]
	v_mfma_f32_16x16x32_bf16 v[68:71], v[160:163], v[212:215], v[68:71]
	v_mfma_f32_16x16x32_bf16 v[72:75], v[136:139], v[196:199], v[72:75]
	v_mfma_f32_16x16x32_bf16 v[72:75], v[140:143], v[212:215], v[72:75]
	v_mfma_f32_16x16x32_bf16 v[76:79], v[128:131], v[196:199], v[76:79]
	v_mfma_f32_16x16x32_bf16 v[76:79], v[132:135], v[212:215], v[76:79]
	s_barrier
	s_add_i32 s6, s68, s46
	v_lshl_add_u64 v[200:201], v[200:201], 0, s[20:21]
	s_mov_b32 m0, s6
	ds_read_b128 v[172:175], v207 offset:49152
	ds_read_b128 v[176:179], v207 offset:50176
	ds_read_b128 v[180:183], v207 offset:51200
	ds_read_b128 v[184:187], v207 offset:52224
	ds_read_b128 v[188:191], v207 offset:53248
	ds_read_b128 v[192:195], v207 offset:54272
	ds_read_b128 v[196:199], v207 offset:55296
	ds_read_b128 v[212:215], v207 offset:56320
	global_load_lds_dwordx4 v[200:201], off
	v_lshl_add_u64 v[200:201], v[216:217], 0, s[20:21]
	s_add_i32 m0, s6, 0x2000
	s_add_i32 s6, s69, s46
	global_load_lds_dwordx4 v[200:201], off
	v_lshl_add_u64 v[200:201], v[218:219], 0, s[20:21]
	s_mov_b32 m0, s6
	s_nop 0
	global_load_lds_dwordx4 v[200:201], off
	v_lshl_add_u64 v[200:201], v[220:221], 0, s[20:21]
	s_add_i32 m0, s6, 0x2000
	s_nop 0
	global_load_lds_dwordx4 v[200:201], off
	v_lshl_add_u64 v[200:201], v[222:223], 0, s[20:21]
	s_mov_b32 m0, s54
	s_nop 0
	global_load_lds_dwordx4 v[200:201], off
	v_lshl_add_u64 v[200:201], v[224:225], 0, s[20:21]
	s_mov_b32 m0, s55
	s_nop 0
	global_load_lds_dwordx4 v[200:201], off
	s_waitcnt vmcnt(8)
	s_waitcnt lgkmcnt(0)
	s_barrier
	s_waitcnt lgkmcnt(0)
	v_mfma_f32_16x16x32_bf16 v[60:63], v[128:131], v[172:175], v[60:63]
	v_mfma_f32_16x16x32_bf16 v[60:63], v[132:135], v[176:179], v[60:63]
	v_mfma_f32_16x16x32_bf16 v[56:59], v[136:139], v[172:175], v[56:59]
	v_mfma_f32_16x16x32_bf16 v[56:59], v[140:143], v[176:179], v[56:59]
	v_mfma_f32_16x16x32_bf16 v[52:55], v[144:147], v[172:175], v[52:55]
	v_mfma_f32_16x16x32_bf16 v[52:55], v[160:163], v[176:179], v[52:55]
	v_mfma_f32_16x16x32_bf16 v[48:51], v[164:167], v[172:175], v[48:51]
	v_mfma_f32_16x16x32_bf16 v[48:51], v[168:171], v[176:179], v[48:51]
	v_mfma_f32_16x16x32_bf16 v[32:35], v[164:167], v[180:183], v[32:35]
	v_mfma_f32_16x16x32_bf16 v[32:35], v[168:171], v[184:187], v[32:35]
	v_mfma_f32_16x16x32_bf16 v[36:39], v[144:147], v[180:183], v[36:39]
	v_mfma_f32_16x16x32_bf16 v[36:39], v[160:163], v[184:187], v[36:39]
	v_mfma_f32_16x16x32_bf16 v[40:43], v[136:139], v[180:183], v[40:43]
	v_mfma_f32_16x16x32_bf16 v[40:43], v[140:143], v[184:187], v[40:43]
	v_mfma_f32_16x16x32_bf16 v[44:47], v[128:131], v[180:183], v[44:47]
	v_mfma_f32_16x16x32_bf16 v[44:47], v[132:135], v[184:187], v[44:47]
	v_mfma_f32_16x16x32_bf16 v[28:31], v[128:131], v[188:191], v[28:31]
	v_mfma_f32_16x16x32_bf16 v[28:31], v[132:135], v[192:195], v[28:31]
	v_mfma_f32_16x16x32_bf16 v[24:27], v[136:139], v[188:191], v[24:27]
	v_mfma_f32_16x16x32_bf16 v[24:27], v[140:143], v[192:195], v[24:27]
	v_mfma_f32_16x16x32_bf16 v[20:23], v[144:147], v[188:191], v[20:23]
	v_mfma_f32_16x16x32_bf16 v[20:23], v[160:163], v[192:195], v[20:23]
	v_mfma_f32_16x16x32_bf16 v[16:19], v[164:167], v[188:191], v[16:19]
	v_mfma_f32_16x16x32_bf16 v[16:19], v[168:171], v[192:195], v[16:19]
	v_mfma_f32_16x16x32_bf16 v[0:3], v[164:167], v[196:199], v[0:3]
	v_mfma_f32_16x16x32_bf16 v[0:3], v[168:171], v[212:215], v[0:3]
	v_mfma_f32_16x16x32_bf16 v[4:7], v[144:147], v[196:199], v[4:7]
	v_mfma_f32_16x16x32_bf16 v[4:7], v[160:163], v[212:215], v[4:7]
	v_mfma_f32_16x16x32_bf16 v[8:11], v[136:139], v[196:199], v[8:11]
	v_mfma_f32_16x16x32_bf16 v[8:11], v[140:143], v[212:215], v[8:11]
	v_mfma_f32_16x16x32_bf16 v[12:15], v[128:131], v[196:199], v[12:15]
	v_mfma_f32_16x16x32_bf16 v[12:15], v[132:135], v[212:215], v[12:15]
	s_barrier
	s_add_u32 s0, s0, 0x100
	s_addc_u32 s1, s1, 0
	s_add_u32 s38, s38, 0x100
	s_addc_u32 s39, s39, 0
	s_cmp_ge_i32 s41, s56
	s_mov_b32 s6, s41
	s_cbranch_scc0 .LBB0_1159
